# GEMM K-loops: removed all s_setprio toggles and the duplicate lgkmcnt(0) wait after each phase barrier
# speedup vs baseline: 1.0028x; 1.0017x over previous
.LBB0_226:
	ds_read_b128 v[144:147], v151
	ds_read_b128 v[158:161], v151 offset:1024
	ds_read_b128 v[162:165], v151 offset:2048
	ds_read_b128 v[166:169], v151 offset:3072
	ds_read_b128 v[170:173], v152
	ds_read_b128 v[174:177], v152 offset:1024
	ds_read_b128 v[178:181], v152 offset:2048
	ds_read_b128 v[182:185], v152 offset:3072
	s_add_u32 s36, s34, 0xfffc0080
	s_addc_u32 s37, s35, -1
	s_cmp_eq_u32 s63, 12
	s_cselect_b32 s39, s7, s37
	s_cselect_b32 s38, s19, s36
	s_cselect_b32 s37, s17, s62
	s_cselect_b32 s36, s31, s61
	v_lshl_add_u64 v[218:219], s[34:35], 0, v[138:139]
	s_add_i32 m0, s46, 0xc000
	ds_read_b128 v[186:189], v153
	ds_read_b128 v[190:193], v153 offset:1024
	ds_read_b128 v[194:197], v153 offset:2048
	ds_read_b128 v[198:201], v153 offset:3072
	ds_read_b128 v[202:205], v153 offset:4096
	ds_read_b128 v[206:209], v153 offset:5120
	ds_read_b128 v[210:213], v153 offset:6144
	ds_read_b128 v[214:217], v153 offset:7168
	global_load_lds_dwordx4 v[218:219], off
	v_lshl_add_u64 v[218:219], s[34:35], 0, v[136:137]
	s_add_i32 m0, s46, 0xe000
	s_nop 0
	global_load_lds_dwordx4 v[218:219], off
	s_waitcnt vmcnt(8)
	s_waitcnt lgkmcnt(0)
	s_barrier
	v_mfma_f32_16x16x32_bf16 v[124:127], v[144:147], v[186:189], v[124:127]
	v_mfma_f32_16x16x32_bf16 v[120:123], v[162:165], v[186:189], v[120:123]
	v_mfma_f32_16x16x32_bf16 v[108:111], v[144:147], v[194:197], v[108:111]
	v_mfma_f32_16x16x32_bf16 v[104:107], v[162:165], v[194:197], v[104:107]
	v_mfma_f32_16x16x32_bf16 v[92:95], v[144:147], v[202:205], v[92:95]
	v_mfma_f32_16x16x32_bf16 v[88:91], v[162:165], v[202:205], v[88:91]
	v_mfma_f32_16x16x32_bf16 v[76:79], v[144:147], v[210:213], v[76:79]
	v_mfma_f32_16x16x32_bf16 v[72:75], v[162:165], v[210:213], v[72:75]
	v_mfma_f32_16x16x32_bf16 v[124:127], v[158:161], v[190:193], v[124:127]
	v_mfma_f32_16x16x32_bf16 v[120:123], v[166:169], v[190:193], v[120:123]
	v_mfma_f32_16x16x32_bf16 v[108:111], v[158:161], v[198:201], v[108:111]
	v_mfma_f32_16x16x32_bf16 v[104:107], v[166:169], v[198:201], v[104:107]
	v_mfma_f32_16x16x32_bf16 v[92:95], v[158:161], v[206:209], v[92:95]
	v_mfma_f32_16x16x32_bf16 v[88:91], v[166:169], v[206:209], v[88:91]
	v_mfma_f32_16x16x32_bf16 v[76:79], v[158:161], v[214:217], v[76:79]
	v_mfma_f32_16x16x32_bf16 v[72:75], v[166:169], v[214:217], v[72:75]
	v_mfma_f32_16x16x32_bf16 v[116:119], v[170:173], v[186:189], v[116:119]
	v_mfma_f32_16x16x32_bf16 v[112:115], v[178:181], v[186:189], v[112:115]
	v_mfma_f32_16x16x32_bf16 v[100:103], v[170:173], v[194:197], v[100:103]
	v_mfma_f32_16x16x32_bf16 v[96:99], v[178:181], v[194:197], v[96:99]
	v_mfma_f32_16x16x32_bf16 v[84:87], v[170:173], v[202:205], v[84:87]
	v_mfma_f32_16x16x32_bf16 v[80:83], v[178:181], v[202:205], v[80:83]
	v_mfma_f32_16x16x32_bf16 v[68:71], v[170:173], v[210:213], v[68:71]
	v_mfma_f32_16x16x32_bf16 v[64:67], v[178:181], v[210:213], v[64:67]
	v_mfma_f32_16x16x32_bf16 v[116:119], v[174:177], v[190:193], v[116:119]
	v_mfma_f32_16x16x32_bf16 v[112:115], v[182:185], v[190:193], v[112:115]
	v_mfma_f32_16x16x32_bf16 v[100:103], v[174:177], v[198:201], v[100:103]
	v_mfma_f32_16x16x32_bf16 v[96:99], v[182:185], v[198:201], v[96:99]
	v_mfma_f32_16x16x32_bf16 v[84:87], v[174:177], v[206:209], v[84:87]
	v_mfma_f32_16x16x32_bf16 v[80:83], v[182:185], v[206:209], v[80:83]
	v_mfma_f32_16x16x32_bf16 v[68:71], v[174:177], v[214:217], v[68:71]
	v_mfma_f32_16x16x32_bf16 v[64:67], v[182:185], v[214:217], v[64:67]
	s_barrier
	s_add_i32 s64, s58, s45
	v_lshl_add_u64 v[218:219], s[36:37], 0, v[130:131]
	s_mov_b32 m0, s64
	ds_read_b128 v[186:189], v153 offset:16384
	ds_read_b128 v[190:193], v153 offset:17408
	ds_read_b128 v[194:197], v153 offset:18432
	ds_read_b128 v[198:201], v153 offset:19456
	ds_read_b128 v[202:205], v153 offset:20480
	ds_read_b128 v[206:209], v153 offset:21504
	ds_read_b128 v[210:213], v153 offset:22528
	ds_read_b128 v[214:217], v153 offset:23552
	global_load_lds_dwordx4 v[218:219], off
	s_add_i32 m0, s64, 0x2000
	s_add_u32 s64, s36, 0x40000
	v_lshl_add_u64 v[220:221], s[36:37], 0, v[134:135]
	s_addc_u32 s65, s37, 0
	s_add_i32 s66, s59, s45
	global_load_lds_dwordx4 v[220:221], off
	v_lshl_add_u64 v[222:223], s[64:65], 0, v[130:131]
	s_mov_b32 m0, s66
	v_lshl_add_u64 v[224:225], s[38:39], 0, v[132:133]
	global_load_lds_dwordx4 v[222:223], off
	v_lshl_add_u64 v[222:223], s[64:65], 0, v[134:135]
	s_add_i32 m0, s66, 0x2000
	s_nop 0
	global_load_lds_dwordx4 v[222:223], off
	v_lshl_add_u64 v[222:223], s[38:39], 0, v[128:129]
	s_mov_b32 m0, s46
	s_nop 0
	global_load_lds_dwordx4 v[222:223], off
	s_mov_b32 m0, s47
	s_nop 0
	global_load_lds_dwordx4 v[224:225], off
	s_waitcnt vmcnt(8)
	s_waitcnt lgkmcnt(0)
	s_barrier
	v_mfma_f32_16x16x32_bf16 v[60:63], v[144:147], v[186:189], v[60:63]
	v_mfma_f32_16x16x32_bf16 v[56:59], v[162:165], v[186:189], v[56:59]
	v_mfma_f32_16x16x32_bf16 v[44:47], v[144:147], v[194:197], v[44:47]
	v_mfma_f32_16x16x32_bf16 v[40:43], v[162:165], v[194:197], v[40:43]
	v_mfma_f32_16x16x32_bf16 v[28:31], v[144:147], v[202:205], v[28:31]
	v_mfma_f32_16x16x32_bf16 v[24:27], v[162:165], v[202:205], v[24:27]
	v_mfma_f32_16x16x32_bf16 v[12:15], v[144:147], v[210:213], v[12:15]
	v_mfma_f32_16x16x32_bf16 v[8:11], v[162:165], v[210:213], v[8:11]
	v_mfma_f32_16x16x32_bf16 v[60:63], v[158:161], v[190:193], v[60:63]
	v_mfma_f32_16x16x32_bf16 v[56:59], v[166:169], v[190:193], v[56:59]
	v_mfma_f32_16x16x32_bf16 v[44:47], v[158:161], v[198:201], v[44:47]
	v_mfma_f32_16x16x32_bf16 v[40:43], v[166:169], v[198:201], v[40:43]
	v_mfma_f32_16x16x32_bf16 v[28:31], v[158:161], v[206:209], v[28:31]
	v_mfma_f32_16x16x32_bf16 v[24:27], v[166:169], v[206:209], v[24:27]
	v_mfma_f32_16x16x32_bf16 v[12:15], v[158:161], v[214:217], v[12:15]
	v_mfma_f32_16x16x32_bf16 v[8:11], v[166:169], v[214:217], v[8:11]
	v_mfma_f32_16x16x32_bf16 v[52:55], v[170:173], v[186:189], v[52:55]
	v_mfma_f32_16x16x32_bf16 v[48:51], v[178:181], v[186:189], v[48:51]
	v_mfma_f32_16x16x32_bf16 v[36:39], v[170:173], v[194:197], v[36:39]
	v_mfma_f32_16x16x32_bf16 v[32:35], v[178:181], v[194:197], v[32:35]
	v_mfma_f32_16x16x32_bf16 v[20:23], v[170:173], v[202:205], v[20:23]
	v_mfma_f32_16x16x32_bf16 v[16:19], v[178:181], v[202:205], v[16:19]
	v_mfma_f32_16x16x32_bf16 v[4:7], v[170:173], v[210:213], v[4:7]
	v_mfma_f32_16x16x32_bf16 v[0:3], v[178:181], v[210:213], v[0:3]
	v_mfma_f32_16x16x32_bf16 v[52:55], v[174:177], v[190:193], v[52:55]
	v_mfma_f32_16x16x32_bf16 v[48:51], v[182:185], v[190:193], v[48:51]
	v_mfma_f32_16x16x32_bf16 v[36:39], v[174:177], v[198:201], v[36:39]
	v_mfma_f32_16x16x32_bf16 v[32:35], v[182:185], v[198:201], v[32:35]
	v_mfma_f32_16x16x32_bf16 v[20:23], v[174:177], v[206:209], v[20:23]
	v_mfma_f32_16x16x32_bf16 v[16:19], v[182:185], v[206:209], v[16:19]
	v_mfma_f32_16x16x32_bf16 v[4:7], v[174:177], v[214:217], v[4:7]
	v_mfma_f32_16x16x32_bf16 v[0:3], v[182:185], v[214:217], v[0:3]
	s_barrier
	s_add_i32 s64, 0, 0x18000
	v_add_u32_e32 v148, s64, v149
	s_add_i32 s65, 0, 0x1c000
	ds_read_b128 v[144:147], v148
	ds_read_b128 v[158:161], v148 offset:1024
	ds_read_b128 v[162:165], v148 offset:2048
	ds_read_b128 v[166:169], v148 offset:3072
	v_add_u32_e32 v148, s65, v149
	ds_read_b128 v[170:173], v148
	ds_read_b128 v[174:177], v148 offset:1024
	ds_read_b128 v[178:181], v148 offset:2048
	ds_read_b128 v[182:185], v148 offset:3072
	s_add_u32 s38, s38, 0x40000
	s_addc_u32 s39, s39, 0
	s_mov_b32 m0, s48
	v_lshl_add_u64 v[226:227], s[38:39], 0, v[128:129]
	ds_read_b128 v[186:189], v153 offset:32768
	ds_read_b128 v[190:193], v153 offset:33792
	ds_read_b128 v[194:197], v153 offset:34816
	ds_read_b128 v[198:201], v153 offset:35840
	ds_read_b128 v[202:205], v153 offset:36864
	ds_read_b128 v[206:209], v153 offset:37888
	ds_read_b128 v[210:213], v153 offset:38912
	ds_read_b128 v[214:217], v153 offset:39936
	global_load_lds_dwordx4 v[226:227], off
	v_lshl_add_u64 v[226:227], s[38:39], 0, v[132:133]
	s_mov_b32 m0, s49
	s_nop 0
	global_load_lds_dwordx4 v[226:227], off
	s_waitcnt vmcnt(8)
	s_waitcnt lgkmcnt(0)
	s_barrier
	v_mfma_f32_16x16x32_bf16 v[124:127], v[144:147], v[186:189], v[124:127]
	v_mfma_f32_16x16x32_bf16 v[120:123], v[162:165], v[186:189], v[120:123]
	v_mfma_f32_16x16x32_bf16 v[108:111], v[144:147], v[194:197], v[108:111]
	v_mfma_f32_16x16x32_bf16 v[104:107], v[162:165], v[194:197], v[104:107]
	v_mfma_f32_16x16x32_bf16 v[92:95], v[144:147], v[202:205], v[92:95]
	v_mfma_f32_16x16x32_bf16 v[88:91], v[162:165], v[202:205], v[88:91]
	v_mfma_f32_16x16x32_bf16 v[76:79], v[144:147], v[210:213], v[76:79]
	v_mfma_f32_16x16x32_bf16 v[72:75], v[162:165], v[210:213], v[72:75]
	v_mfma_f32_16x16x32_bf16 v[124:127], v[158:161], v[190:193], v[124:127]
	v_mfma_f32_16x16x32_bf16 v[120:123], v[166:169], v[190:193], v[120:123]
	v_mfma_f32_16x16x32_bf16 v[108:111], v[158:161], v[198:201], v[108:111]
	v_mfma_f32_16x16x32_bf16 v[104:107], v[166:169], v[198:201], v[104:107]
	v_mfma_f32_16x16x32_bf16 v[92:95], v[158:161], v[206:209], v[92:95]
	v_mfma_f32_16x16x32_bf16 v[88:91], v[166:169], v[206:209], v[88:91]
	v_mfma_f32_16x16x32_bf16 v[76:79], v[158:161], v[214:217], v[76:79]
	v_mfma_f32_16x16x32_bf16 v[72:75], v[166:169], v[214:217], v[72:75]
	v_mfma_f32_16x16x32_bf16 v[116:119], v[170:173], v[186:189], v[116:119]
	v_mfma_f32_16x16x32_bf16 v[112:115], v[178:181], v[186:189], v[112:115]
	v_mfma_f32_16x16x32_bf16 v[100:103], v[170:173], v[194:197], v[100:103]
	v_mfma_f32_16x16x32_bf16 v[96:99], v[178:181], v[194:197], v[96:99]
	v_mfma_f32_16x16x32_bf16 v[84:87], v[170:173], v[202:205], v[84:87]
	v_mfma_f32_16x16x32_bf16 v[80:83], v[178:181], v[202:205], v[80:83]
	v_mfma_f32_16x16x32_bf16 v[68:71], v[170:173], v[210:213], v[68:71]
	v_mfma_f32_16x16x32_bf16 v[64:67], v[178:181], v[210:213], v[64:67]
	v_mfma_f32_16x16x32_bf16 v[116:119], v[174:177], v[190:193], v[116:119]
	v_mfma_f32_16x16x32_bf16 v[112:115], v[182:185], v[190:193], v[112:115]
	v_mfma_f32_16x16x32_bf16 v[100:103], v[174:177], v[198:201], v[100:103]
	v_mfma_f32_16x16x32_bf16 v[96:99], v[182:185], v[198:201], v[96:99]
	v_mfma_f32_16x16x32_bf16 v[84:87], v[174:177], v[206:209], v[84:87]
	v_mfma_f32_16x16x32_bf16 v[80:83], v[182:185], v[206:209], v[80:83]
	v_mfma_f32_16x16x32_bf16 v[68:71], v[174:177], v[214:217], v[68:71]
	v_mfma_f32_16x16x32_bf16 v[64:67], v[182:185], v[214:217], v[64:67]
	s_barrier
	s_add_i32 s38, s64, s45
	v_lshl_add_u64 v[218:219], v[218:219], 0, s[10:11]
	s_mov_b32 m0, s38
	ds_read_b128 v[186:189], v153 offset:49152
	ds_read_b128 v[190:193], v153 offset:50176
	ds_read_b128 v[194:197], v153 offset:51200
	ds_read_b128 v[198:201], v153 offset:52224
	ds_read_b128 v[202:205], v153 offset:53248
	ds_read_b128 v[206:209], v153 offset:54272
	ds_read_b128 v[210:213], v153 offset:55296
	ds_read_b128 v[214:217], v153 offset:56320
	global_load_lds_dwordx4 v[218:219], off
	s_add_i32 m0, s38, 0x2000
	s_add_u32 s36, s36, 0x40080
	v_lshl_add_u64 v[218:219], v[220:221], 0, s[10:11]
	s_addc_u32 s37, s37, 0
	s_add_i32 s38, s65, s45
	global_load_lds_dwordx4 v[218:219], off
	v_lshl_add_u64 v[218:219], s[36:37], 0, v[130:131]
	s_mov_b32 m0, s38
	s_nop 0
	global_load_lds_dwordx4 v[218:219], off
	v_lshl_add_u64 v[218:219], s[36:37], 0, v[134:135]
	s_add_i32 m0, s38, 0x2000
	s_nop 0
	global_load_lds_dwordx4 v[218:219], off
	v_lshl_add_u64 v[218:219], v[222:223], 0, s[10:11]
	s_mov_b32 m0, s53
	s_nop 0
	global_load_lds_dwordx4 v[218:219], off
	v_lshl_add_u64 v[218:219], v[224:225], 0, s[10:11]
	s_mov_b32 m0, s54
	s_nop 0
	global_load_lds_dwordx4 v[218:219], off
	s_waitcnt vmcnt(8)
	s_waitcnt lgkmcnt(0)
	s_barrier
	v_mfma_f32_16x16x32_bf16 v[60:63], v[144:147], v[186:189], v[60:63]
	v_mfma_f32_16x16x32_bf16 v[56:59], v[162:165], v[186:189], v[56:59]
	v_mfma_f32_16x16x32_bf16 v[44:47], v[144:147], v[194:197], v[44:47]
	v_mfma_f32_16x16x32_bf16 v[40:43], v[162:165], v[194:197], v[40:43]
	v_mfma_f32_16x16x32_bf16 v[28:31], v[144:147], v[202:205], v[28:31]
	v_mfma_f32_16x16x32_bf16 v[24:27], v[162:165], v[202:205], v[24:27]
	v_mfma_f32_16x16x32_bf16 v[12:15], v[144:147], v[210:213], v[12:15]
	v_mfma_f32_16x16x32_bf16 v[8:11], v[162:165], v[210:213], v[8:11]
	v_mfma_f32_16x16x32_bf16 v[60:63], v[158:161], v[190:193], v[60:63]
	v_mfma_f32_16x16x32_bf16 v[56:59], v[166:169], v[190:193], v[56:59]
	v_mfma_f32_16x16x32_bf16 v[44:47], v[158:161], v[198:201], v[44:47]
	v_mfma_f32_16x16x32_bf16 v[40:43], v[166:169], v[198:201], v[40:43]
	v_mfma_f32_16x16x32_bf16 v[28:31], v[158:161], v[206:209], v[28:31]
	v_mfma_f32_16x16x32_bf16 v[24:27], v[166:169], v[206:209], v[24:27]
	v_mfma_f32_16x16x32_bf16 v[12:15], v[158:161], v[214:217], v[12:15]
	v_mfma_f32_16x16x32_bf16 v[8:11], v[166:169], v[214:217], v[8:11]
	v_mfma_f32_16x16x32_bf16 v[52:55], v[170:173], v[186:189], v[52:55]
	v_mfma_f32_16x16x32_bf16 v[48:51], v[178:181], v[186:189], v[48:51]
	v_mfma_f32_16x16x32_bf16 v[36:39], v[170:173], v[194:197], v[36:39]
	v_mfma_f32_16x16x32_bf16 v[32:35], v[178:181], v[194:197], v[32:35]
	v_mfma_f32_16x16x32_bf16 v[20:23], v[170:173], v[202:205], v[20:23]
	v_mfma_f32_16x16x32_bf16 v[16:19], v[178:181], v[202:205], v[16:19]
	v_mfma_f32_16x16x32_bf16 v[4:7], v[170:173], v[210:213], v[4:7]
	v_mfma_f32_16x16x32_bf16 v[0:3], v[178:181], v[210:213], v[0:3]
	v_mfma_f32_16x16x32_bf16 v[52:55], v[174:177], v[190:193], v[52:55]
	v_mfma_f32_16x16x32_bf16 v[48:51], v[182:185], v[190:193], v[48:51]
	v_mfma_f32_16x16x32_bf16 v[36:39], v[174:177], v[198:201], v[36:39]
	v_mfma_f32_16x16x32_bf16 v[32:35], v[182:185], v[198:201], v[32:35]
	v_mfma_f32_16x16x32_bf16 v[20:23], v[174:177], v[206:209], v[20:23]
	v_mfma_f32_16x16x32_bf16 v[16:19], v[182:185], v[206:209], v[16:19]
	v_mfma_f32_16x16x32_bf16 v[4:7], v[174:177], v[214:217], v[4:7]
	v_mfma_f32_16x16x32_bf16 v[0:3], v[182:185], v[214:217], v[0:3]
	s_barrier
	s_add_i32 s63, s63, 2
	s_add_u32 s61, s61, 0x100
	s_addc_u32 s62, s62, 0
	s_add_u32 s34, s34, 0x100
	s_addc_u32 s35, s35, 0
	s_cmp_gt_u32 s63, 13
	s_cbranch_scc0 .LBB0_226
	s_and_b64 vcc, exec, s[12:13]
	s_cbranch_vccz .LBB0_229
	s_barrier

.LBB0_599:
	ds_read_b128 v[144:147], v149
	ds_read_b128 v[156:159], v149 offset:1024
	ds_read_b128 v[160:163], v149 offset:2048
	ds_read_b128 v[164:167], v149 offset:3072
	ds_read_b128 v[168:171], v150
	ds_read_b128 v[172:175], v150 offset:1024
	ds_read_b128 v[176:179], v150 offset:2048
	ds_read_b128 v[180:183], v150 offset:3072
	s_add_u32 s34, s10, 0xfffc0080
	s_addc_u32 s35, s11, -1
	s_cmp_eq_u32 s60, 12
	s_cselect_b32 s37, s9, s35
	s_cselect_b32 s36, s19, s34
	s_cselect_b32 s35, s17, s59
	s_cselect_b32 s34, s31, s58
	v_lshl_add_u64 v[216:217], s[10:11], 0, v[138:139]
	s_add_i32 m0, s44, 0xc000
	ds_read_b128 v[184:187], v151
	ds_read_b128 v[188:191], v151 offset:1024
	ds_read_b128 v[192:195], v151 offset:2048
	ds_read_b128 v[196:199], v151 offset:3072
	ds_read_b128 v[200:203], v151 offset:4096
	ds_read_b128 v[204:207], v151 offset:5120
	ds_read_b128 v[208:211], v151 offset:6144
	ds_read_b128 v[212:215], v151 offset:7168
	global_load_lds_dwordx4 v[216:217], off
	v_lshl_add_u64 v[216:217], s[10:11], 0, v[136:137]
	s_add_i32 m0, s44, 0xe000
	s_nop 0
	global_load_lds_dwordx4 v[216:217], off
	s_waitcnt vmcnt(8)
	s_waitcnt lgkmcnt(0)
	s_barrier
	v_mfma_f32_16x16x32_bf16 v[124:127], v[144:147], v[184:187], v[124:127]
	v_mfma_f32_16x16x32_bf16 v[120:123], v[160:163], v[184:187], v[120:123]
	v_mfma_f32_16x16x32_bf16 v[108:111], v[144:147], v[192:195], v[108:111]
	v_mfma_f32_16x16x32_bf16 v[104:107], v[160:163], v[192:195], v[104:107]
	v_mfma_f32_16x16x32_bf16 v[92:95], v[144:147], v[200:203], v[92:95]
	v_mfma_f32_16x16x32_bf16 v[88:91], v[160:163], v[200:203], v[88:91]
	v_mfma_f32_16x16x32_bf16 v[76:79], v[144:147], v[208:211], v[76:79]
	v_mfma_f32_16x16x32_bf16 v[72:75], v[160:163], v[208:211], v[72:75]
	v_mfma_f32_16x16x32_bf16 v[124:127], v[156:159], v[188:191], v[124:127]
	v_mfma_f32_16x16x32_bf16 v[120:123], v[164:167], v[188:191], v[120:123]
	v_mfma_f32_16x16x32_bf16 v[108:111], v[156:159], v[196:199], v[108:111]
	v_mfma_f32_16x16x32_bf16 v[104:107], v[164:167], v[196:199], v[104:107]
	v_mfma_f32_16x16x32_bf16 v[92:95], v[156:159], v[204:207], v[92:95]
	v_mfma_f32_16x16x32_bf16 v[88:91], v[164:167], v[204:207], v[88:91]
	v_mfma_f32_16x16x32_bf16 v[76:79], v[156:159], v[212:215], v[76:79]
	v_mfma_f32_16x16x32_bf16 v[72:75], v[164:167], v[212:215], v[72:75]
	v_mfma_f32_16x16x32_bf16 v[116:119], v[168:171], v[184:187], v[116:119]
	v_mfma_f32_16x16x32_bf16 v[112:115], v[176:179], v[184:187], v[112:115]
	v_mfma_f32_16x16x32_bf16 v[100:103], v[168:171], v[192:195], v[100:103]
	v_mfma_f32_16x16x32_bf16 v[96:99], v[176:179], v[192:195], v[96:99]
	v_mfma_f32_16x16x32_bf16 v[84:87], v[168:171], v[200:203], v[84:87]
	v_mfma_f32_16x16x32_bf16 v[80:83], v[176:179], v[200:203], v[80:83]
	v_mfma_f32_16x16x32_bf16 v[68:71], v[168:171], v[208:211], v[68:71]
	v_mfma_f32_16x16x32_bf16 v[64:67], v[176:179], v[208:211], v[64:67]
	v_mfma_f32_16x16x32_bf16 v[116:119], v[172:175], v[188:191], v[116:119]
	v_mfma_f32_16x16x32_bf16 v[112:115], v[180:183], v[188:191], v[112:115]
	v_mfma_f32_16x16x32_bf16 v[100:103], v[172:175], v[196:199], v[100:103]
	v_mfma_f32_16x16x32_bf16 v[96:99], v[180:183], v[196:199], v[96:99]
	v_mfma_f32_16x16x32_bf16 v[84:87], v[172:175], v[204:207], v[84:87]
	v_mfma_f32_16x16x32_bf16 v[80:83], v[180:183], v[204:207], v[80:83]
	v_mfma_f32_16x16x32_bf16 v[68:71], v[172:175], v[212:215], v[68:71]
	v_mfma_f32_16x16x32_bf16 v[64:67], v[180:183], v[212:215], v[64:67]
	s_barrier
	s_add_i32 s61, s56, s43
	v_lshl_add_u64 v[216:217], s[34:35], 0, v[130:131]
	s_mov_b32 m0, s61
	ds_read_b128 v[184:187], v151 offset:16384
	ds_read_b128 v[188:191], v151 offset:17408
	ds_read_b128 v[192:195], v151 offset:18432
	ds_read_b128 v[196:199], v151 offset:19456
	ds_read_b128 v[200:203], v151 offset:20480
	ds_read_b128 v[204:207], v151 offset:21504
	ds_read_b128 v[208:211], v151 offset:22528
	ds_read_b128 v[212:215], v151 offset:23552
	global_load_lds_dwordx4 v[216:217], off
	s_add_i32 m0, s61, 0x2000
	s_add_u32 s62, s34, 0x40000
	v_lshl_add_u64 v[218:219], s[34:35], 0, v[134:135]
	s_addc_u32 s63, s35, 0
	s_add_i32 s61, s57, s43
	global_load_lds_dwordx4 v[218:219], off
	v_lshl_add_u64 v[220:221], s[62:63], 0, v[130:131]
	s_mov_b32 m0, s61
	v_lshl_add_u64 v[222:223], s[36:37], 0, v[132:133]
	global_load_lds_dwordx4 v[220:221], off
	v_lshl_add_u64 v[220:221], s[62:63], 0, v[134:135]
	s_add_i32 m0, s61, 0x2000
	s_nop 0
	global_load_lds_dwordx4 v[220:221], off
	v_lshl_add_u64 v[220:221], s[36:37], 0, v[128:129]
	s_mov_b32 m0, s44
	s_nop 0
	global_load_lds_dwordx4 v[220:221], off
	s_mov_b32 m0, s45
	s_nop 0
	global_load_lds_dwordx4 v[222:223], off
	s_waitcnt vmcnt(8)
	s_waitcnt lgkmcnt(0)
	s_barrier
	v_mfma_f32_16x16x32_bf16 v[60:63], v[144:147], v[184:187], v[60:63]
	v_mfma_f32_16x16x32_bf16 v[56:59], v[160:163], v[184:187], v[56:59]
	v_mfma_f32_16x16x32_bf16 v[44:47], v[144:147], v[192:195], v[44:47]
	v_mfma_f32_16x16x32_bf16 v[40:43], v[160:163], v[192:195], v[40:43]
	v_mfma_f32_16x16x32_bf16 v[28:31], v[144:147], v[200:203], v[28:31]
	v_mfma_f32_16x16x32_bf16 v[24:27], v[160:163], v[200:203], v[24:27]
	v_mfma_f32_16x16x32_bf16 v[12:15], v[144:147], v[208:211], v[12:15]
	v_mfma_f32_16x16x32_bf16 v[8:11], v[160:163], v[208:211], v[8:11]
	v_mfma_f32_16x16x32_bf16 v[60:63], v[156:159], v[188:191], v[60:63]
	v_mfma_f32_16x16x32_bf16 v[56:59], v[164:167], v[188:191], v[56:59]
	v_mfma_f32_16x16x32_bf16 v[44:47], v[156:159], v[196:199], v[44:47]
	v_mfma_f32_16x16x32_bf16 v[40:43], v[164:167], v[196:199], v[40:43]
	v_mfma_f32_16x16x32_bf16 v[28:31], v[156:159], v[204:207], v[28:31]
	v_mfma_f32_16x16x32_bf16 v[24:27], v[164:167], v[204:207], v[24:27]
	v_mfma_f32_16x16x32_bf16 v[12:15], v[156:159], v[212:215], v[12:15]
	v_mfma_f32_16x16x32_bf16 v[8:11], v[164:167], v[212:215], v[8:11]
	v_mfma_f32_16x16x32_bf16 v[52:55], v[168:171], v[184:187], v[52:55]
	v_mfma_f32_16x16x32_bf16 v[48:51], v[176:179], v[184:187], v[48:51]
	v_mfma_f32_16x16x32_bf16 v[36:39], v[168:171], v[192:195], v[36:39]
	v_mfma_f32_16x16x32_bf16 v[32:35], v[176:179], v[192:195], v[32:35]
	v_mfma_f32_16x16x32_bf16 v[20:23], v[168:171], v[200:203], v[20:23]
	v_mfma_f32_16x16x32_bf16 v[16:19], v[176:179], v[200:203], v[16:19]
	v_mfma_f32_16x16x32_bf16 v[4:7], v[168:171], v[208:211], v[4:7]
	v_mfma_f32_16x16x32_bf16 v[0:3], v[176:179], v[208:211], v[0:3]
	v_mfma_f32_16x16x32_bf16 v[52:55], v[172:175], v[188:191], v[52:55]
	v_mfma_f32_16x16x32_bf16 v[48:51], v[180:183], v[188:191], v[48:51]
	v_mfma_f32_16x16x32_bf16 v[36:39], v[172:175], v[196:199], v[36:39]
	v_mfma_f32_16x16x32_bf16 v[32:35], v[180:183], v[196:199], v[32:35]
	v_mfma_f32_16x16x32_bf16 v[20:23], v[172:175], v[204:207], v[20:23]
	v_mfma_f32_16x16x32_bf16 v[16:19], v[180:183], v[204:207], v[16:19]
	v_mfma_f32_16x16x32_bf16 v[4:7], v[172:175], v[212:215], v[4:7]
	v_mfma_f32_16x16x32_bf16 v[0:3], v[180:183], v[212:215], v[0:3]
	s_barrier
	s_add_i32 s61, 0, 0x18000
	v_add_u32_e32 v153, s61, v148
	s_add_i32 s62, 0, 0x1c000
	ds_read_b128 v[144:147], v153
	ds_read_b128 v[156:159], v153 offset:1024
	ds_read_b128 v[160:163], v153 offset:2048
	ds_read_b128 v[164:167], v153 offset:3072
	v_add_u32_e32 v153, s62, v148
	ds_read_b128 v[168:171], v153
	ds_read_b128 v[172:175], v153 offset:1024
	ds_read_b128 v[176:179], v153 offset:2048
	ds_read_b128 v[180:183], v153 offset:3072
	s_add_u32 s36, s36, 0x40000
	s_addc_u32 s37, s37, 0
	s_mov_b32 m0, s46
	v_lshl_add_u64 v[224:225], s[36:37], 0, v[128:129]
	ds_read_b128 v[184:187], v151 offset:32768
	ds_read_b128 v[188:191], v151 offset:33792
	ds_read_b128 v[192:195], v151 offset:34816
	ds_read_b128 v[196:199], v151 offset:35840
	ds_read_b128 v[200:203], v151 offset:36864
	ds_read_b128 v[204:207], v151 offset:37888
	ds_read_b128 v[208:211], v151 offset:38912
	ds_read_b128 v[212:215], v151 offset:39936
	global_load_lds_dwordx4 v[224:225], off
	v_lshl_add_u64 v[224:225], s[36:37], 0, v[132:133]
	s_mov_b32 m0, s47
	s_nop 0
	global_load_lds_dwordx4 v[224:225], off
	s_waitcnt vmcnt(8)
	s_waitcnt lgkmcnt(0)
	s_barrier
	v_mfma_f32_16x16x32_bf16 v[124:127], v[144:147], v[184:187], v[124:127]
	v_mfma_f32_16x16x32_bf16 v[120:123], v[160:163], v[184:187], v[120:123]
	v_mfma_f32_16x16x32_bf16 v[108:111], v[144:147], v[192:195], v[108:111]
	v_mfma_f32_16x16x32_bf16 v[104:107], v[160:163], v[192:195], v[104:107]
	v_mfma_f32_16x16x32_bf16 v[92:95], v[144:147], v[200:203], v[92:95]
	v_mfma_f32_16x16x32_bf16 v[88:91], v[160:163], v[200:203], v[88:91]
	v_mfma_f32_16x16x32_bf16 v[76:79], v[144:147], v[208:211], v[76:79]
	v_mfma_f32_16x16x32_bf16 v[72:75], v[160:163], v[208:211], v[72:75]
	v_mfma_f32_16x16x32_bf16 v[124:127], v[156:159], v[188:191], v[124:127]
	v_mfma_f32_16x16x32_bf16 v[120:123], v[164:167], v[188:191], v[120:123]
	v_mfma_f32_16x16x32_bf16 v[108:111], v[156:159], v[196:199], v[108:111]
	v_mfma_f32_16x16x32_bf16 v[104:107], v[164:167], v[196:199], v[104:107]
	v_mfma_f32_16x16x32_bf16 v[92:95], v[156:159], v[204:207], v[92:95]
	v_mfma_f32_16x16x32_bf16 v[88:91], v[164:167], v[204:207], v[88:91]
	v_mfma_f32_16x16x32_bf16 v[76:79], v[156:159], v[212:215], v[76:79]
	v_mfma_f32_16x16x32_bf16 v[72:75], v[164:167], v[212:215], v[72:75]
	v_mfma_f32_16x16x32_bf16 v[116:119], v[168:171], v[184:187], v[116:119]
	v_mfma_f32_16x16x32_bf16 v[112:115], v[176:179], v[184:187], v[112:115]
	v_mfma_f32_16x16x32_bf16 v[100:103], v[168:171], v[192:195], v[100:103]
	v_mfma_f32_16x16x32_bf16 v[96:99], v[176:179], v[192:195], v[96:99]
	v_mfma_f32_16x16x32_bf16 v[84:87], v[168:171], v[200:203], v[84:87]
	v_mfma_f32_16x16x32_bf16 v[80:83], v[176:179], v[200:203], v[80:83]
	v_mfma_f32_16x16x32_bf16 v[68:71], v[168:171], v[208:211], v[68:71]
	v_mfma_f32_16x16x32_bf16 v[64:67], v[176:179], v[208:211], v[64:67]
	v_mfma_f32_16x16x32_bf16 v[116:119], v[172:175], v[188:191], v[116:119]
	v_mfma_f32_16x16x32_bf16 v[112:115], v[180:183], v[188:191], v[112:115]
	v_mfma_f32_16x16x32_bf16 v[100:103], v[172:175], v[196:199], v[100:103]
	v_mfma_f32_16x16x32_bf16 v[96:99], v[180:183], v[196:199], v[96:99]
	v_mfma_f32_16x16x32_bf16 v[84:87], v[172:175], v[204:207], v[84:87]
	v_mfma_f32_16x16x32_bf16 v[80:83], v[180:183], v[204:207], v[80:83]
	v_mfma_f32_16x16x32_bf16 v[68:71], v[172:175], v[212:215], v[68:71]
	v_mfma_f32_16x16x32_bf16 v[64:67], v[180:183], v[212:215], v[64:67]
	s_barrier
	s_add_i32 s36, s61, s43
	v_lshl_add_u64 v[216:217], v[216:217], 0, s[12:13]
	s_mov_b32 m0, s36
	ds_read_b128 v[184:187], v151 offset:49152
	ds_read_b128 v[188:191], v151 offset:50176
	ds_read_b128 v[192:195], v151 offset:51200
	ds_read_b128 v[196:199], v151 offset:52224
	ds_read_b128 v[200:203], v151 offset:53248
	ds_read_b128 v[204:207], v151 offset:54272
	ds_read_b128 v[208:211], v151 offset:55296
	ds_read_b128 v[212:215], v151 offset:56320
	global_load_lds_dwordx4 v[216:217], off
	s_add_i32 m0, s36, 0x2000
	s_add_u32 s34, s34, 0x40080
	v_lshl_add_u64 v[216:217], v[218:219], 0, s[12:13]
	s_addc_u32 s35, s35, 0
	s_add_i32 s36, s62, s43
	global_load_lds_dwordx4 v[216:217], off
	v_lshl_add_u64 v[216:217], s[34:35], 0, v[130:131]
	s_mov_b32 m0, s36
	s_nop 0
	global_load_lds_dwordx4 v[216:217], off
	v_lshl_add_u64 v[216:217], s[34:35], 0, v[134:135]
	s_add_i32 m0, s36, 0x2000
	s_nop 0
	global_load_lds_dwordx4 v[216:217], off
	v_lshl_add_u64 v[216:217], v[220:221], 0, s[12:13]
	s_mov_b32 m0, s52
	s_nop 0
	global_load_lds_dwordx4 v[216:217], off
	v_lshl_add_u64 v[216:217], v[222:223], 0, s[12:13]
	s_mov_b32 m0, s53
	s_nop 0
	global_load_lds_dwordx4 v[216:217], off
	s_waitcnt vmcnt(8)
	s_waitcnt lgkmcnt(0)
	s_barrier
	v_mfma_f32_16x16x32_bf16 v[60:63], v[144:147], v[184:187], v[60:63]
	v_mfma_f32_16x16x32_bf16 v[56:59], v[160:163], v[184:187], v[56:59]
	v_mfma_f32_16x16x32_bf16 v[44:47], v[144:147], v[192:195], v[44:47]
	v_mfma_f32_16x16x32_bf16 v[40:43], v[160:163], v[192:195], v[40:43]
	v_mfma_f32_16x16x32_bf16 v[28:31], v[144:147], v[200:203], v[28:31]
	v_mfma_f32_16x16x32_bf16 v[24:27], v[160:163], v[200:203], v[24:27]
	v_mfma_f32_16x16x32_bf16 v[12:15], v[144:147], v[208:211], v[12:15]
	v_mfma_f32_16x16x32_bf16 v[8:11], v[160:163], v[208:211], v[8:11]
	v_mfma_f32_16x16x32_bf16 v[60:63], v[156:159], v[188:191], v[60:63]
	v_mfma_f32_16x16x32_bf16 v[56:59], v[164:167], v[188:191], v[56:59]
	v_mfma_f32_16x16x32_bf16 v[44:47], v[156:159], v[196:199], v[44:47]
	v_mfma_f32_16x16x32_bf16 v[40:43], v[164:167], v[196:199], v[40:43]
	v_mfma_f32_16x16x32_bf16 v[28:31], v[156:159], v[204:207], v[28:31]
	v_mfma_f32_16x16x32_bf16 v[24:27], v[164:167], v[204:207], v[24:27]
	v_mfma_f32_16x16x32_bf16 v[12:15], v[156:159], v[212:215], v[12:15]
	v_mfma_f32_16x16x32_bf16 v[8:11], v[164:167], v[212:215], v[8:11]
	v_mfma_f32_16x16x32_bf16 v[52:55], v[168:171], v[184:187], v[52:55]
	v_mfma_f32_16x16x32_bf16 v[48:51], v[176:179], v[184:187], v[48:51]
	v_mfma_f32_16x16x32_bf16 v[36:39], v[168:171], v[192:195], v[36:39]
	v_mfma_f32_16x16x32_bf16 v[32:35], v[176:179], v[192:195], v[32:35]
	v_mfma_f32_16x16x32_bf16 v[20:23], v[168:171], v[200:203], v[20:23]
	v_mfma_f32_16x16x32_bf16 v[16:19], v[176:179], v[200:203], v[16:19]
	v_mfma_f32_16x16x32_bf16 v[4:7], v[168:171], v[208:211], v[4:7]
	v_mfma_f32_16x16x32_bf16 v[0:3], v[176:179], v[208:211], v[0:3]
	v_mfma_f32_16x16x32_bf16 v[52:55], v[172:175], v[188:191], v[52:55]
	v_mfma_f32_16x16x32_bf16 v[48:51], v[180:183], v[188:191], v[48:51]
	v_mfma_f32_16x16x32_bf16 v[36:39], v[172:175], v[196:199], v[36:39]
	v_mfma_f32_16x16x32_bf16 v[32:35], v[180:183], v[196:199], v[32:35]
	v_mfma_f32_16x16x32_bf16 v[20:23], v[172:175], v[204:207], v[20:23]
	v_mfma_f32_16x16x32_bf16 v[16:19], v[180:183], v[204:207], v[16:19]
	v_mfma_f32_16x16x32_bf16 v[4:7], v[172:175], v[212:215], v[4:7]
	v_mfma_f32_16x16x32_bf16 v[0:3], v[180:183], v[212:215], v[0:3]
	s_barrier
	s_add_i32 s60, s60, 2
	s_add_u32 s58, s58, 0x100
	s_addc_u32 s59, s59, 0
	s_add_u32 s10, s10, 0x100
	s_addc_u32 s11, s11, 0
	s_cmp_gt_u32 s60, 13
	s_cbranch_scc0 .LBB0_599
	s_and_b64 vcc, exec, s[14:15]
	s_cbranch_vccz .LBB0_602
	s_barrier

.LBB0_683:
	ds_read_b128 v[144:147], v149
	ds_read_b128 v[156:159], v149 offset:1024
	ds_read_b128 v[160:163], v149 offset:2048
	ds_read_b128 v[164:167], v149 offset:3072
	ds_read_b128 v[168:171], v150
	ds_read_b128 v[172:175], v150 offset:1024
	ds_read_b128 v[176:179], v150 offset:2048
	ds_read_b128 v[180:183], v150 offset:3072
	s_add_u32 s36, s30, 0xfffc0080
	s_addc_u32 s37, s31, -1
	s_cmp_eq_u32 s63, 12
	s_cselect_b32 s39, s19, s37
	s_cselect_b32 s38, s59, s36
	s_cselect_b32 s37, s17, s62
	s_cselect_b32 s36, s60, s61
	v_lshl_add_u64 v[216:217], s[30:31], 0, v[138:139]
	s_add_i32 m0, s35, 0xc000
	ds_read_b128 v[184:187], v151
	ds_read_b128 v[188:191], v151 offset:1024
	ds_read_b128 v[192:195], v151 offset:2048
	ds_read_b128 v[196:199], v151 offset:3072
	ds_read_b128 v[200:203], v151 offset:4096
	ds_read_b128 v[204:207], v151 offset:5120
	ds_read_b128 v[208:211], v151 offset:6144
	ds_read_b128 v[212:215], v151 offset:7168
	global_load_lds_dwordx4 v[216:217], off
	v_lshl_add_u64 v[216:217], s[30:31], 0, v[136:137]
	s_add_i32 m0, s35, 0xe000
	s_nop 0
	global_load_lds_dwordx4 v[216:217], off
	s_waitcnt vmcnt(8)
	s_waitcnt lgkmcnt(0)
	s_barrier
	v_mfma_f32_16x16x32_bf16 v[124:127], v[144:147], v[184:187], v[124:127]
	v_mfma_f32_16x16x32_bf16 v[120:123], v[160:163], v[184:187], v[120:123]
	v_mfma_f32_16x16x32_bf16 v[108:111], v[144:147], v[192:195], v[108:111]
	v_mfma_f32_16x16x32_bf16 v[104:107], v[160:163], v[192:195], v[104:107]
	v_mfma_f32_16x16x32_bf16 v[92:95], v[144:147], v[200:203], v[92:95]
	v_mfma_f32_16x16x32_bf16 v[88:91], v[160:163], v[200:203], v[88:91]
	v_mfma_f32_16x16x32_bf16 v[76:79], v[144:147], v[208:211], v[76:79]
	v_mfma_f32_16x16x32_bf16 v[72:75], v[160:163], v[208:211], v[72:75]
	v_mfma_f32_16x16x32_bf16 v[124:127], v[156:159], v[188:191], v[124:127]
	v_mfma_f32_16x16x32_bf16 v[120:123], v[164:167], v[188:191], v[120:123]
	v_mfma_f32_16x16x32_bf16 v[108:111], v[156:159], v[196:199], v[108:111]
	v_mfma_f32_16x16x32_bf16 v[104:107], v[164:167], v[196:199], v[104:107]
	v_mfma_f32_16x16x32_bf16 v[92:95], v[156:159], v[204:207], v[92:95]
	v_mfma_f32_16x16x32_bf16 v[88:91], v[164:167], v[204:207], v[88:91]
	v_mfma_f32_16x16x32_bf16 v[76:79], v[156:159], v[212:215], v[76:79]
	v_mfma_f32_16x16x32_bf16 v[72:75], v[164:167], v[212:215], v[72:75]
	v_mfma_f32_16x16x32_bf16 v[116:119], v[168:171], v[184:187], v[116:119]
	v_mfma_f32_16x16x32_bf16 v[112:115], v[176:179], v[184:187], v[112:115]
	v_mfma_f32_16x16x32_bf16 v[100:103], v[168:171], v[192:195], v[100:103]
	v_mfma_f32_16x16x32_bf16 v[96:99], v[176:179], v[192:195], v[96:99]
	v_mfma_f32_16x16x32_bf16 v[84:87], v[168:171], v[200:203], v[84:87]
	v_mfma_f32_16x16x32_bf16 v[80:83], v[176:179], v[200:203], v[80:83]
	v_mfma_f32_16x16x32_bf16 v[68:71], v[168:171], v[208:211], v[68:71]
	v_mfma_f32_16x16x32_bf16 v[64:67], v[176:179], v[208:211], v[64:67]
	v_mfma_f32_16x16x32_bf16 v[116:119], v[172:175], v[188:191], v[116:119]
	v_mfma_f32_16x16x32_bf16 v[112:115], v[180:183], v[188:191], v[112:115]
	v_mfma_f32_16x16x32_bf16 v[100:103], v[172:175], v[196:199], v[100:103]
	v_mfma_f32_16x16x32_bf16 v[96:99], v[180:183], v[196:199], v[96:99]
	v_mfma_f32_16x16x32_bf16 v[84:87], v[172:175], v[204:207], v[84:87]
	v_mfma_f32_16x16x32_bf16 v[80:83], v[180:183], v[204:207], v[80:83]
	v_mfma_f32_16x16x32_bf16 v[68:71], v[172:175], v[212:215], v[68:71]
	v_mfma_f32_16x16x32_bf16 v[64:67], v[180:183], v[212:215], v[64:67]
	s_barrier
	s_add_i32 s64, s55, s43
	v_lshl_add_u64 v[216:217], s[36:37], 0, v[132:133]
	s_mov_b32 m0, s64
	ds_read_b128 v[184:187], v151 offset:16384
	ds_read_b128 v[188:191], v151 offset:17408
	ds_read_b128 v[192:195], v151 offset:18432
	ds_read_b128 v[196:199], v151 offset:19456
	ds_read_b128 v[200:203], v151 offset:20480
	ds_read_b128 v[204:207], v151 offset:21504
	ds_read_b128 v[208:211], v151 offset:22528
	ds_read_b128 v[212:215], v151 offset:23552
	global_load_lds_dwordx4 v[216:217], off
	s_add_i32 m0, s64, 0x2000
	s_add_u32 s64, s36, 0x40000
	v_lshl_add_u64 v[218:219], s[36:37], 0, v[128:129]
	s_addc_u32 s65, s37, 0
	s_add_i32 s66, s56, s43
	global_load_lds_dwordx4 v[218:219], off
	v_lshl_add_u64 v[220:221], s[64:65], 0, v[132:133]
	s_mov_b32 m0, s66
	v_lshl_add_u64 v[222:223], s[38:39], 0, v[130:131]
	global_load_lds_dwordx4 v[220:221], off
	v_lshl_add_u64 v[220:221], s[64:65], 0, v[128:129]
	s_add_i32 m0, s66, 0x2000
	s_nop 0
	global_load_lds_dwordx4 v[220:221], off
	v_lshl_add_u64 v[220:221], s[38:39], 0, v[134:135]
	s_mov_b32 m0, s35
	s_nop 0
	global_load_lds_dwordx4 v[220:221], off
	s_mov_b32 m0, s46
	s_nop 0
	global_load_lds_dwordx4 v[222:223], off
	s_waitcnt vmcnt(8)
	s_waitcnt lgkmcnt(0)
	s_barrier
	v_mfma_f32_16x16x32_bf16 v[60:63], v[144:147], v[184:187], v[60:63]
	v_mfma_f32_16x16x32_bf16 v[56:59], v[160:163], v[184:187], v[56:59]
	v_mfma_f32_16x16x32_bf16 v[44:47], v[144:147], v[192:195], v[44:47]
	v_mfma_f32_16x16x32_bf16 v[40:43], v[160:163], v[192:195], v[40:43]
	v_mfma_f32_16x16x32_bf16 v[28:31], v[144:147], v[200:203], v[28:31]
	v_mfma_f32_16x16x32_bf16 v[24:27], v[160:163], v[200:203], v[24:27]
	v_mfma_f32_16x16x32_bf16 v[12:15], v[144:147], v[208:211], v[12:15]
	v_mfma_f32_16x16x32_bf16 v[8:11], v[160:163], v[208:211], v[8:11]
	v_mfma_f32_16x16x32_bf16 v[60:63], v[156:159], v[188:191], v[60:63]
	v_mfma_f32_16x16x32_bf16 v[56:59], v[164:167], v[188:191], v[56:59]
	v_mfma_f32_16x16x32_bf16 v[44:47], v[156:159], v[196:199], v[44:47]
	v_mfma_f32_16x16x32_bf16 v[40:43], v[164:167], v[196:199], v[40:43]
	v_mfma_f32_16x16x32_bf16 v[28:31], v[156:159], v[204:207], v[28:31]
	v_mfma_f32_16x16x32_bf16 v[24:27], v[164:167], v[204:207], v[24:27]
	v_mfma_f32_16x16x32_bf16 v[12:15], v[156:159], v[212:215], v[12:15]
	v_mfma_f32_16x16x32_bf16 v[8:11], v[164:167], v[212:215], v[8:11]
	v_mfma_f32_16x16x32_bf16 v[52:55], v[168:171], v[184:187], v[52:55]
	v_mfma_f32_16x16x32_bf16 v[48:51], v[176:179], v[184:187], v[48:51]
	v_mfma_f32_16x16x32_bf16 v[36:39], v[168:171], v[192:195], v[36:39]
	v_mfma_f32_16x16x32_bf16 v[32:35], v[176:179], v[192:195], v[32:35]
	v_mfma_f32_16x16x32_bf16 v[20:23], v[168:171], v[200:203], v[20:23]
	v_mfma_f32_16x16x32_bf16 v[16:19], v[176:179], v[200:203], v[16:19]
	v_mfma_f32_16x16x32_bf16 v[4:7], v[168:171], v[208:211], v[4:7]
	v_mfma_f32_16x16x32_bf16 v[0:3], v[176:179], v[208:211], v[0:3]
	v_mfma_f32_16x16x32_bf16 v[52:55], v[172:175], v[188:191], v[52:55]
	v_mfma_f32_16x16x32_bf16 v[48:51], v[180:183], v[188:191], v[48:51]
	v_mfma_f32_16x16x32_bf16 v[36:39], v[172:175], v[196:199], v[36:39]
	v_mfma_f32_16x16x32_bf16 v[32:35], v[180:183], v[196:199], v[32:35]
	v_mfma_f32_16x16x32_bf16 v[20:23], v[172:175], v[204:207], v[20:23]
	v_mfma_f32_16x16x32_bf16 v[16:19], v[180:183], v[204:207], v[16:19]
	v_mfma_f32_16x16x32_bf16 v[4:7], v[172:175], v[212:215], v[4:7]
	v_mfma_f32_16x16x32_bf16 v[0:3], v[180:183], v[212:215], v[0:3]
	s_barrier
	s_add_i32 s64, 0, 0x18000
	v_add_u32_e32 v153, s64, v148
	s_add_i32 s65, 0, 0x1c000
	ds_read_b128 v[144:147], v153
	ds_read_b128 v[156:159], v153 offset:1024
	ds_read_b128 v[160:163], v153 offset:2048
	ds_read_b128 v[164:167], v153 offset:3072
	v_add_u32_e32 v153, s65, v148
	ds_read_b128 v[168:171], v153
	ds_read_b128 v[172:175], v153 offset:1024
	ds_read_b128 v[176:179], v153 offset:2048
	ds_read_b128 v[180:183], v153 offset:3072
	s_add_u32 s38, s38, 0x40000
	s_addc_u32 s39, s39, 0
	s_mov_b32 m0, s47
	v_lshl_add_u64 v[224:225], s[38:39], 0, v[134:135]
	ds_read_b128 v[184:187], v151 offset:32768
	ds_read_b128 v[188:191], v151 offset:33792
	ds_read_b128 v[192:195], v151 offset:34816
	ds_read_b128 v[196:199], v151 offset:35840
	ds_read_b128 v[200:203], v151 offset:36864
	ds_read_b128 v[204:207], v151 offset:37888
	ds_read_b128 v[208:211], v151 offset:38912
	ds_read_b128 v[212:215], v151 offset:39936
	global_load_lds_dwordx4 v[224:225], off
	v_lshl_add_u64 v[224:225], s[38:39], 0, v[130:131]
	s_mov_b32 m0, s48
	s_nop 0
	global_load_lds_dwordx4 v[224:225], off
	s_waitcnt vmcnt(8)
	s_waitcnt lgkmcnt(0)
	s_barrier
	v_mfma_f32_16x16x32_bf16 v[124:127], v[144:147], v[184:187], v[124:127]
	v_mfma_f32_16x16x32_bf16 v[120:123], v[160:163], v[184:187], v[120:123]
	v_mfma_f32_16x16x32_bf16 v[108:111], v[144:147], v[192:195], v[108:111]
	v_mfma_f32_16x16x32_bf16 v[104:107], v[160:163], v[192:195], v[104:107]
	v_mfma_f32_16x16x32_bf16 v[92:95], v[144:147], v[200:203], v[92:95]
	v_mfma_f32_16x16x32_bf16 v[88:91], v[160:163], v[200:203], v[88:91]
	v_mfma_f32_16x16x32_bf16 v[76:79], v[144:147], v[208:211], v[76:79]
	v_mfma_f32_16x16x32_bf16 v[72:75], v[160:163], v[208:211], v[72:75]
	v_mfma_f32_16x16x32_bf16 v[124:127], v[156:159], v[188:191], v[124:127]
	v_mfma_f32_16x16x32_bf16 v[120:123], v[164:167], v[188:191], v[120:123]
	v_mfma_f32_16x16x32_bf16 v[108:111], v[156:159], v[196:199], v[108:111]
	v_mfma_f32_16x16x32_bf16 v[104:107], v[164:167], v[196:199], v[104:107]
	v_mfma_f32_16x16x32_bf16 v[92:95], v[156:159], v[204:207], v[92:95]
	v_mfma_f32_16x16x32_bf16 v[88:91], v[164:167], v[204:207], v[88:91]
	v_mfma_f32_16x16x32_bf16 v[76:79], v[156:159], v[212:215], v[76:79]
	v_mfma_f32_16x16x32_bf16 v[72:75], v[164:167], v[212:215], v[72:75]
	v_mfma_f32_16x16x32_bf16 v[116:119], v[168:171], v[184:187], v[116:119]
	v_mfma_f32_16x16x32_bf16 v[112:115], v[176:179], v[184:187], v[112:115]
	v_mfma_f32_16x16x32_bf16 v[100:103], v[168:171], v[192:195], v[100:103]
	v_mfma_f32_16x16x32_bf16 v[96:99], v[176:179], v[192:195], v[96:99]
	v_mfma_f32_16x16x32_bf16 v[84:87], v[168:171], v[200:203], v[84:87]
	v_mfma_f32_16x16x32_bf16 v[80:83], v[176:179], v[200:203], v[80:83]
	v_mfma_f32_16x16x32_bf16 v[68:71], v[168:171], v[208:211], v[68:71]
	v_mfma_f32_16x16x32_bf16 v[64:67], v[176:179], v[208:211], v[64:67]
	v_mfma_f32_16x16x32_bf16 v[116:119], v[172:175], v[188:191], v[116:119]
	v_mfma_f32_16x16x32_bf16 v[112:115], v[180:183], v[188:191], v[112:115]
	v_mfma_f32_16x16x32_bf16 v[100:103], v[172:175], v[196:199], v[100:103]
	v_mfma_f32_16x16x32_bf16 v[96:99], v[180:183], v[196:199], v[96:99]
	v_mfma_f32_16x16x32_bf16 v[84:87], v[172:175], v[204:207], v[84:87]
	v_mfma_f32_16x16x32_bf16 v[80:83], v[180:183], v[204:207], v[80:83]
	v_mfma_f32_16x16x32_bf16 v[68:71], v[172:175], v[212:215], v[68:71]
	v_mfma_f32_16x16x32_bf16 v[64:67], v[180:183], v[212:215], v[64:67]
	s_barrier
	s_add_i32 s38, s64, s43
	v_lshl_add_u64 v[216:217], v[216:217], 0, s[10:11]
	s_mov_b32 m0, s38
	ds_read_b128 v[184:187], v151 offset:49152
	ds_read_b128 v[188:191], v151 offset:50176
	ds_read_b128 v[192:195], v151 offset:51200
	ds_read_b128 v[196:199], v151 offset:52224
	ds_read_b128 v[200:203], v151 offset:53248
	ds_read_b128 v[204:207], v151 offset:54272
	ds_read_b128 v[208:211], v151 offset:55296
	ds_read_b128 v[212:215], v151 offset:56320
	global_load_lds_dwordx4 v[216:217], off
	s_add_i32 m0, s38, 0x2000
	s_add_u32 s36, s36, 0x40080
	v_lshl_add_u64 v[216:217], v[218:219], 0, s[10:11]
	s_addc_u32 s37, s37, 0
	s_add_i32 s38, s65, s43
	global_load_lds_dwordx4 v[216:217], off
	v_lshl_add_u64 v[216:217], s[36:37], 0, v[132:133]
	s_mov_b32 m0, s38
	s_nop 0
	global_load_lds_dwordx4 v[216:217], off
	v_lshl_add_u64 v[216:217], s[36:37], 0, v[128:129]
	s_add_i32 m0, s38, 0x2000
	s_nop 0
	global_load_lds_dwordx4 v[216:217], off
	v_lshl_add_u64 v[216:217], v[220:221], 0, s[10:11]
	s_mov_b32 m0, s51
	s_nop 0
	global_load_lds_dwordx4 v[216:217], off
	v_lshl_add_u64 v[216:217], v[222:223], 0, s[10:11]
	s_mov_b32 m0, s52
	s_nop 0
	global_load_lds_dwordx4 v[216:217], off
	s_waitcnt vmcnt(8)
	s_waitcnt lgkmcnt(0)
	s_barrier
	v_mfma_f32_16x16x32_bf16 v[60:63], v[144:147], v[184:187], v[60:63]
	v_mfma_f32_16x16x32_bf16 v[56:59], v[160:163], v[184:187], v[56:59]
	v_mfma_f32_16x16x32_bf16 v[44:47], v[144:147], v[192:195], v[44:47]
	v_mfma_f32_16x16x32_bf16 v[40:43], v[160:163], v[192:195], v[40:43]
	v_mfma_f32_16x16x32_bf16 v[28:31], v[144:147], v[200:203], v[28:31]
	v_mfma_f32_16x16x32_bf16 v[24:27], v[160:163], v[200:203], v[24:27]
	v_mfma_f32_16x16x32_bf16 v[12:15], v[144:147], v[208:211], v[12:15]
	v_mfma_f32_16x16x32_bf16 v[8:11], v[160:163], v[208:211], v[8:11]
	v_mfma_f32_16x16x32_bf16 v[60:63], v[156:159], v[188:191], v[60:63]
	v_mfma_f32_16x16x32_bf16 v[56:59], v[164:167], v[188:191], v[56:59]
	v_mfma_f32_16x16x32_bf16 v[44:47], v[156:159], v[196:199], v[44:47]
	v_mfma_f32_16x16x32_bf16 v[40:43], v[164:167], v[196:199], v[40:43]
	v_mfma_f32_16x16x32_bf16 v[28:31], v[156:159], v[204:207], v[28:31]
	v_mfma_f32_16x16x32_bf16 v[24:27], v[164:167], v[204:207], v[24:27]
	v_mfma_f32_16x16x32_bf16 v[12:15], v[156:159], v[212:215], v[12:15]
	v_mfma_f32_16x16x32_bf16 v[8:11], v[164:167], v[212:215], v[8:11]
	v_mfma_f32_16x16x32_bf16 v[52:55], v[168:171], v[184:187], v[52:55]
	v_mfma_f32_16x16x32_bf16 v[48:51], v[176:179], v[184:187], v[48:51]
	v_mfma_f32_16x16x32_bf16 v[36:39], v[168:171], v[192:195], v[36:39]
	v_mfma_f32_16x16x32_bf16 v[32:35], v[176:179], v[192:195], v[32:35]
	v_mfma_f32_16x16x32_bf16 v[20:23], v[168:171], v[200:203], v[20:23]
	v_mfma_f32_16x16x32_bf16 v[16:19], v[176:179], v[200:203], v[16:19]
	v_mfma_f32_16x16x32_bf16 v[4:7], v[168:171], v[208:211], v[4:7]
	v_mfma_f32_16x16x32_bf16 v[0:3], v[176:179], v[208:211], v[0:3]
	v_mfma_f32_16x16x32_bf16 v[52:55], v[172:175], v[188:191], v[52:55]
	v_mfma_f32_16x16x32_bf16 v[48:51], v[180:183], v[188:191], v[48:51]
	v_mfma_f32_16x16x32_bf16 v[36:39], v[172:175], v[196:199], v[36:39]
	v_mfma_f32_16x16x32_bf16 v[32:35], v[180:183], v[196:199], v[32:35]
	v_mfma_f32_16x16x32_bf16 v[20:23], v[172:175], v[204:207], v[20:23]
	v_mfma_f32_16x16x32_bf16 v[16:19], v[180:183], v[204:207], v[16:19]
	v_mfma_f32_16x16x32_bf16 v[4:7], v[172:175], v[212:215], v[4:7]
	v_mfma_f32_16x16x32_bf16 v[0:3], v[180:183], v[212:215], v[0:3]
	s_barrier
	s_add_i32 s63, s63, 2
	s_add_u32 s61, s61, 0x100
	s_addc_u32 s62, s62, 0
	s_add_u32 s30, s30, 0x100
	s_addc_u32 s31, s31, 0
	s_cmp_gt_u32 s63, 13
	s_cbranch_scc0 .LBB0_683
	s_and_b64 vcc, exec, s[12:13]
	s_cbranch_vccz .LBB0_686
	s_barrier

.LBB0_707:
	s_add_u32 s49, s38, s48
	s_addc_u32 s54, s39, 0
	s_add_u32 s52, s49, 0x100
	s_addc_u32 s53, s54, 0
	s_and_b64 s[50:51], s[46:47], exec
	s_cselect_b32 s51, s35, s53
	s_cselect_b32 s50, s81, s52
	s_add_u32 s48, s36, s48
	s_addc_u32 s52, s37, 0
	s_add_u32 s48, s48, 0x100
	s_addc_u32 s52, s52, 0
	s_and_b64 s[46:47], s[46:47], exec
	s_cselect_b32 s53, s31, s52
	s_cselect_b32 s52, s82, s48
	s_add_u32 s56, s49, 0x10080
	ds_read_b128 v[144:147], v141
	ds_read_b128 v[148:151], v141 offset:1024
	ds_read_b128 v[156:159], v141 offset:2048
	ds_read_b128 v[160:163], v141 offset:3072
	ds_read_b128 v[164:167], v142
	ds_read_b128 v[168:171], v142 offset:1024
	ds_read_b128 v[172:175], v142 offset:2048
	ds_read_b128 v[176:179], v142 offset:3072
	s_addc_u32 s57, s54, 0
	s_add_i32 s90, s74, s63
	s_add_i32 m0, s29, 0xc000
	s_add_i32 s93, s29, 0xe000
	s_add_i32 s87, s90, 0x2000
	s_add_u32 s54, s52, 0x10000
	s_addc_u32 s55, s53, 0
	s_add_i32 s89, s75, s63
	s_add_i32 s88, s89, 0x2000
	s_add_i32 s86, 0, 0x18000
	s_add_i32 s85, 0, 0x1c000
	s_add_u32 s48, s50, 0x10000
	s_addc_u32 s49, s51, 0
	s_add_i32 s84, s86, s63
	s_add_i32 s83, s84, 0x2000
	s_add_u32 s46, s52, 0x10080
	s_addc_u32 s47, s53, 0
	s_add_i32 s92, s85, s63
	s_add_i32 s91, s92, 0x2000
	v_lshl_add_u64 v[152:153], s[56:57], 0, v[128:129]
	ds_read_b128 v[180:183], v143
	ds_read_b128 v[184:187], v143 offset:1024
	ds_read_b128 v[188:191], v143 offset:2048
	ds_read_b128 v[192:195], v143 offset:3072
	ds_read_b128 v[196:199], v143 offset:4096
	ds_read_b128 v[200:203], v143 offset:5120
	ds_read_b128 v[204:207], v143 offset:6144
	ds_read_b128 v[208:211], v143 offset:7168
	global_load_lds_dwordx4 v[152:153], off
	v_lshl_add_u64 v[152:153], s[56:57], 0, v[132:133]
	s_mov_b32 m0, s93
	s_nop 0
	global_load_lds_dwordx4 v[152:153], off
	s_waitcnt vmcnt(8)
	s_waitcnt lgkmcnt(0)
	s_barrier
	v_mfma_f32_16x16x32_bf16 v[124:127], v[144:147], v[180:183], v[124:127]
	v_mfma_f32_16x16x32_bf16 v[120:123], v[156:159], v[180:183], v[120:123]
	v_mfma_f32_16x16x32_bf16 v[116:119], v[144:147], v[188:191], v[116:119]
	v_mfma_f32_16x16x32_bf16 v[112:115], v[156:159], v[188:191], v[112:115]
	v_mfma_f32_16x16x32_bf16 v[100:103], v[144:147], v[196:199], v[100:103]
	v_mfma_f32_16x16x32_bf16 v[96:99], v[156:159], v[196:199], v[96:99]
	v_mfma_f32_16x16x32_bf16 v[84:87], v[144:147], v[204:207], v[84:87]
	v_mfma_f32_16x16x32_bf16 v[80:83], v[156:159], v[204:207], v[80:83]
	v_mfma_f32_16x16x32_bf16 v[124:127], v[148:151], v[184:187], v[124:127]
	v_mfma_f32_16x16x32_bf16 v[120:123], v[160:163], v[184:187], v[120:123]
	v_mfma_f32_16x16x32_bf16 v[116:119], v[148:151], v[192:195], v[116:119]
	v_mfma_f32_16x16x32_bf16 v[112:115], v[160:163], v[192:195], v[112:115]
	v_mfma_f32_16x16x32_bf16 v[100:103], v[148:151], v[200:203], v[100:103]
	v_mfma_f32_16x16x32_bf16 v[96:99], v[160:163], v[200:203], v[96:99]
	v_mfma_f32_16x16x32_bf16 v[84:87], v[148:151], v[208:211], v[84:87]
	v_mfma_f32_16x16x32_bf16 v[80:83], v[160:163], v[208:211], v[80:83]
	v_mfma_f32_16x16x32_bf16 v[108:111], v[164:167], v[180:183], v[108:111]
	v_mfma_f32_16x16x32_bf16 v[104:107], v[172:175], v[180:183], v[104:107]
	v_mfma_f32_16x16x32_bf16 v[92:95], v[164:167], v[188:191], v[92:95]
	v_mfma_f32_16x16x32_bf16 v[88:91], v[172:175], v[188:191], v[88:91]
	v_mfma_f32_16x16x32_bf16 v[76:79], v[164:167], v[196:199], v[76:79]
	v_mfma_f32_16x16x32_bf16 v[72:75], v[172:175], v[196:199], v[72:75]
	v_mfma_f32_16x16x32_bf16 v[68:71], v[164:167], v[204:207], v[68:71]
	v_mfma_f32_16x16x32_bf16 v[64:67], v[172:175], v[204:207], v[64:67]
	v_mfma_f32_16x16x32_bf16 v[108:111], v[168:171], v[184:187], v[108:111]
	v_mfma_f32_16x16x32_bf16 v[104:107], v[176:179], v[184:187], v[104:107]
	v_mfma_f32_16x16x32_bf16 v[92:95], v[168:171], v[192:195], v[92:95]
	v_mfma_f32_16x16x32_bf16 v[88:91], v[176:179], v[192:195], v[88:91]
	v_mfma_f32_16x16x32_bf16 v[76:79], v[168:171], v[200:203], v[76:79]
	v_mfma_f32_16x16x32_bf16 v[72:75], v[176:179], v[200:203], v[72:75]
	v_mfma_f32_16x16x32_bf16 v[68:71], v[168:171], v[208:211], v[68:71]
	v_mfma_f32_16x16x32_bf16 v[64:67], v[176:179], v[208:211], v[64:67]
	s_barrier
	s_mov_b32 m0, s90
	v_lshl_add_u64 v[152:153], s[52:53], 0, v[130:131]
	ds_read_b128 v[180:183], v143 offset:16384
	ds_read_b128 v[184:187], v143 offset:17408
	ds_read_b128 v[188:191], v143 offset:18432
	ds_read_b128 v[192:195], v143 offset:19456
	ds_read_b128 v[196:199], v143 offset:20480
	ds_read_b128 v[200:203], v143 offset:21504
	ds_read_b128 v[204:207], v143 offset:22528
	ds_read_b128 v[208:211], v143 offset:23552
	global_load_lds_dwordx4 v[152:153], off
	v_lshl_add_u64 v[212:213], s[52:53], 0, v[134:135]
	s_mov_b32 m0, s87
	v_lshl_add_u64 v[214:215], s[54:55], 0, v[130:131]
	global_load_lds_dwordx4 v[212:213], off
	s_mov_b32 m0, s89
	v_lshl_add_u64 v[216:217], s[50:51], 0, v[132:133]
	global_load_lds_dwordx4 v[214:215], off
	v_lshl_add_u64 v[214:215], s[54:55], 0, v[134:135]
	s_mov_b32 m0, s88
	s_nop 0
	global_load_lds_dwordx4 v[214:215], off
	v_lshl_add_u64 v[214:215], s[50:51], 0, v[128:129]
	s_mov_b32 m0, s29
	s_nop 0
	global_load_lds_dwordx4 v[214:215], off
	s_mov_b32 m0, s64
	s_nop 0
	global_load_lds_dwordx4 v[216:217], off
	s_waitcnt vmcnt(8)
	s_waitcnt lgkmcnt(0)
	s_barrier
	v_mfma_f32_16x16x32_bf16 v[60:63], v[144:147], v[180:183], v[60:63]
	v_mfma_f32_16x16x32_bf16 v[56:59], v[156:159], v[180:183], v[56:59]
	v_mfma_f32_16x16x32_bf16 v[52:55], v[144:147], v[188:191], v[52:55]
	v_mfma_f32_16x16x32_bf16 v[48:51], v[156:159], v[188:191], v[48:51]
	v_mfma_f32_16x16x32_bf16 v[36:39], v[144:147], v[196:199], v[36:39]
	v_mfma_f32_16x16x32_bf16 v[32:35], v[156:159], v[196:199], v[32:35]
	v_mfma_f32_16x16x32_bf16 v[20:23], v[144:147], v[204:207], v[20:23]
	v_mfma_f32_16x16x32_bf16 v[16:19], v[156:159], v[204:207], v[16:19]
	v_mfma_f32_16x16x32_bf16 v[60:63], v[148:151], v[184:187], v[60:63]
	v_mfma_f32_16x16x32_bf16 v[56:59], v[160:163], v[184:187], v[56:59]
	v_mfma_f32_16x16x32_bf16 v[52:55], v[148:151], v[192:195], v[52:55]
	v_mfma_f32_16x16x32_bf16 v[48:51], v[160:163], v[192:195], v[48:51]
	v_mfma_f32_16x16x32_bf16 v[36:39], v[148:151], v[200:203], v[36:39]
	v_mfma_f32_16x16x32_bf16 v[32:35], v[160:163], v[200:203], v[32:35]
	v_mfma_f32_16x16x32_bf16 v[20:23], v[148:151], v[208:211], v[20:23]
	v_mfma_f32_16x16x32_bf16 v[16:19], v[160:163], v[208:211], v[16:19]
	v_mfma_f32_16x16x32_bf16 v[44:47], v[164:167], v[180:183], v[44:47]
	v_mfma_f32_16x16x32_bf16 v[40:43], v[172:175], v[180:183], v[40:43]
	v_mfma_f32_16x16x32_bf16 v[28:31], v[164:167], v[188:191], v[28:31]
	v_mfma_f32_16x16x32_bf16 v[24:27], v[172:175], v[188:191], v[24:27]
	v_mfma_f32_16x16x32_bf16 v[12:15], v[164:167], v[196:199], v[12:15]
	v_mfma_f32_16x16x32_bf16 v[8:11], v[172:175], v[196:199], v[8:11]
	v_mfma_f32_16x16x32_bf16 v[4:7], v[164:167], v[204:207], v[4:7]
	v_mfma_f32_16x16x32_bf16 v[0:3], v[172:175], v[204:207], v[0:3]
	v_mfma_f32_16x16x32_bf16 v[44:47], v[168:171], v[184:187], v[44:47]
	v_mfma_f32_16x16x32_bf16 v[40:43], v[176:179], v[184:187], v[40:43]
	v_mfma_f32_16x16x32_bf16 v[28:31], v[168:171], v[192:195], v[28:31]
	v_mfma_f32_16x16x32_bf16 v[24:27], v[176:179], v[192:195], v[24:27]
	v_mfma_f32_16x16x32_bf16 v[12:15], v[168:171], v[200:203], v[12:15]
	v_mfma_f32_16x16x32_bf16 v[8:11], v[176:179], v[200:203], v[8:11]
	v_mfma_f32_16x16x32_bf16 v[4:7], v[168:171], v[208:211], v[4:7]
	v_mfma_f32_16x16x32_bf16 v[0:3], v[176:179], v[208:211], v[0:3]
	s_barrier
	v_add_u32_e32 v160, s86, v140
	v_add_u32_e32 v176, s85, v140
	ds_read_b128 v[144:147], v160
	ds_read_b128 v[148:151], v160 offset:1024
	ds_read_b128 v[156:159], v160 offset:2048
	ds_read_b128 v[160:163], v160 offset:3072
	ds_read_b128 v[164:167], v176
	ds_read_b128 v[168:171], v176 offset:1024
	ds_read_b128 v[172:175], v176 offset:2048
	ds_read_b128 v[176:179], v176 offset:3072
	s_mov_b32 m0, s65
	v_lshl_add_u64 v[218:219], s[48:49], 0, v[128:129]
	ds_read_b128 v[180:183], v143 offset:32768
	ds_read_b128 v[184:187], v143 offset:33792
	ds_read_b128 v[188:191], v143 offset:34816
	ds_read_b128 v[192:195], v143 offset:35840
	ds_read_b128 v[196:199], v143 offset:36864
	ds_read_b128 v[200:203], v143 offset:37888
	ds_read_b128 v[204:207], v143 offset:38912
	ds_read_b128 v[208:211], v143 offset:39936
	global_load_lds_dwordx4 v[218:219], off
	v_lshl_add_u64 v[218:219], s[48:49], 0, v[132:133]
	s_mov_b32 m0, s66
	s_nop 0
	global_load_lds_dwordx4 v[218:219], off
	s_waitcnt vmcnt(8)
	s_waitcnt lgkmcnt(0)
	s_barrier
	v_mfma_f32_16x16x32_bf16 v[124:127], v[144:147], v[180:183], v[124:127]
	v_mfma_f32_16x16x32_bf16 v[120:123], v[156:159], v[180:183], v[120:123]
	v_mfma_f32_16x16x32_bf16 v[116:119], v[144:147], v[188:191], v[116:119]
	v_mfma_f32_16x16x32_bf16 v[112:115], v[156:159], v[188:191], v[112:115]
	v_mfma_f32_16x16x32_bf16 v[100:103], v[144:147], v[196:199], v[100:103]
	v_mfma_f32_16x16x32_bf16 v[96:99], v[156:159], v[196:199], v[96:99]
	v_mfma_f32_16x16x32_bf16 v[84:87], v[144:147], v[204:207], v[84:87]
	v_mfma_f32_16x16x32_bf16 v[80:83], v[156:159], v[204:207], v[80:83]
	v_mfma_f32_16x16x32_bf16 v[124:127], v[148:151], v[184:187], v[124:127]
	v_mfma_f32_16x16x32_bf16 v[120:123], v[160:163], v[184:187], v[120:123]
	v_mfma_f32_16x16x32_bf16 v[116:119], v[148:151], v[192:195], v[116:119]
	v_mfma_f32_16x16x32_bf16 v[112:115], v[160:163], v[192:195], v[112:115]
	v_mfma_f32_16x16x32_bf16 v[100:103], v[148:151], v[200:203], v[100:103]
	v_mfma_f32_16x16x32_bf16 v[96:99], v[160:163], v[200:203], v[96:99]
	v_mfma_f32_16x16x32_bf16 v[84:87], v[148:151], v[208:211], v[84:87]
	v_mfma_f32_16x16x32_bf16 v[80:83], v[160:163], v[208:211], v[80:83]
	v_mfma_f32_16x16x32_bf16 v[108:111], v[164:167], v[180:183], v[108:111]
	v_mfma_f32_16x16x32_bf16 v[104:107], v[172:175], v[180:183], v[104:107]
	v_mfma_f32_16x16x32_bf16 v[92:95], v[164:167], v[188:191], v[92:95]
	v_mfma_f32_16x16x32_bf16 v[88:91], v[172:175], v[188:191], v[88:91]
	v_mfma_f32_16x16x32_bf16 v[76:79], v[164:167], v[196:199], v[76:79]
	v_mfma_f32_16x16x32_bf16 v[72:75], v[172:175], v[196:199], v[72:75]
	v_mfma_f32_16x16x32_bf16 v[68:71], v[164:167], v[204:207], v[68:71]
	v_mfma_f32_16x16x32_bf16 v[64:67], v[172:175], v[204:207], v[64:67]
	v_mfma_f32_16x16x32_bf16 v[108:111], v[168:171], v[184:187], v[108:111]
	v_mfma_f32_16x16x32_bf16 v[104:107], v[176:179], v[184:187], v[104:107]
	v_mfma_f32_16x16x32_bf16 v[92:95], v[168:171], v[192:195], v[92:95]
	v_mfma_f32_16x16x32_bf16 v[88:91], v[176:179], v[192:195], v[88:91]
	v_mfma_f32_16x16x32_bf16 v[76:79], v[168:171], v[200:203], v[76:79]
	v_mfma_f32_16x16x32_bf16 v[72:75], v[176:179], v[200:203], v[72:75]
	v_mfma_f32_16x16x32_bf16 v[68:71], v[168:171], v[208:211], v[68:71]
	v_mfma_f32_16x16x32_bf16 v[64:67], v[176:179], v[208:211], v[64:67]
	s_barrier
	s_mov_b32 m0, s84
	v_lshl_add_u64 v[152:153], v[152:153], 0, s[8:9]
	ds_read_b128 v[180:183], v143 offset:49152
	ds_read_b128 v[184:187], v143 offset:50176
	ds_read_b128 v[188:191], v143 offset:51200
	ds_read_b128 v[192:195], v143 offset:52224
	ds_read_b128 v[196:199], v143 offset:53248
	ds_read_b128 v[200:203], v143 offset:54272
	ds_read_b128 v[204:207], v143 offset:55296
	ds_read_b128 v[208:211], v143 offset:56320
	global_load_lds_dwordx4 v[152:153], off
	v_lshl_add_u64 v[152:153], v[212:213], 0, s[8:9]
	s_mov_b32 m0, s83
	s_nop 0
	global_load_lds_dwordx4 v[152:153], off
	v_lshl_add_u64 v[152:153], s[46:47], 0, v[130:131]
	s_mov_b32 m0, s92
	s_nop 0
	global_load_lds_dwordx4 v[152:153], off
	v_lshl_add_u64 v[152:153], s[46:47], 0, v[134:135]
	s_mov_b32 m0, s91
	s_nop 0
	global_load_lds_dwordx4 v[152:153], off
	v_lshl_add_u64 v[152:153], v[214:215], 0, s[8:9]
	s_mov_b32 m0, s71
	s_nop 0
	global_load_lds_dwordx4 v[152:153], off
	v_lshl_add_u64 v[152:153], v[216:217], 0, s[8:9]
	s_mov_b32 m0, s72
	s_nop 0
	global_load_lds_dwordx4 v[152:153], off
	s_waitcnt vmcnt(8)
	s_waitcnt lgkmcnt(0)
	s_barrier
	v_mfma_f32_16x16x32_bf16 v[60:63], v[144:147], v[180:183], v[60:63]
	v_mfma_f32_16x16x32_bf16 v[56:59], v[156:159], v[180:183], v[56:59]
	v_mfma_f32_16x16x32_bf16 v[52:55], v[144:147], v[188:191], v[52:55]
	v_mfma_f32_16x16x32_bf16 v[48:51], v[156:159], v[188:191], v[48:51]
	v_mfma_f32_16x16x32_bf16 v[36:39], v[144:147], v[196:199], v[36:39]
	v_mfma_f32_16x16x32_bf16 v[32:35], v[156:159], v[196:199], v[32:35]
	v_mfma_f32_16x16x32_bf16 v[20:23], v[144:147], v[204:207], v[20:23]
	v_mfma_f32_16x16x32_bf16 v[16:19], v[156:159], v[204:207], v[16:19]
	v_mfma_f32_16x16x32_bf16 v[60:63], v[148:151], v[184:187], v[60:63]
	v_mfma_f32_16x16x32_bf16 v[56:59], v[160:163], v[184:187], v[56:59]
	v_mfma_f32_16x16x32_bf16 v[52:55], v[148:151], v[192:195], v[52:55]
	v_mfma_f32_16x16x32_bf16 v[48:51], v[160:163], v[192:195], v[48:51]
	v_mfma_f32_16x16x32_bf16 v[36:39], v[148:151], v[200:203], v[36:39]
	v_mfma_f32_16x16x32_bf16 v[32:35], v[160:163], v[200:203], v[32:35]
	v_mfma_f32_16x16x32_bf16 v[20:23], v[148:151], v[208:211], v[20:23]
	v_mfma_f32_16x16x32_bf16 v[16:19], v[160:163], v[208:211], v[16:19]
	v_mfma_f32_16x16x32_bf16 v[44:47], v[164:167], v[180:183], v[44:47]
	v_mfma_f32_16x16x32_bf16 v[40:43], v[172:175], v[180:183], v[40:43]
	v_mfma_f32_16x16x32_bf16 v[28:31], v[164:167], v[188:191], v[28:31]
	v_mfma_f32_16x16x32_bf16 v[24:27], v[172:175], v[188:191], v[24:27]
	v_mfma_f32_16x16x32_bf16 v[12:15], v[164:167], v[196:199], v[12:15]
	v_mfma_f32_16x16x32_bf16 v[8:11], v[172:175], v[196:199], v[8:11]
	v_mfma_f32_16x16x32_bf16 v[4:7], v[164:167], v[204:207], v[4:7]
	v_mfma_f32_16x16x32_bf16 v[0:3], v[172:175], v[204:207], v[0:3]
	v_mfma_f32_16x16x32_bf16 v[44:47], v[168:171], v[184:187], v[44:47]
	v_mfma_f32_16x16x32_bf16 v[40:43], v[176:179], v[184:187], v[40:43]
	v_mfma_f32_16x16x32_bf16 v[28:31], v[168:171], v[192:195], v[28:31]
	v_mfma_f32_16x16x32_bf16 v[24:27], v[176:179], v[192:195], v[24:27]
	v_mfma_f32_16x16x32_bf16 v[12:15], v[168:171], v[200:203], v[12:15]
	v_mfma_f32_16x16x32_bf16 v[8:11], v[176:179], v[200:203], v[8:11]
	v_mfma_f32_16x16x32_bf16 v[4:7], v[168:171], v[208:211], v[4:7]
	v_mfma_f32_16x16x32_bf16 v[0:3], v[176:179], v[208:211], v[0:3]
	s_barrier
	s_movk_i32 s48, 0x100
	s_andn2_b64 vcc, exec, s[44:45]
	s_mov_b64 s[46:47], -1
	s_mov_b64 s[44:45], 0
	s_cbranch_vccz .LBB0_707
	s_and_b64 vcc, exec, s[10:11]
	s_cbranch_vccz .LBB0_710
	s_barrier

.LBB0_789:
	ds_read_b128 v[144:147], v149
	ds_read_b128 v[156:159], v149 offset:1024
	ds_read_b128 v[160:163], v149 offset:2048
	ds_read_b128 v[164:167], v149 offset:3072
	ds_read_b128 v[168:171], v150
	ds_read_b128 v[172:175], v150 offset:1024
	ds_read_b128 v[176:179], v150 offset:2048
	ds_read_b128 v[180:183], v150 offset:3072
	s_add_u32 s10, s8, 0x100
	s_addc_u32 s11, s9, 0
	s_cmp_eq_u32 s58, 40
	s_cselect_b32 s29, s7, s11
	s_cselect_b32 s28, s6, s10
	s_cselect_b32 s27, s19, s57
	s_cselect_b32 s26, s18, s56
	v_lshl_add_u64 v[216:217], s[8:9], 0, v[138:139]
	s_add_i32 m0, s38, 0xc000
	ds_read_b128 v[184:187], v151
	ds_read_b128 v[188:191], v151 offset:1024
	ds_read_b128 v[192:195], v151 offset:2048
	ds_read_b128 v[196:199], v151 offset:3072
	ds_read_b128 v[200:203], v151 offset:4096
	ds_read_b128 v[204:207], v151 offset:5120
	ds_read_b128 v[208:211], v151 offset:6144
	ds_read_b128 v[212:215], v151 offset:7168
	global_load_lds_dwordx4 v[216:217], off
	v_lshl_add_u64 v[216:217], s[8:9], 0, v[136:137]
	s_add_i32 m0, s38, 0xe000
	s_nop 0
	global_load_lds_dwordx4 v[216:217], off
	s_waitcnt vmcnt(8)
	s_waitcnt lgkmcnt(0)
	s_barrier
	v_mfma_f32_16x16x32_bf16 v[124:127], v[144:147], v[184:187], v[124:127]
	v_mfma_f32_16x16x32_bf16 v[120:123], v[160:163], v[184:187], v[120:123]
	v_mfma_f32_16x16x32_bf16 v[108:111], v[144:147], v[192:195], v[108:111]
	v_mfma_f32_16x16x32_bf16 v[104:107], v[160:163], v[192:195], v[104:107]
	v_mfma_f32_16x16x32_bf16 v[92:95], v[144:147], v[200:203], v[92:95]
	v_mfma_f32_16x16x32_bf16 v[88:91], v[160:163], v[200:203], v[88:91]
	v_mfma_f32_16x16x32_bf16 v[76:79], v[144:147], v[208:211], v[76:79]
	v_mfma_f32_16x16x32_bf16 v[72:75], v[160:163], v[208:211], v[72:75]
	v_mfma_f32_16x16x32_bf16 v[124:127], v[156:159], v[188:191], v[124:127]
	v_mfma_f32_16x16x32_bf16 v[120:123], v[164:167], v[188:191], v[120:123]
	v_mfma_f32_16x16x32_bf16 v[108:111], v[156:159], v[196:199], v[108:111]
	v_mfma_f32_16x16x32_bf16 v[104:107], v[164:167], v[196:199], v[104:107]
	v_mfma_f32_16x16x32_bf16 v[92:95], v[156:159], v[204:207], v[92:95]
	v_mfma_f32_16x16x32_bf16 v[88:91], v[164:167], v[204:207], v[88:91]
	v_mfma_f32_16x16x32_bf16 v[76:79], v[156:159], v[212:215], v[76:79]
	v_mfma_f32_16x16x32_bf16 v[72:75], v[164:167], v[212:215], v[72:75]
	v_mfma_f32_16x16x32_bf16 v[116:119], v[168:171], v[184:187], v[116:119]
	v_mfma_f32_16x16x32_bf16 v[112:115], v[176:179], v[184:187], v[112:115]
	v_mfma_f32_16x16x32_bf16 v[100:103], v[168:171], v[192:195], v[100:103]
	v_mfma_f32_16x16x32_bf16 v[96:99], v[176:179], v[192:195], v[96:99]
	v_mfma_f32_16x16x32_bf16 v[84:87], v[168:171], v[200:203], v[84:87]
	v_mfma_f32_16x16x32_bf16 v[80:83], v[176:179], v[200:203], v[80:83]
	v_mfma_f32_16x16x32_bf16 v[68:71], v[168:171], v[208:211], v[68:71]
	v_mfma_f32_16x16x32_bf16 v[64:67], v[176:179], v[208:211], v[64:67]
	v_mfma_f32_16x16x32_bf16 v[116:119], v[172:175], v[188:191], v[116:119]
	v_mfma_f32_16x16x32_bf16 v[112:115], v[180:183], v[188:191], v[112:115]
	v_mfma_f32_16x16x32_bf16 v[100:103], v[172:175], v[196:199], v[100:103]
	v_mfma_f32_16x16x32_bf16 v[96:99], v[180:183], v[196:199], v[96:99]
	v_mfma_f32_16x16x32_bf16 v[84:87], v[172:175], v[204:207], v[84:87]
	v_mfma_f32_16x16x32_bf16 v[80:83], v[180:183], v[204:207], v[80:83]
	v_mfma_f32_16x16x32_bf16 v[68:71], v[172:175], v[212:215], v[68:71]
	v_mfma_f32_16x16x32_bf16 v[64:67], v[180:183], v[212:215], v[64:67]
	s_barrier
	s_add_i32 s8, s50, s37
	v_lshl_add_u64 v[216:217], s[26:27], 0, v[130:131]
	s_mov_b32 m0, s8
	ds_read_b128 v[184:187], v151 offset:16384
	ds_read_b128 v[188:191], v151 offset:17408
	ds_read_b128 v[192:195], v151 offset:18432
	ds_read_b128 v[196:199], v151 offset:19456
	ds_read_b128 v[200:203], v151 offset:20480
	ds_read_b128 v[204:207], v151 offset:21504
	ds_read_b128 v[208:211], v151 offset:22528
	ds_read_b128 v[212:215], v151 offset:23552
	global_load_lds_dwordx4 v[216:217], off
	s_add_i32 m0, s8, 0x2000
	s_add_u32 s8, s26, 0xb0000
	v_lshl_add_u64 v[218:219], s[26:27], 0, v[134:135]
	s_addc_u32 s9, s27, 0
	s_add_i32 s59, s51, s37
	global_load_lds_dwordx4 v[218:219], off
	v_lshl_add_u64 v[220:221], s[8:9], 0, v[130:131]
	s_mov_b32 m0, s59
	v_lshl_add_u64 v[222:223], s[28:29], 0, v[132:133]
	global_load_lds_dwordx4 v[220:221], off
	v_lshl_add_u64 v[220:221], s[8:9], 0, v[134:135]
	s_add_i32 m0, s59, 0x2000
	s_nop 0
	global_load_lds_dwordx4 v[220:221], off
	v_lshl_add_u64 v[220:221], s[28:29], 0, v[128:129]
	s_mov_b32 m0, s38
	s_nop 0
	global_load_lds_dwordx4 v[220:221], off
	s_mov_b32 m0, s39
	s_nop 0
	global_load_lds_dwordx4 v[222:223], off
	s_waitcnt vmcnt(8)
	s_waitcnt lgkmcnt(0)
	s_barrier
	v_mfma_f32_16x16x32_bf16 v[60:63], v[144:147], v[184:187], v[60:63]
	v_mfma_f32_16x16x32_bf16 v[56:59], v[160:163], v[184:187], v[56:59]
	v_mfma_f32_16x16x32_bf16 v[44:47], v[144:147], v[192:195], v[44:47]
	v_mfma_f32_16x16x32_bf16 v[40:43], v[160:163], v[192:195], v[40:43]
	v_mfma_f32_16x16x32_bf16 v[28:31], v[144:147], v[200:203], v[28:31]
	v_mfma_f32_16x16x32_bf16 v[24:27], v[160:163], v[200:203], v[24:27]
	v_mfma_f32_16x16x32_bf16 v[12:15], v[144:147], v[208:211], v[12:15]
	v_mfma_f32_16x16x32_bf16 v[8:11], v[160:163], v[208:211], v[8:11]
	v_mfma_f32_16x16x32_bf16 v[60:63], v[156:159], v[188:191], v[60:63]
	v_mfma_f32_16x16x32_bf16 v[56:59], v[164:167], v[188:191], v[56:59]
	v_mfma_f32_16x16x32_bf16 v[44:47], v[156:159], v[196:199], v[44:47]
	v_mfma_f32_16x16x32_bf16 v[40:43], v[164:167], v[196:199], v[40:43]
	v_mfma_f32_16x16x32_bf16 v[28:31], v[156:159], v[204:207], v[28:31]
	v_mfma_f32_16x16x32_bf16 v[24:27], v[164:167], v[204:207], v[24:27]
	v_mfma_f32_16x16x32_bf16 v[12:15], v[156:159], v[212:215], v[12:15]
	v_mfma_f32_16x16x32_bf16 v[8:11], v[164:167], v[212:215], v[8:11]
	v_mfma_f32_16x16x32_bf16 v[52:55], v[168:171], v[184:187], v[52:55]
	v_mfma_f32_16x16x32_bf16 v[48:51], v[176:179], v[184:187], v[48:51]
	v_mfma_f32_16x16x32_bf16 v[36:39], v[168:171], v[192:195], v[36:39]
	v_mfma_f32_16x16x32_bf16 v[32:35], v[176:179], v[192:195], v[32:35]
	v_mfma_f32_16x16x32_bf16 v[20:23], v[168:171], v[200:203], v[20:23]
	v_mfma_f32_16x16x32_bf16 v[16:19], v[176:179], v[200:203], v[16:19]
	v_mfma_f32_16x16x32_bf16 v[4:7], v[168:171], v[208:211], v[4:7]
	v_mfma_f32_16x16x32_bf16 v[0:3], v[176:179], v[208:211], v[0:3]
	v_mfma_f32_16x16x32_bf16 v[52:55], v[172:175], v[188:191], v[52:55]
	v_mfma_f32_16x16x32_bf16 v[48:51], v[180:183], v[188:191], v[48:51]
	v_mfma_f32_16x16x32_bf16 v[36:39], v[172:175], v[196:199], v[36:39]
	v_mfma_f32_16x16x32_bf16 v[32:35], v[180:183], v[196:199], v[32:35]
	v_mfma_f32_16x16x32_bf16 v[20:23], v[172:175], v[204:207], v[20:23]
	v_mfma_f32_16x16x32_bf16 v[16:19], v[180:183], v[204:207], v[16:19]
	v_mfma_f32_16x16x32_bf16 v[4:7], v[172:175], v[212:215], v[4:7]
	v_mfma_f32_16x16x32_bf16 v[0:3], v[180:183], v[212:215], v[0:3]
	s_barrier
	s_add_i32 s59, 0, 0x18000
	v_add_u32_e32 v153, s59, v148
	s_add_i32 s60, 0, 0x1c000
	ds_read_b128 v[144:147], v153
	ds_read_b128 v[156:159], v153 offset:1024
	ds_read_b128 v[160:163], v153 offset:2048
	ds_read_b128 v[164:167], v153 offset:3072
	v_add_u32_e32 v153, s60, v148
	ds_read_b128 v[168:171], v153
	ds_read_b128 v[172:175], v153 offset:1024
	ds_read_b128 v[176:179], v153 offset:2048
	ds_read_b128 v[180:183], v153 offset:3072
	s_add_u32 s8, s28, 0xb0000
	s_addc_u32 s9, s29, 0
	s_mov_b32 m0, s40
	v_lshl_add_u64 v[224:225], s[8:9], 0, v[128:129]
	ds_read_b128 v[184:187], v151 offset:32768
	ds_read_b128 v[188:191], v151 offset:33792
	ds_read_b128 v[192:195], v151 offset:34816
	ds_read_b128 v[196:199], v151 offset:35840
	ds_read_b128 v[200:203], v151 offset:36864
	ds_read_b128 v[204:207], v151 offset:37888
	ds_read_b128 v[208:211], v151 offset:38912
	ds_read_b128 v[212:215], v151 offset:39936
	global_load_lds_dwordx4 v[224:225], off
	v_lshl_add_u64 v[224:225], s[8:9], 0, v[132:133]
	s_mov_b32 m0, s41
	s_nop 0
	global_load_lds_dwordx4 v[224:225], off
	s_waitcnt vmcnt(8)
	s_waitcnt lgkmcnt(0)
	s_barrier
	v_mfma_f32_16x16x32_bf16 v[124:127], v[144:147], v[184:187], v[124:127]
	v_mfma_f32_16x16x32_bf16 v[120:123], v[160:163], v[184:187], v[120:123]
	v_mfma_f32_16x16x32_bf16 v[108:111], v[144:147], v[192:195], v[108:111]
	v_mfma_f32_16x16x32_bf16 v[104:107], v[160:163], v[192:195], v[104:107]
	v_mfma_f32_16x16x32_bf16 v[92:95], v[144:147], v[200:203], v[92:95]
	v_mfma_f32_16x16x32_bf16 v[88:91], v[160:163], v[200:203], v[88:91]
	v_mfma_f32_16x16x32_bf16 v[76:79], v[144:147], v[208:211], v[76:79]
	v_mfma_f32_16x16x32_bf16 v[72:75], v[160:163], v[208:211], v[72:75]
	v_mfma_f32_16x16x32_bf16 v[124:127], v[156:159], v[188:191], v[124:127]
	v_mfma_f32_16x16x32_bf16 v[120:123], v[164:167], v[188:191], v[120:123]
	v_mfma_f32_16x16x32_bf16 v[108:111], v[156:159], v[196:199], v[108:111]
	v_mfma_f32_16x16x32_bf16 v[104:107], v[164:167], v[196:199], v[104:107]
	v_mfma_f32_16x16x32_bf16 v[92:95], v[156:159], v[204:207], v[92:95]
	v_mfma_f32_16x16x32_bf16 v[88:91], v[164:167], v[204:207], v[88:91]
	v_mfma_f32_16x16x32_bf16 v[76:79], v[156:159], v[212:215], v[76:79]
	v_mfma_f32_16x16x32_bf16 v[72:75], v[164:167], v[212:215], v[72:75]
	v_mfma_f32_16x16x32_bf16 v[116:119], v[168:171], v[184:187], v[116:119]
	v_mfma_f32_16x16x32_bf16 v[112:115], v[176:179], v[184:187], v[112:115]
	v_mfma_f32_16x16x32_bf16 v[100:103], v[168:171], v[192:195], v[100:103]
	v_mfma_f32_16x16x32_bf16 v[96:99], v[176:179], v[192:195], v[96:99]
	v_mfma_f32_16x16x32_bf16 v[84:87], v[168:171], v[200:203], v[84:87]
	v_mfma_f32_16x16x32_bf16 v[80:83], v[176:179], v[200:203], v[80:83]
	v_mfma_f32_16x16x32_bf16 v[68:71], v[168:171], v[208:211], v[68:71]
	v_mfma_f32_16x16x32_bf16 v[64:67], v[176:179], v[208:211], v[64:67]
	v_mfma_f32_16x16x32_bf16 v[116:119], v[172:175], v[188:191], v[116:119]
	v_mfma_f32_16x16x32_bf16 v[112:115], v[180:183], v[188:191], v[112:115]
	v_mfma_f32_16x16x32_bf16 v[100:103], v[172:175], v[196:199], v[100:103]
	v_mfma_f32_16x16x32_bf16 v[96:99], v[180:183], v[196:199], v[96:99]
	v_mfma_f32_16x16x32_bf16 v[84:87], v[172:175], v[204:207], v[84:87]
	v_mfma_f32_16x16x32_bf16 v[80:83], v[180:183], v[204:207], v[80:83]
	v_mfma_f32_16x16x32_bf16 v[68:71], v[172:175], v[212:215], v[68:71]
	v_mfma_f32_16x16x32_bf16 v[64:67], v[180:183], v[212:215], v[64:67]
	s_barrier
	s_add_i32 s8, s59, s37
	v_lshl_add_u64 v[216:217], v[216:217], 0, s[14:15]
	s_mov_b32 m0, s8
	ds_read_b128 v[184:187], v151 offset:49152
	ds_read_b128 v[188:191], v151 offset:50176
	ds_read_b128 v[192:195], v151 offset:51200
	ds_read_b128 v[196:199], v151 offset:52224
	ds_read_b128 v[200:203], v151 offset:53248
	ds_read_b128 v[204:207], v151 offset:54272
	ds_read_b128 v[208:211], v151 offset:55296
	ds_read_b128 v[212:215], v151 offset:56320
	global_load_lds_dwordx4 v[216:217], off
	s_add_i32 m0, s8, 0x2000
	s_add_u32 s8, s26, 0xb0080
	v_lshl_add_u64 v[216:217], v[218:219], 0, s[14:15]
	s_addc_u32 s9, s27, 0
	s_add_i32 s26, s60, s37
	global_load_lds_dwordx4 v[216:217], off
	v_lshl_add_u64 v[216:217], s[8:9], 0, v[130:131]
	s_mov_b32 m0, s26
	s_nop 0
	global_load_lds_dwordx4 v[216:217], off
	v_lshl_add_u64 v[216:217], s[8:9], 0, v[134:135]
	s_add_i32 m0, s26, 0x2000
	s_nop 0
	global_load_lds_dwordx4 v[216:217], off
	v_lshl_add_u64 v[216:217], v[220:221], 0, s[14:15]
	s_mov_b32 m0, s46
	s_nop 0
	global_load_lds_dwordx4 v[216:217], off
	v_lshl_add_u64 v[216:217], v[222:223], 0, s[14:15]
	s_mov_b32 m0, s47
	s_nop 0
	global_load_lds_dwordx4 v[216:217], off
	s_waitcnt vmcnt(8)
	s_waitcnt lgkmcnt(0)
	s_barrier
	v_mfma_f32_16x16x32_bf16 v[60:63], v[144:147], v[184:187], v[60:63]
	v_mfma_f32_16x16x32_bf16 v[56:59], v[160:163], v[184:187], v[56:59]
	v_mfma_f32_16x16x32_bf16 v[44:47], v[144:147], v[192:195], v[44:47]
	v_mfma_f32_16x16x32_bf16 v[40:43], v[160:163], v[192:195], v[40:43]
	v_mfma_f32_16x16x32_bf16 v[28:31], v[144:147], v[200:203], v[28:31]
	v_mfma_f32_16x16x32_bf16 v[24:27], v[160:163], v[200:203], v[24:27]
	v_mfma_f32_16x16x32_bf16 v[12:15], v[144:147], v[208:211], v[12:15]
	v_mfma_f32_16x16x32_bf16 v[8:11], v[160:163], v[208:211], v[8:11]
	v_mfma_f32_16x16x32_bf16 v[60:63], v[156:159], v[188:191], v[60:63]
	v_mfma_f32_16x16x32_bf16 v[56:59], v[164:167], v[188:191], v[56:59]
	v_mfma_f32_16x16x32_bf16 v[44:47], v[156:159], v[196:199], v[44:47]
	v_mfma_f32_16x16x32_bf16 v[40:43], v[164:167], v[196:199], v[40:43]
	v_mfma_f32_16x16x32_bf16 v[28:31], v[156:159], v[204:207], v[28:31]
	v_mfma_f32_16x16x32_bf16 v[24:27], v[164:167], v[204:207], v[24:27]
	v_mfma_f32_16x16x32_bf16 v[12:15], v[156:159], v[212:215], v[12:15]
	v_mfma_f32_16x16x32_bf16 v[8:11], v[164:167], v[212:215], v[8:11]
	v_mfma_f32_16x16x32_bf16 v[52:55], v[168:171], v[184:187], v[52:55]
	v_mfma_f32_16x16x32_bf16 v[48:51], v[176:179], v[184:187], v[48:51]
	v_mfma_f32_16x16x32_bf16 v[36:39], v[168:171], v[192:195], v[36:39]
	v_mfma_f32_16x16x32_bf16 v[32:35], v[176:179], v[192:195], v[32:35]
	v_mfma_f32_16x16x32_bf16 v[20:23], v[168:171], v[200:203], v[20:23]
	v_mfma_f32_16x16x32_bf16 v[16:19], v[176:179], v[200:203], v[16:19]
	v_mfma_f32_16x16x32_bf16 v[4:7], v[168:171], v[208:211], v[4:7]
	v_mfma_f32_16x16x32_bf16 v[0:3], v[176:179], v[208:211], v[0:3]
	v_mfma_f32_16x16x32_bf16 v[52:55], v[172:175], v[188:191], v[52:55]
	v_mfma_f32_16x16x32_bf16 v[48:51], v[180:183], v[188:191], v[48:51]
	v_mfma_f32_16x16x32_bf16 v[36:39], v[172:175], v[196:199], v[36:39]
	v_mfma_f32_16x16x32_bf16 v[32:35], v[180:183], v[196:199], v[32:35]
	v_mfma_f32_16x16x32_bf16 v[20:23], v[172:175], v[204:207], v[20:23]
	v_mfma_f32_16x16x32_bf16 v[16:19], v[180:183], v[204:207], v[16:19]
	v_mfma_f32_16x16x32_bf16 v[4:7], v[172:175], v[212:215], v[4:7]
	v_mfma_f32_16x16x32_bf16 v[0:3], v[180:183], v[212:215], v[0:3]
	s_barrier
	s_add_i32 s58, s58, 2
	s_add_u32 s56, s56, 0x100
	s_addc_u32 s57, s57, 0
	s_cmp_gt_u32 s58, 41
	s_mov_b64 s[8:9], s[10:11]
	s_cbranch_scc0 .LBB0_789
	s_and_b64 vcc, exec, s[16:17]
	s_cbranch_vccz .LBB0_792
	s_barrier

.LBB0_883:
	ds_read_b128 v[144:147], v157
	ds_read_b128 v[148:151], v157 offset:1024
	ds_read_b128 v[162:165], v157 offset:2048
	ds_read_b128 v[166:169], v157 offset:3072
	ds_read_b128 v[170:173], v158
	ds_read_b128 v[174:177], v158 offset:1024
	ds_read_b128 v[178:181], v158 offset:2048
	ds_read_b128 v[182:185], v158 offset:3072
	s_add_u32 s14, s12, 0xfffc0080
	s_addc_u32 s15, s13, -1
	s_cmp_eq_u32 s41, 12
	s_cselect_b32 s35, s27, s15
	s_cselect_b32 s34, s36, s14
	s_cselect_b32 s15, s19, s39
	s_cselect_b32 s14, s37, s38
	v_lshl_add_u64 v[152:153], s[12:13], 0, v[138:139]
	s_add_i32 m0, s43, 0xc000
	ds_read_b128 v[186:189], v159
	ds_read_b128 v[190:193], v159 offset:1024
	ds_read_b128 v[194:197], v159 offset:2048
	ds_read_b128 v[198:201], v159 offset:3072
	ds_read_b128 v[202:205], v159 offset:4096
	ds_read_b128 v[206:209], v159 offset:5120
	ds_read_b128 v[210:213], v159 offset:6144
	ds_read_b128 v[214:217], v159 offset:7168
	global_load_lds_dwordx4 v[152:153], off
	v_lshl_add_u64 v[152:153], s[12:13], 0, v[136:137]
	s_add_i32 m0, s43, 0xe000
	s_nop 0
	global_load_lds_dwordx4 v[152:153], off
	s_waitcnt vmcnt(8)
	s_waitcnt lgkmcnt(0)
	s_barrier
	v_mfma_f32_16x16x32_bf16 v[124:127], v[144:147], v[186:189], v[124:127]
	v_mfma_f32_16x16x32_bf16 v[120:123], v[162:165], v[186:189], v[120:123]
	v_mfma_f32_16x16x32_bf16 v[108:111], v[144:147], v[194:197], v[108:111]
	v_mfma_f32_16x16x32_bf16 v[104:107], v[162:165], v[194:197], v[104:107]
	v_mfma_f32_16x16x32_bf16 v[92:95], v[144:147], v[202:205], v[92:95]
	v_mfma_f32_16x16x32_bf16 v[88:91], v[162:165], v[202:205], v[88:91]
	v_mfma_f32_16x16x32_bf16 v[76:79], v[144:147], v[210:213], v[76:79]
	v_mfma_f32_16x16x32_bf16 v[72:75], v[162:165], v[210:213], v[72:75]
	v_mfma_f32_16x16x32_bf16 v[124:127], v[148:151], v[190:193], v[124:127]
	v_mfma_f32_16x16x32_bf16 v[120:123], v[166:169], v[190:193], v[120:123]
	v_mfma_f32_16x16x32_bf16 v[108:111], v[148:151], v[198:201], v[108:111]
	v_mfma_f32_16x16x32_bf16 v[104:107], v[166:169], v[198:201], v[104:107]
	v_mfma_f32_16x16x32_bf16 v[92:95], v[148:151], v[206:209], v[92:95]
	v_mfma_f32_16x16x32_bf16 v[88:91], v[166:169], v[206:209], v[88:91]
	v_mfma_f32_16x16x32_bf16 v[76:79], v[148:151], v[214:217], v[76:79]
	v_mfma_f32_16x16x32_bf16 v[72:75], v[166:169], v[214:217], v[72:75]
	v_mfma_f32_16x16x32_bf16 v[116:119], v[170:173], v[186:189], v[116:119]
	v_mfma_f32_16x16x32_bf16 v[112:115], v[178:181], v[186:189], v[112:115]
	v_mfma_f32_16x16x32_bf16 v[100:103], v[170:173], v[194:197], v[100:103]
	v_mfma_f32_16x16x32_bf16 v[96:99], v[178:181], v[194:197], v[96:99]
	v_mfma_f32_16x16x32_bf16 v[84:87], v[170:173], v[202:205], v[84:87]
	v_mfma_f32_16x16x32_bf16 v[80:83], v[178:181], v[202:205], v[80:83]
	v_mfma_f32_16x16x32_bf16 v[68:71], v[170:173], v[210:213], v[68:71]
	v_mfma_f32_16x16x32_bf16 v[64:67], v[178:181], v[210:213], v[64:67]
	v_mfma_f32_16x16x32_bf16 v[116:119], v[174:177], v[190:193], v[116:119]
	v_mfma_f32_16x16x32_bf16 v[112:115], v[182:185], v[190:193], v[112:115]
	v_mfma_f32_16x16x32_bf16 v[100:103], v[174:177], v[198:201], v[100:103]
	v_mfma_f32_16x16x32_bf16 v[96:99], v[182:185], v[198:201], v[96:99]
	v_mfma_f32_16x16x32_bf16 v[84:87], v[174:177], v[206:209], v[84:87]
	v_mfma_f32_16x16x32_bf16 v[80:83], v[182:185], v[206:209], v[80:83]
	v_mfma_f32_16x16x32_bf16 v[68:71], v[174:177], v[214:217], v[68:71]
	v_mfma_f32_16x16x32_bf16 v[64:67], v[182:185], v[214:217], v[64:67]
	s_barrier
	s_add_i32 s44, s61, s49
	v_lshl_add_u64 v[152:153], s[14:15], 0, v[130:131]
	s_mov_b32 m0, s44
	ds_read_b128 v[186:189], v159 offset:16384
	ds_read_b128 v[190:193], v159 offset:17408
	ds_read_b128 v[194:197], v159 offset:18432
	ds_read_b128 v[198:201], v159 offset:19456
	ds_read_b128 v[202:205], v159 offset:20480
	ds_read_b128 v[206:209], v159 offset:21504
	ds_read_b128 v[210:213], v159 offset:22528
	ds_read_b128 v[214:217], v159 offset:23552
	global_load_lds_dwordx4 v[152:153], off
	s_add_i32 m0, s44, 0x2000
	s_add_u32 s44, s14, 0x40000
	v_lshl_add_u64 v[218:219], s[14:15], 0, v[134:135]
	s_addc_u32 s45, s15, 0
	s_add_i32 s63, s62, s49
	global_load_lds_dwordx4 v[218:219], off
	v_lshl_add_u64 v[220:221], s[44:45], 0, v[130:131]
	s_mov_b32 m0, s63
	v_lshl_add_u64 v[222:223], s[34:35], 0, v[132:133]
	global_load_lds_dwordx4 v[220:221], off
	v_lshl_add_u64 v[220:221], s[44:45], 0, v[134:135]
	s_add_i32 m0, s63, 0x2000
	s_nop 0
	global_load_lds_dwordx4 v[220:221], off
	v_lshl_add_u64 v[220:221], s[34:35], 0, v[128:129]
	s_mov_b32 m0, s43
	s_nop 0
	global_load_lds_dwordx4 v[220:221], off
	s_mov_b32 m0, s50
	s_nop 0
	global_load_lds_dwordx4 v[222:223], off
	s_waitcnt vmcnt(8)
	s_waitcnt lgkmcnt(0)
	s_barrier
	v_mfma_f32_16x16x32_bf16 v[60:63], v[144:147], v[186:189], v[60:63]
	v_mfma_f32_16x16x32_bf16 v[56:59], v[162:165], v[186:189], v[56:59]
	v_mfma_f32_16x16x32_bf16 v[44:47], v[144:147], v[194:197], v[44:47]
	v_mfma_f32_16x16x32_bf16 v[40:43], v[162:165], v[194:197], v[40:43]
	v_mfma_f32_16x16x32_bf16 v[28:31], v[144:147], v[202:205], v[28:31]
	v_mfma_f32_16x16x32_bf16 v[24:27], v[162:165], v[202:205], v[24:27]
	v_mfma_f32_16x16x32_bf16 v[12:15], v[144:147], v[210:213], v[12:15]
	v_mfma_f32_16x16x32_bf16 v[8:11], v[162:165], v[210:213], v[8:11]
	v_mfma_f32_16x16x32_bf16 v[60:63], v[148:151], v[190:193], v[60:63]
	v_mfma_f32_16x16x32_bf16 v[56:59], v[166:169], v[190:193], v[56:59]
	v_mfma_f32_16x16x32_bf16 v[44:47], v[148:151], v[198:201], v[44:47]
	v_mfma_f32_16x16x32_bf16 v[40:43], v[166:169], v[198:201], v[40:43]
	v_mfma_f32_16x16x32_bf16 v[28:31], v[148:151], v[206:209], v[28:31]
	v_mfma_f32_16x16x32_bf16 v[24:27], v[166:169], v[206:209], v[24:27]
	v_mfma_f32_16x16x32_bf16 v[12:15], v[148:151], v[214:217], v[12:15]
	v_mfma_f32_16x16x32_bf16 v[8:11], v[166:169], v[214:217], v[8:11]
	v_mfma_f32_16x16x32_bf16 v[52:55], v[170:173], v[186:189], v[52:55]
	v_mfma_f32_16x16x32_bf16 v[48:51], v[178:181], v[186:189], v[48:51]
	v_mfma_f32_16x16x32_bf16 v[36:39], v[170:173], v[194:197], v[36:39]
	v_mfma_f32_16x16x32_bf16 v[32:35], v[178:181], v[194:197], v[32:35]
	v_mfma_f32_16x16x32_bf16 v[20:23], v[170:173], v[202:205], v[20:23]
	v_mfma_f32_16x16x32_bf16 v[16:19], v[178:181], v[202:205], v[16:19]
	v_mfma_f32_16x16x32_bf16 v[4:7], v[170:173], v[210:213], v[4:7]
	v_mfma_f32_16x16x32_bf16 v[0:3], v[178:181], v[210:213], v[0:3]
	v_mfma_f32_16x16x32_bf16 v[52:55], v[174:177], v[190:193], v[52:55]
	v_mfma_f32_16x16x32_bf16 v[48:51], v[182:185], v[190:193], v[48:51]
	v_mfma_f32_16x16x32_bf16 v[36:39], v[174:177], v[198:201], v[36:39]
	v_mfma_f32_16x16x32_bf16 v[32:35], v[182:185], v[198:201], v[32:35]
	v_mfma_f32_16x16x32_bf16 v[20:23], v[174:177], v[206:209], v[20:23]
	v_mfma_f32_16x16x32_bf16 v[16:19], v[182:185], v[206:209], v[16:19]
	v_mfma_f32_16x16x32_bf16 v[4:7], v[174:177], v[214:217], v[4:7]
	v_mfma_f32_16x16x32_bf16 v[0:3], v[182:185], v[214:217], v[0:3]
	s_barrier
	s_add_i32 s44, 0, 0x18000
	s_add_i32 s45, 0, 0x1c000
	v_add_u32_e32 v166, s44, v156
	v_add_u32_e32 v182, s45, v156
	ds_read_b128 v[144:147], v166
	ds_read_b128 v[148:151], v166 offset:1024
	ds_read_b128 v[162:165], v166 offset:2048
	ds_read_b128 v[166:169], v166 offset:3072
	ds_read_b128 v[170:173], v182
	ds_read_b128 v[174:177], v182 offset:1024
	ds_read_b128 v[178:181], v182 offset:2048
	ds_read_b128 v[182:185], v182 offset:3072
	s_add_u32 s34, s34, 0x40000
	s_addc_u32 s35, s35, 0
	s_mov_b32 m0, s51
	v_lshl_add_u64 v[224:225], s[34:35], 0, v[128:129]
	ds_read_b128 v[186:189], v159 offset:32768
	ds_read_b128 v[190:193], v159 offset:33792
	ds_read_b128 v[194:197], v159 offset:34816
	ds_read_b128 v[198:201], v159 offset:35840
	ds_read_b128 v[202:205], v159 offset:36864
	ds_read_b128 v[206:209], v159 offset:37888
	ds_read_b128 v[210:213], v159 offset:38912
	ds_read_b128 v[214:217], v159 offset:39936
	global_load_lds_dwordx4 v[224:225], off
	v_lshl_add_u64 v[224:225], s[34:35], 0, v[132:133]
	s_mov_b32 m0, s52
	s_nop 0
	global_load_lds_dwordx4 v[224:225], off
	s_waitcnt vmcnt(8)
	s_waitcnt lgkmcnt(0)
	s_barrier
	v_mfma_f32_16x16x32_bf16 v[124:127], v[144:147], v[186:189], v[124:127]
	v_mfma_f32_16x16x32_bf16 v[120:123], v[162:165], v[186:189], v[120:123]
	v_mfma_f32_16x16x32_bf16 v[108:111], v[144:147], v[194:197], v[108:111]
	v_mfma_f32_16x16x32_bf16 v[104:107], v[162:165], v[194:197], v[104:107]
	v_mfma_f32_16x16x32_bf16 v[92:95], v[144:147], v[202:205], v[92:95]
	v_mfma_f32_16x16x32_bf16 v[88:91], v[162:165], v[202:205], v[88:91]
	v_mfma_f32_16x16x32_bf16 v[76:79], v[144:147], v[210:213], v[76:79]
	v_mfma_f32_16x16x32_bf16 v[72:75], v[162:165], v[210:213], v[72:75]
	v_mfma_f32_16x16x32_bf16 v[124:127], v[148:151], v[190:193], v[124:127]
	v_mfma_f32_16x16x32_bf16 v[120:123], v[166:169], v[190:193], v[120:123]
	v_mfma_f32_16x16x32_bf16 v[108:111], v[148:151], v[198:201], v[108:111]
	v_mfma_f32_16x16x32_bf16 v[104:107], v[166:169], v[198:201], v[104:107]
	v_mfma_f32_16x16x32_bf16 v[92:95], v[148:151], v[206:209], v[92:95]
	v_mfma_f32_16x16x32_bf16 v[88:91], v[166:169], v[206:209], v[88:91]
	v_mfma_f32_16x16x32_bf16 v[76:79], v[148:151], v[214:217], v[76:79]
	v_mfma_f32_16x16x32_bf16 v[72:75], v[166:169], v[214:217], v[72:75]
	v_mfma_f32_16x16x32_bf16 v[116:119], v[170:173], v[186:189], v[116:119]
	v_mfma_f32_16x16x32_bf16 v[112:115], v[178:181], v[186:189], v[112:115]
	v_mfma_f32_16x16x32_bf16 v[100:103], v[170:173], v[194:197], v[100:103]
	v_mfma_f32_16x16x32_bf16 v[96:99], v[178:181], v[194:197], v[96:99]
	v_mfma_f32_16x16x32_bf16 v[84:87], v[170:173], v[202:205], v[84:87]
	v_mfma_f32_16x16x32_bf16 v[80:83], v[178:181], v[202:205], v[80:83]
	v_mfma_f32_16x16x32_bf16 v[68:71], v[170:173], v[210:213], v[68:71]
	v_mfma_f32_16x16x32_bf16 v[64:67], v[178:181], v[210:213], v[64:67]
	v_mfma_f32_16x16x32_bf16 v[116:119], v[174:177], v[190:193], v[116:119]
	v_mfma_f32_16x16x32_bf16 v[112:115], v[182:185], v[190:193], v[112:115]
	v_mfma_f32_16x16x32_bf16 v[100:103], v[174:177], v[198:201], v[100:103]
	v_mfma_f32_16x16x32_bf16 v[96:99], v[182:185], v[198:201], v[96:99]
	v_mfma_f32_16x16x32_bf16 v[84:87], v[174:177], v[206:209], v[84:87]
	v_mfma_f32_16x16x32_bf16 v[80:83], v[182:185], v[206:209], v[80:83]
	v_mfma_f32_16x16x32_bf16 v[68:71], v[174:177], v[214:217], v[68:71]
	v_mfma_f32_16x16x32_bf16 v[64:67], v[182:185], v[214:217], v[64:67]
	s_barrier
	s_add_i32 s34, s44, s49
	v_lshl_add_u64 v[152:153], v[152:153], 0, s[10:11]
	s_mov_b32 m0, s34
	ds_read_b128 v[186:189], v159 offset:49152
	ds_read_b128 v[190:193], v159 offset:50176
	ds_read_b128 v[194:197], v159 offset:51200
	ds_read_b128 v[198:201], v159 offset:52224
	ds_read_b128 v[202:205], v159 offset:53248
	ds_read_b128 v[206:209], v159 offset:54272
	ds_read_b128 v[210:213], v159 offset:55296
	ds_read_b128 v[214:217], v159 offset:56320
	global_load_lds_dwordx4 v[152:153], off
	s_add_i32 m0, s34, 0x2000
	s_add_u32 s14, s14, 0x40080
	v_lshl_add_u64 v[152:153], v[218:219], 0, s[10:11]
	s_addc_u32 s15, s15, 0
	s_add_i32 s34, s45, s49
	global_load_lds_dwordx4 v[152:153], off
	v_lshl_add_u64 v[152:153], s[14:15], 0, v[130:131]
	s_mov_b32 m0, s34
	s_nop 0
	global_load_lds_dwordx4 v[152:153], off
	v_lshl_add_u64 v[152:153], s[14:15], 0, v[134:135]
	s_add_i32 m0, s34, 0x2000
	s_nop 0
	global_load_lds_dwordx4 v[152:153], off
	v_lshl_add_u64 v[152:153], v[220:221], 0, s[10:11]
	s_mov_b32 m0, s57
	s_nop 0
	global_load_lds_dwordx4 v[152:153], off
	v_lshl_add_u64 v[152:153], v[222:223], 0, s[10:11]
	s_mov_b32 m0, s58
	s_nop 0
	global_load_lds_dwordx4 v[152:153], off
	s_waitcnt vmcnt(8)
	s_waitcnt lgkmcnt(0)
	s_barrier
	v_mfma_f32_16x16x32_bf16 v[60:63], v[144:147], v[186:189], v[60:63]
	v_mfma_f32_16x16x32_bf16 v[56:59], v[162:165], v[186:189], v[56:59]
	v_mfma_f32_16x16x32_bf16 v[44:47], v[144:147], v[194:197], v[44:47]
	v_mfma_f32_16x16x32_bf16 v[40:43], v[162:165], v[194:197], v[40:43]
	v_mfma_f32_16x16x32_bf16 v[28:31], v[144:147], v[202:205], v[28:31]
	v_mfma_f32_16x16x32_bf16 v[24:27], v[162:165], v[202:205], v[24:27]
	v_mfma_f32_16x16x32_bf16 v[12:15], v[144:147], v[210:213], v[12:15]
	v_mfma_f32_16x16x32_bf16 v[8:11], v[162:165], v[210:213], v[8:11]
	v_mfma_f32_16x16x32_bf16 v[60:63], v[148:151], v[190:193], v[60:63]
	v_mfma_f32_16x16x32_bf16 v[56:59], v[166:169], v[190:193], v[56:59]
	v_mfma_f32_16x16x32_bf16 v[44:47], v[148:151], v[198:201], v[44:47]
	v_mfma_f32_16x16x32_bf16 v[40:43], v[166:169], v[198:201], v[40:43]
	v_mfma_f32_16x16x32_bf16 v[28:31], v[148:151], v[206:209], v[28:31]
	v_mfma_f32_16x16x32_bf16 v[24:27], v[166:169], v[206:209], v[24:27]
	v_mfma_f32_16x16x32_bf16 v[12:15], v[148:151], v[214:217], v[12:15]
	v_mfma_f32_16x16x32_bf16 v[8:11], v[166:169], v[214:217], v[8:11]
	v_mfma_f32_16x16x32_bf16 v[52:55], v[170:173], v[186:189], v[52:55]
	v_mfma_f32_16x16x32_bf16 v[48:51], v[178:181], v[186:189], v[48:51]
	v_mfma_f32_16x16x32_bf16 v[36:39], v[170:173], v[194:197], v[36:39]
	v_mfma_f32_16x16x32_bf16 v[32:35], v[178:181], v[194:197], v[32:35]
	v_mfma_f32_16x16x32_bf16 v[20:23], v[170:173], v[202:205], v[20:23]
	v_mfma_f32_16x16x32_bf16 v[16:19], v[178:181], v[202:205], v[16:19]
	v_mfma_f32_16x16x32_bf16 v[4:7], v[170:173], v[210:213], v[4:7]
	v_mfma_f32_16x16x32_bf16 v[0:3], v[178:181], v[210:213], v[0:3]
	v_mfma_f32_16x16x32_bf16 v[52:55], v[174:177], v[190:193], v[52:55]
	v_mfma_f32_16x16x32_bf16 v[48:51], v[182:185], v[190:193], v[48:51]
	v_mfma_f32_16x16x32_bf16 v[36:39], v[174:177], v[198:201], v[36:39]
	v_mfma_f32_16x16x32_bf16 v[32:35], v[182:185], v[198:201], v[32:35]
	v_mfma_f32_16x16x32_bf16 v[20:23], v[174:177], v[206:209], v[20:23]
	v_mfma_f32_16x16x32_bf16 v[16:19], v[182:185], v[206:209], v[16:19]
	v_mfma_f32_16x16x32_bf16 v[4:7], v[174:177], v[214:217], v[4:7]
	v_mfma_f32_16x16x32_bf16 v[0:3], v[182:185], v[214:217], v[0:3]
	s_barrier
	s_add_i32 s41, s41, 2
	s_add_u32 s38, s38, 0x100
	s_addc_u32 s39, s39, 0
	s_add_u32 s12, s12, 0x100
	s_addc_u32 s13, s13, 0
	s_cmp_gt_u32 s41, 13
	s_cbranch_scc0 .LBB0_883
	s_and_b64 vcc, exec, s[16:17]
	s_cbranch_vccz .LBB0_886
	s_barrier

.LBB0_967:
	ds_read_b128 v[144:147], v149
	ds_read_b128 v[156:159], v149 offset:1024
	ds_read_b128 v[160:163], v149 offset:2048
	ds_read_b128 v[164:167], v149 offset:3072
	ds_read_b128 v[168:171], v150
	ds_read_b128 v[172:175], v150 offset:1024
	ds_read_b128 v[176:179], v150 offset:2048
	ds_read_b128 v[180:183], v150 offset:3072
	s_add_u32 s34, s30, 0xfffc0080
	s_addc_u32 s35, s31, -1
	s_cmp_eq_u32 s63, 12
	s_cselect_b32 s37, s17, s35
	s_cselect_b32 s36, s29, s34
	s_cselect_b32 s35, s15, s62
	s_cselect_b32 s34, s60, s61
	v_lshl_add_u64 v[216:217], s[30:31], 0, v[138:139]
	s_add_i32 m0, s46, 0xc000
	ds_read_b128 v[184:187], v151
	ds_read_b128 v[188:191], v151 offset:1024
	ds_read_b128 v[192:195], v151 offset:2048
	ds_read_b128 v[196:199], v151 offset:3072
	ds_read_b128 v[200:203], v151 offset:4096
	ds_read_b128 v[204:207], v151 offset:5120
	ds_read_b128 v[208:211], v151 offset:6144
	ds_read_b128 v[212:215], v151 offset:7168
	global_load_lds_dwordx4 v[216:217], off
	v_lshl_add_u64 v[216:217], s[30:31], 0, v[136:137]
	s_add_i32 m0, s46, 0xe000
	s_nop 0
	global_load_lds_dwordx4 v[216:217], off
	s_waitcnt vmcnt(8)
	s_waitcnt lgkmcnt(0)
	s_barrier
	v_mfma_f32_16x16x32_bf16 v[124:127], v[144:147], v[184:187], v[124:127]
	v_mfma_f32_16x16x32_bf16 v[120:123], v[160:163], v[184:187], v[120:123]
	v_mfma_f32_16x16x32_bf16 v[108:111], v[144:147], v[192:195], v[108:111]
	v_mfma_f32_16x16x32_bf16 v[104:107], v[160:163], v[192:195], v[104:107]
	v_mfma_f32_16x16x32_bf16 v[92:95], v[144:147], v[200:203], v[92:95]
	v_mfma_f32_16x16x32_bf16 v[88:91], v[160:163], v[200:203], v[88:91]
	v_mfma_f32_16x16x32_bf16 v[76:79], v[144:147], v[208:211], v[76:79]
	v_mfma_f32_16x16x32_bf16 v[72:75], v[160:163], v[208:211], v[72:75]
	v_mfma_f32_16x16x32_bf16 v[124:127], v[156:159], v[188:191], v[124:127]
	v_mfma_f32_16x16x32_bf16 v[120:123], v[164:167], v[188:191], v[120:123]
	v_mfma_f32_16x16x32_bf16 v[108:111], v[156:159], v[196:199], v[108:111]
	v_mfma_f32_16x16x32_bf16 v[104:107], v[164:167], v[196:199], v[104:107]
	v_mfma_f32_16x16x32_bf16 v[92:95], v[156:159], v[204:207], v[92:95]
	v_mfma_f32_16x16x32_bf16 v[88:91], v[164:167], v[204:207], v[88:91]
	v_mfma_f32_16x16x32_bf16 v[76:79], v[156:159], v[212:215], v[76:79]
	v_mfma_f32_16x16x32_bf16 v[72:75], v[164:167], v[212:215], v[72:75]
	v_mfma_f32_16x16x32_bf16 v[116:119], v[168:171], v[184:187], v[116:119]
	v_mfma_f32_16x16x32_bf16 v[112:115], v[176:179], v[184:187], v[112:115]
	v_mfma_f32_16x16x32_bf16 v[100:103], v[168:171], v[192:195], v[100:103]
	v_mfma_f32_16x16x32_bf16 v[96:99], v[176:179], v[192:195], v[96:99]
	v_mfma_f32_16x16x32_bf16 v[84:87], v[168:171], v[200:203], v[84:87]
	v_mfma_f32_16x16x32_bf16 v[80:83], v[176:179], v[200:203], v[80:83]
	v_mfma_f32_16x16x32_bf16 v[68:71], v[168:171], v[208:211], v[68:71]
	v_mfma_f32_16x16x32_bf16 v[64:67], v[176:179], v[208:211], v[64:67]
	v_mfma_f32_16x16x32_bf16 v[116:119], v[172:175], v[188:191], v[116:119]
	v_mfma_f32_16x16x32_bf16 v[112:115], v[180:183], v[188:191], v[112:115]
	v_mfma_f32_16x16x32_bf16 v[100:103], v[172:175], v[196:199], v[100:103]
	v_mfma_f32_16x16x32_bf16 v[96:99], v[180:183], v[196:199], v[96:99]
	v_mfma_f32_16x16x32_bf16 v[84:87], v[172:175], v[204:207], v[84:87]
	v_mfma_f32_16x16x32_bf16 v[80:83], v[180:183], v[204:207], v[80:83]
	v_mfma_f32_16x16x32_bf16 v[68:71], v[172:175], v[212:215], v[68:71]
	v_mfma_f32_16x16x32_bf16 v[64:67], v[180:183], v[212:215], v[64:67]
	s_barrier
	s_add_i32 s64, s56, s43
	v_lshl_add_u64 v[216:217], s[34:35], 0, v[132:133]
	s_mov_b32 m0, s64
	ds_read_b128 v[184:187], v151 offset:16384
	ds_read_b128 v[188:191], v151 offset:17408
	ds_read_b128 v[192:195], v151 offset:18432
	ds_read_b128 v[196:199], v151 offset:19456
	ds_read_b128 v[200:203], v151 offset:20480
	ds_read_b128 v[204:207], v151 offset:21504
	ds_read_b128 v[208:211], v151 offset:22528
	ds_read_b128 v[212:215], v151 offset:23552
	global_load_lds_dwordx4 v[216:217], off
	s_add_i32 m0, s64, 0x2000
	s_add_u32 s64, s34, 0x40000
	v_lshl_add_u64 v[218:219], s[34:35], 0, v[128:129]
	s_addc_u32 s65, s35, 0
	s_add_i32 s66, s57, s43
	global_load_lds_dwordx4 v[218:219], off
	v_lshl_add_u64 v[220:221], s[64:65], 0, v[132:133]
	s_mov_b32 m0, s66
	v_lshl_add_u64 v[222:223], s[36:37], 0, v[130:131]
	global_load_lds_dwordx4 v[220:221], off
	v_lshl_add_u64 v[220:221], s[64:65], 0, v[128:129]
	s_add_i32 m0, s66, 0x2000
	s_nop 0
	global_load_lds_dwordx4 v[220:221], off
	v_lshl_add_u64 v[220:221], s[36:37], 0, v[134:135]
	s_mov_b32 m0, s46
	s_nop 0
	global_load_lds_dwordx4 v[220:221], off
	s_mov_b32 m0, s47
	s_nop 0
	global_load_lds_dwordx4 v[222:223], off
	s_waitcnt vmcnt(8)
	s_waitcnt lgkmcnt(0)
	s_barrier
	v_mfma_f32_16x16x32_bf16 v[60:63], v[144:147], v[184:187], v[60:63]
	v_mfma_f32_16x16x32_bf16 v[56:59], v[160:163], v[184:187], v[56:59]
	v_mfma_f32_16x16x32_bf16 v[44:47], v[144:147], v[192:195], v[44:47]
	v_mfma_f32_16x16x32_bf16 v[40:43], v[160:163], v[192:195], v[40:43]
	v_mfma_f32_16x16x32_bf16 v[28:31], v[144:147], v[200:203], v[28:31]
	v_mfma_f32_16x16x32_bf16 v[24:27], v[160:163], v[200:203], v[24:27]
	v_mfma_f32_16x16x32_bf16 v[12:15], v[144:147], v[208:211], v[12:15]
	v_mfma_f32_16x16x32_bf16 v[8:11], v[160:163], v[208:211], v[8:11]
	v_mfma_f32_16x16x32_bf16 v[60:63], v[156:159], v[188:191], v[60:63]
	v_mfma_f32_16x16x32_bf16 v[56:59], v[164:167], v[188:191], v[56:59]
	v_mfma_f32_16x16x32_bf16 v[44:47], v[156:159], v[196:199], v[44:47]
	v_mfma_f32_16x16x32_bf16 v[40:43], v[164:167], v[196:199], v[40:43]
	v_mfma_f32_16x16x32_bf16 v[28:31], v[156:159], v[204:207], v[28:31]
	v_mfma_f32_16x16x32_bf16 v[24:27], v[164:167], v[204:207], v[24:27]
	v_mfma_f32_16x16x32_bf16 v[12:15], v[156:159], v[212:215], v[12:15]
	v_mfma_f32_16x16x32_bf16 v[8:11], v[164:167], v[212:215], v[8:11]
	v_mfma_f32_16x16x32_bf16 v[52:55], v[168:171], v[184:187], v[52:55]
	v_mfma_f32_16x16x32_bf16 v[48:51], v[176:179], v[184:187], v[48:51]
	v_mfma_f32_16x16x32_bf16 v[36:39], v[168:171], v[192:195], v[36:39]
	v_mfma_f32_16x16x32_bf16 v[32:35], v[176:179], v[192:195], v[32:35]
	v_mfma_f32_16x16x32_bf16 v[20:23], v[168:171], v[200:203], v[20:23]
	v_mfma_f32_16x16x32_bf16 v[16:19], v[176:179], v[200:203], v[16:19]
	v_mfma_f32_16x16x32_bf16 v[4:7], v[168:171], v[208:211], v[4:7]
	v_mfma_f32_16x16x32_bf16 v[0:3], v[176:179], v[208:211], v[0:3]
	v_mfma_f32_16x16x32_bf16 v[52:55], v[172:175], v[188:191], v[52:55]
	v_mfma_f32_16x16x32_bf16 v[48:51], v[180:183], v[188:191], v[48:51]
	v_mfma_f32_16x16x32_bf16 v[36:39], v[172:175], v[196:199], v[36:39]
	v_mfma_f32_16x16x32_bf16 v[32:35], v[180:183], v[196:199], v[32:35]
	v_mfma_f32_16x16x32_bf16 v[20:23], v[172:175], v[204:207], v[20:23]
	v_mfma_f32_16x16x32_bf16 v[16:19], v[180:183], v[204:207], v[16:19]
	v_mfma_f32_16x16x32_bf16 v[4:7], v[172:175], v[212:215], v[4:7]
	v_mfma_f32_16x16x32_bf16 v[0:3], v[180:183], v[212:215], v[0:3]
	s_barrier
	s_add_i32 s64, 0, 0x18000
	v_add_u32_e32 v153, s64, v148
	s_add_i32 s65, 0, 0x1c000
	ds_read_b128 v[144:147], v153
	ds_read_b128 v[156:159], v153 offset:1024
	ds_read_b128 v[160:163], v153 offset:2048
	ds_read_b128 v[164:167], v153 offset:3072
	v_add_u32_e32 v153, s65, v148
	ds_read_b128 v[168:171], v153
	ds_read_b128 v[172:175], v153 offset:1024
	ds_read_b128 v[176:179], v153 offset:2048
	ds_read_b128 v[180:183], v153 offset:3072
	s_add_u32 s36, s36, 0x40000
	s_addc_u32 s37, s37, 0
	s_mov_b32 m0, s48
	v_lshl_add_u64 v[224:225], s[36:37], 0, v[134:135]
	ds_read_b128 v[184:187], v151 offset:32768
	ds_read_b128 v[188:191], v151 offset:33792
	ds_read_b128 v[192:195], v151 offset:34816
	ds_read_b128 v[196:199], v151 offset:35840
	ds_read_b128 v[200:203], v151 offset:36864
	ds_read_b128 v[204:207], v151 offset:37888
	ds_read_b128 v[208:211], v151 offset:38912
	ds_read_b128 v[212:215], v151 offset:39936
	global_load_lds_dwordx4 v[224:225], off
	v_lshl_add_u64 v[224:225], s[36:37], 0, v[130:131]
	s_mov_b32 m0, s49
	s_nop 0
	global_load_lds_dwordx4 v[224:225], off
	s_waitcnt vmcnt(8)
	s_waitcnt lgkmcnt(0)
	s_barrier
	v_mfma_f32_16x16x32_bf16 v[124:127], v[144:147], v[184:187], v[124:127]
	v_mfma_f32_16x16x32_bf16 v[120:123], v[160:163], v[184:187], v[120:123]
	v_mfma_f32_16x16x32_bf16 v[108:111], v[144:147], v[192:195], v[108:111]
	v_mfma_f32_16x16x32_bf16 v[104:107], v[160:163], v[192:195], v[104:107]
	v_mfma_f32_16x16x32_bf16 v[92:95], v[144:147], v[200:203], v[92:95]
	v_mfma_f32_16x16x32_bf16 v[88:91], v[160:163], v[200:203], v[88:91]
	v_mfma_f32_16x16x32_bf16 v[76:79], v[144:147], v[208:211], v[76:79]
	v_mfma_f32_16x16x32_bf16 v[72:75], v[160:163], v[208:211], v[72:75]
	v_mfma_f32_16x16x32_bf16 v[124:127], v[156:159], v[188:191], v[124:127]
	v_mfma_f32_16x16x32_bf16 v[120:123], v[164:167], v[188:191], v[120:123]
	v_mfma_f32_16x16x32_bf16 v[108:111], v[156:159], v[196:199], v[108:111]
	v_mfma_f32_16x16x32_bf16 v[104:107], v[164:167], v[196:199], v[104:107]
	v_mfma_f32_16x16x32_bf16 v[92:95], v[156:159], v[204:207], v[92:95]
	v_mfma_f32_16x16x32_bf16 v[88:91], v[164:167], v[204:207], v[88:91]
	v_mfma_f32_16x16x32_bf16 v[76:79], v[156:159], v[212:215], v[76:79]
	v_mfma_f32_16x16x32_bf16 v[72:75], v[164:167], v[212:215], v[72:75]
	v_mfma_f32_16x16x32_bf16 v[116:119], v[168:171], v[184:187], v[116:119]
	v_mfma_f32_16x16x32_bf16 v[112:115], v[176:179], v[184:187], v[112:115]
	v_mfma_f32_16x16x32_bf16 v[100:103], v[168:171], v[192:195], v[100:103]
	v_mfma_f32_16x16x32_bf16 v[96:99], v[176:179], v[192:195], v[96:99]
	v_mfma_f32_16x16x32_bf16 v[84:87], v[168:171], v[200:203], v[84:87]
	v_mfma_f32_16x16x32_bf16 v[80:83], v[176:179], v[200:203], v[80:83]
	v_mfma_f32_16x16x32_bf16 v[68:71], v[168:171], v[208:211], v[68:71]
	v_mfma_f32_16x16x32_bf16 v[64:67], v[176:179], v[208:211], v[64:67]
	v_mfma_f32_16x16x32_bf16 v[116:119], v[172:175], v[188:191], v[116:119]
	v_mfma_f32_16x16x32_bf16 v[112:115], v[180:183], v[188:191], v[112:115]
	v_mfma_f32_16x16x32_bf16 v[100:103], v[172:175], v[196:199], v[100:103]
	v_mfma_f32_16x16x32_bf16 v[96:99], v[180:183], v[196:199], v[96:99]
	v_mfma_f32_16x16x32_bf16 v[84:87], v[172:175], v[204:207], v[84:87]
	v_mfma_f32_16x16x32_bf16 v[80:83], v[180:183], v[204:207], v[80:83]
	v_mfma_f32_16x16x32_bf16 v[68:71], v[172:175], v[212:215], v[68:71]
	v_mfma_f32_16x16x32_bf16 v[64:67], v[180:183], v[212:215], v[64:67]
	s_barrier
	s_add_i32 s36, s64, s43
	v_lshl_add_u64 v[216:217], v[216:217], 0, s[8:9]
	s_mov_b32 m0, s36
	ds_read_b128 v[184:187], v151 offset:49152
	ds_read_b128 v[188:191], v151 offset:50176
	ds_read_b128 v[192:195], v151 offset:51200
	ds_read_b128 v[196:199], v151 offset:52224
	ds_read_b128 v[200:203], v151 offset:53248
	ds_read_b128 v[204:207], v151 offset:54272
	ds_read_b128 v[208:211], v151 offset:55296
	ds_read_b128 v[212:215], v151 offset:56320
	global_load_lds_dwordx4 v[216:217], off
	s_add_i32 m0, s36, 0x2000
	s_add_u32 s34, s34, 0x40080
	v_lshl_add_u64 v[216:217], v[218:219], 0, s[8:9]
	s_addc_u32 s35, s35, 0
	s_add_i32 s36, s65, s43
	global_load_lds_dwordx4 v[216:217], off
	v_lshl_add_u64 v[216:217], s[34:35], 0, v[132:133]
	s_mov_b32 m0, s36
	s_nop 0
	global_load_lds_dwordx4 v[216:217], off
	v_lshl_add_u64 v[216:217], s[34:35], 0, v[128:129]
	s_add_i32 m0, s36, 0x2000
	s_nop 0
	global_load_lds_dwordx4 v[216:217], off
	v_lshl_add_u64 v[216:217], v[220:221], 0, s[8:9]
	s_mov_b32 m0, s53
	s_nop 0
	global_load_lds_dwordx4 v[216:217], off
	v_lshl_add_u64 v[216:217], v[222:223], 0, s[8:9]
	s_mov_b32 m0, s54
	s_nop 0
	global_load_lds_dwordx4 v[216:217], off
	s_waitcnt vmcnt(8)
	s_waitcnt lgkmcnt(0)
	s_barrier
	v_mfma_f32_16x16x32_bf16 v[60:63], v[144:147], v[184:187], v[60:63]
	v_mfma_f32_16x16x32_bf16 v[56:59], v[160:163], v[184:187], v[56:59]
	v_mfma_f32_16x16x32_bf16 v[44:47], v[144:147], v[192:195], v[44:47]
	v_mfma_f32_16x16x32_bf16 v[40:43], v[160:163], v[192:195], v[40:43]
	v_mfma_f32_16x16x32_bf16 v[28:31], v[144:147], v[200:203], v[28:31]
	v_mfma_f32_16x16x32_bf16 v[24:27], v[160:163], v[200:203], v[24:27]
	v_mfma_f32_16x16x32_bf16 v[12:15], v[144:147], v[208:211], v[12:15]
	v_mfma_f32_16x16x32_bf16 v[8:11], v[160:163], v[208:211], v[8:11]
	v_mfma_f32_16x16x32_bf16 v[60:63], v[156:159], v[188:191], v[60:63]
	v_mfma_f32_16x16x32_bf16 v[56:59], v[164:167], v[188:191], v[56:59]
	v_mfma_f32_16x16x32_bf16 v[44:47], v[156:159], v[196:199], v[44:47]
	v_mfma_f32_16x16x32_bf16 v[40:43], v[164:167], v[196:199], v[40:43]
	v_mfma_f32_16x16x32_bf16 v[28:31], v[156:159], v[204:207], v[28:31]
	v_mfma_f32_16x16x32_bf16 v[24:27], v[164:167], v[204:207], v[24:27]
	v_mfma_f32_16x16x32_bf16 v[12:15], v[156:159], v[212:215], v[12:15]
	v_mfma_f32_16x16x32_bf16 v[8:11], v[164:167], v[212:215], v[8:11]
	v_mfma_f32_16x16x32_bf16 v[52:55], v[168:171], v[184:187], v[52:55]
	v_mfma_f32_16x16x32_bf16 v[48:51], v[176:179], v[184:187], v[48:51]
	v_mfma_f32_16x16x32_bf16 v[36:39], v[168:171], v[192:195], v[36:39]
	v_mfma_f32_16x16x32_bf16 v[32:35], v[176:179], v[192:195], v[32:35]
	v_mfma_f32_16x16x32_bf16 v[20:23], v[168:171], v[200:203], v[20:23]
	v_mfma_f32_16x16x32_bf16 v[16:19], v[176:179], v[200:203], v[16:19]
	v_mfma_f32_16x16x32_bf16 v[4:7], v[168:171], v[208:211], v[4:7]
	v_mfma_f32_16x16x32_bf16 v[0:3], v[176:179], v[208:211], v[0:3]
	v_mfma_f32_16x16x32_bf16 v[52:55], v[172:175], v[188:191], v[52:55]
	v_mfma_f32_16x16x32_bf16 v[48:51], v[180:183], v[188:191], v[48:51]
	v_mfma_f32_16x16x32_bf16 v[36:39], v[172:175], v[196:199], v[36:39]
	v_mfma_f32_16x16x32_bf16 v[32:35], v[180:183], v[196:199], v[32:35]
	v_mfma_f32_16x16x32_bf16 v[20:23], v[172:175], v[204:207], v[20:23]
	v_mfma_f32_16x16x32_bf16 v[16:19], v[180:183], v[204:207], v[16:19]
	v_mfma_f32_16x16x32_bf16 v[4:7], v[172:175], v[212:215], v[4:7]
	v_mfma_f32_16x16x32_bf16 v[0:3], v[180:183], v[212:215], v[0:3]
	s_barrier
	s_add_i32 s63, s63, 2
	s_add_u32 s61, s61, 0x100
	s_addc_u32 s62, s62, 0
	s_add_u32 s30, s30, 0x100
	s_addc_u32 s31, s31, 0
	s_cmp_gt_u32 s63, 13
	s_cbranch_scc0 .LBB0_967
	s_and_b64 vcc, exec, s[10:11]
	s_cbranch_vccz .LBB0_970
	s_barrier

.LBB0_1137:
	s_ashr_i32 s35, s34, 31
	s_lshl_b64 s[12:13], s[34:35], 17
	s_add_u32 s36, s44, s12
	s_addc_u32 s37, s45, s13
	s_and_b64 s[12:13], s[4:5], exec
	s_cselect_b32 s13, s37, s11
	s_cselect_b32 s12, s36, s10
	s_ashr_i32 s31, s30, 31
	s_lshl_b64 s[38:39], s[30:31], 16
	s_add_u32 s38, s46, s38
	s_addc_u32 s39, s47, s39
	s_add_u32 s40, s10, 0x10080
	ds_read_b128 v[0:3], v153
	ds_read_b128 v[4:7], v153 offset:1024
	ds_read_b128 v[8:11], v153 offset:2048
	ds_read_b128 v[12:15], v153 offset:3072
	ds_read_b128 v[16:19], v156
	ds_read_b128 v[20:23], v156 offset:1024
	ds_read_b128 v[24:27], v156 offset:2048
	ds_read_b128 v[28:31], v156 offset:3072
	s_addc_u32 s41, s11, 0
	s_add_u32 s10, s12, 0x10000
	s_addc_u32 s11, s13, 0
	s_and_b64 s[42:43], s[4:5], exec
	s_cselect_b32 s8, s38, s8
	s_cselect_b32 s9, s39, s9
	s_add_u32 s42, s8, 0x8000
	s_addc_u32 s43, s9, 0
	v_lshl_add_u64 v[64:65], s[40:41], 0, v[136:137]
	s_add_i32 m0, s49, 0xc000
	ds_read_b128 v[32:35], v157
	ds_read_b128 v[36:39], v157 offset:1024
	ds_read_b128 v[40:43], v157 offset:2048
	ds_read_b128 v[44:47], v157 offset:3072
	ds_read_b128 v[48:51], v157 offset:4096
	ds_read_b128 v[52:55], v157 offset:5120
	ds_read_b128 v[56:59], v157 offset:6144
	ds_read_b128 v[60:63], v157 offset:7168
	global_load_lds_dwordx4 v[64:65], off
	v_lshl_add_u64 v[64:65], s[40:41], 0, v[140:141]
	s_add_i32 m0, s49, 0xe000
	s_nop 0
	global_load_lds_dwordx4 v[64:65], off
	s_waitcnt vmcnt(8)
	s_waitcnt lgkmcnt(0)
	s_barrier
	v_mfma_f32_16x16x32_bf16 v[64:67], v[0:3], v[32:35], 0
	v_mfma_f32_16x16x32_bf16 v[68:71], v[8:11], v[32:35], 0
	v_mfma_f32_16x16x32_bf16 v[72:75], v[0:3], v[40:43], 0
	v_mfma_f32_16x16x32_bf16 v[76:79], v[8:11], v[40:43], 0
	v_mfma_f32_16x16x32_bf16 v[80:83], v[0:3], v[48:51], 0
	v_mfma_f32_16x16x32_bf16 v[84:87], v[8:11], v[48:51], 0
	v_mfma_f32_16x16x32_bf16 v[88:91], v[0:3], v[56:59], 0
	v_mfma_f32_16x16x32_bf16 v[92:95], v[8:11], v[56:59], 0
	v_mfma_f32_16x16x32_bf16 v[64:67], v[4:7], v[36:39], v[64:67]
	v_mfma_f32_16x16x32_bf16 v[68:71], v[12:15], v[36:39], v[68:71]
	v_mfma_f32_16x16x32_bf16 v[72:75], v[4:7], v[44:47], v[72:75]
	v_mfma_f32_16x16x32_bf16 v[76:79], v[12:15], v[44:47], v[76:79]
	v_mfma_f32_16x16x32_bf16 v[80:83], v[4:7], v[52:55], v[80:83]
	v_mfma_f32_16x16x32_bf16 v[84:87], v[12:15], v[52:55], v[84:87]
	v_mfma_f32_16x16x32_bf16 v[88:91], v[4:7], v[60:63], v[88:91]
	v_mfma_f32_16x16x32_bf16 v[92:95], v[12:15], v[60:63], v[92:95]
	v_mfma_f32_16x16x32_bf16 v[96:99], v[16:19], v[32:35], 0
	v_mfma_f32_16x16x32_bf16 v[32:35], v[24:27], v[32:35], 0
	v_mfma_f32_16x16x32_bf16 v[120:123], v[20:23], v[36:39], v[96:99]
	v_mfma_f32_16x16x32_bf16 v[32:35], v[28:31], v[36:39], v[32:35]
	v_mfma_f32_16x16x32_bf16 v[36:39], v[16:19], v[40:43], 0
	v_mfma_f32_16x16x32_bf16 v[40:43], v[24:27], v[40:43], 0
	v_mfma_f32_16x16x32_bf16 v[36:39], v[20:23], v[44:47], v[36:39]
	v_mfma_f32_16x16x32_bf16 v[40:43], v[28:31], v[44:47], v[40:43]
	v_mfma_f32_16x16x32_bf16 v[44:47], v[16:19], v[48:51], 0
	v_mfma_f32_16x16x32_bf16 v[48:51], v[24:27], v[48:51], 0
	v_mfma_f32_16x16x32_bf16 v[124:127], v[28:31], v[52:55], v[48:51]
	v_mfma_f32_16x16x32_bf16 v[48:51], v[16:19], v[56:59], 0
	v_mfma_f32_16x16x32_bf16 v[44:47], v[20:23], v[52:55], v[44:47]
	v_mfma_f32_16x16x32_bf16 v[148:151], v[20:23], v[60:63], v[48:51]
	v_mfma_f32_16x16x32_bf16 v[48:51], v[24:27], v[56:59], 0
	v_mfma_f32_16x16x32_bf16 v[160:163], v[28:31], v[60:63], v[48:51]
	s_barrier
	s_add_i32 s31, s58, s48
	v_lshl_add_u64 v[252:253], s[8:9], 0, v[138:139]
	s_mov_b32 m0, s31
	s_nop 1
	ds_read_b128 v[48:51], v157 offset:16384
	ds_read_b128 v[52:55], v157 offset:17408
	ds_read_b128 v[56:59], v157 offset:18432
	ds_read_b128 v[60:63], v157 offset:19456
	ds_read_b128 v[96:99], v157 offset:20480
	ds_read_b128 v[100:103], v157 offset:21504
	ds_read_b128 v[104:107], v157 offset:22528
	ds_read_b128 v[108:111], v157 offset:23552
	global_load_lds_dwordx4 v[252:253], off
	v_lshl_add_u64 v[254:255], s[8:9], 0, v[142:143]
	s_add_i32 m0, s31, 0x2000
	s_add_i32 s31, s59, s48
	global_load_lds_dwordx4 v[254:255], off
	v_lshl_add_u64 v[112:113], s[42:43], 0, v[138:139]
	s_mov_b32 m0, s31
	v_lshl_add_u64 v[144:145], s[12:13], 0, v[136:137]
	global_load_lds_dwordx4 v[112:113], off
	v_lshl_add_u64 v[112:113], s[42:43], 0, v[142:143]
	s_add_i32 m0, s31, 0x2000
	v_lshl_add_u64 v[146:147], s[12:13], 0, v[140:141]
	global_load_lds_dwordx4 v[112:113], off
	s_mov_b32 m0, s49
	s_nop 0
	global_load_lds_dwordx4 v[144:145], off
	s_mov_b32 m0, s50
	s_nop 0
	global_load_lds_dwordx4 v[146:147], off
	s_waitcnt vmcnt(8)
	s_waitcnt lgkmcnt(0)
	s_barrier
	v_mfma_f32_16x16x32_bf16 v[112:115], v[0:3], v[48:51], 0
	v_mfma_f32_16x16x32_bf16 v[164:167], v[4:7], v[52:55], v[112:115]
	v_mfma_f32_16x16x32_bf16 v[112:115], v[8:11], v[48:51], 0
	v_mfma_f32_16x16x32_bf16 v[168:171], v[12:15], v[52:55], v[112:115]
	v_mfma_f32_16x16x32_bf16 v[112:115], v[0:3], v[56:59], 0
	v_mfma_f32_16x16x32_bf16 v[172:175], v[4:7], v[60:63], v[112:115]
	v_mfma_f32_16x16x32_bf16 v[112:115], v[8:11], v[56:59], 0
	v_mfma_f32_16x16x32_bf16 v[176:179], v[12:15], v[60:63], v[112:115]
	v_mfma_f32_16x16x32_bf16 v[112:115], v[0:3], v[96:99], 0
	v_mfma_f32_16x16x32_bf16 v[0:3], v[0:3], v[104:107], 0
	v_mfma_f32_16x16x32_bf16 v[180:183], v[4:7], v[100:103], v[112:115]
	v_mfma_f32_16x16x32_bf16 v[0:3], v[4:7], v[108:111], v[0:3]
	v_mfma_f32_16x16x32_bf16 v[4:7], v[8:11], v[104:107], 0
	v_mfma_f32_16x16x32_bf16 v[112:115], v[8:11], v[96:99], 0
	v_mfma_f32_16x16x32_bf16 v[4:7], v[12:15], v[108:111], v[4:7]
	v_mfma_f32_16x16x32_bf16 v[184:187], v[12:15], v[100:103], v[112:115]
	v_mfma_f32_16x16x32_bf16 v[8:11], v[16:19], v[48:51], 0
	v_mfma_f32_16x16x32_bf16 v[12:15], v[24:27], v[48:51], 0
	v_mfma_f32_16x16x32_bf16 v[48:51], v[16:19], v[56:59], 0
	v_mfma_f32_16x16x32_bf16 v[188:191], v[20:23], v[60:63], v[48:51]
	v_mfma_f32_16x16x32_bf16 v[48:51], v[24:27], v[56:59], 0
	v_mfma_f32_16x16x32_bf16 v[192:195], v[28:31], v[60:63], v[48:51]
	v_mfma_f32_16x16x32_bf16 v[48:51], v[16:19], v[96:99], 0
	v_mfma_f32_16x16x32_bf16 v[16:19], v[16:19], v[104:107], 0
	v_mfma_f32_16x16x32_bf16 v[8:11], v[20:23], v[52:55], v[8:11]
	v_mfma_f32_16x16x32_bf16 v[12:15], v[28:31], v[52:55], v[12:15]
	v_mfma_f32_16x16x32_bf16 v[196:199], v[20:23], v[100:103], v[48:51]
	v_mfma_f32_16x16x32_bf16 v[48:51], v[24:27], v[96:99], 0
	v_mfma_f32_16x16x32_bf16 v[204:207], v[20:23], v[108:111], v[16:19]
	v_mfma_f32_16x16x32_bf16 v[16:19], v[24:27], v[104:107], 0
	v_mfma_f32_16x16x32_bf16 v[200:203], v[28:31], v[100:103], v[48:51]
	v_mfma_f32_16x16x32_bf16 v[208:211], v[28:31], v[108:111], v[16:19]
	s_barrier
	s_add_i32 s12, 0, 0x18000
	s_add_i32 s13, 0, 0x1c000
	v_add_u32_e32 v28, s12, v152
	v_add_u32_e32 v48, s13, v152
	ds_read_b128 v[16:19], v28
	ds_read_b128 v[20:23], v28 offset:1024
	ds_read_b128 v[24:27], v28 offset:2048
	ds_read_b128 v[28:31], v28 offset:3072
	ds_read_b128 v[212:215], v48
	ds_read_b128 v[216:219], v48 offset:1024
	ds_read_b128 v[220:223], v48 offset:2048
	ds_read_b128 v[224:227], v48 offset:3072
	s_mov_b32 m0, s51
	v_lshl_add_u64 v[56:57], s[10:11], 0, v[136:137]
	ds_read_b128 v[48:51], v157 offset:32768
	ds_read_b128 v[52:55], v157 offset:33792
	ds_read_b128 v[228:231], v157 offset:34816
	ds_read_b128 v[232:235], v157 offset:35840
	ds_read_b128 v[236:239], v157 offset:36864
	ds_read_b128 v[240:243], v157 offset:37888
	ds_read_b128 v[244:247], v157 offset:38912
	ds_read_b128 v[248:251], v157 offset:39936
	global_load_lds_dwordx4 v[56:57], off
	v_lshl_add_u64 v[56:57], s[10:11], 0, v[140:141]
	s_mov_b32 m0, s52
	s_nop 0
	global_load_lds_dwordx4 v[56:57], off
	s_waitcnt vmcnt(8)
	s_waitcnt lgkmcnt(0)
	s_barrier
	v_mfma_f32_16x16x32_bf16 v[56:59], v[16:19], v[48:51], v[64:67]
	v_mfma_f32_16x16x32_bf16 v[132:135], v[20:23], v[52:55], v[56:59]
	v_mfma_f32_16x16x32_bf16 v[56:59], v[24:27], v[48:51], v[68:71]
	v_mfma_f32_16x16x32_bf16 v[128:131], v[28:31], v[52:55], v[56:59]
	v_mfma_f32_16x16x32_bf16 v[56:59], v[16:19], v[228:231], v[72:75]
	v_mfma_f32_16x16x32_bf16 v[116:119], v[20:23], v[232:235], v[56:59]
	v_mfma_f32_16x16x32_bf16 v[56:59], v[24:27], v[228:231], v[76:79]
	v_mfma_f32_16x16x32_bf16 v[112:115], v[28:31], v[232:235], v[56:59]
	v_mfma_f32_16x16x32_bf16 v[56:59], v[16:19], v[236:239], v[80:83]
	v_mfma_f32_16x16x32_bf16 v[108:111], v[20:23], v[240:243], v[56:59]
	v_mfma_f32_16x16x32_bf16 v[56:59], v[24:27], v[236:239], v[84:87]
	v_mfma_f32_16x16x32_bf16 v[104:107], v[28:31], v[240:243], v[56:59]
	v_mfma_f32_16x16x32_bf16 v[56:59], v[16:19], v[244:247], v[88:91]
	v_mfma_f32_16x16x32_bf16 v[100:103], v[20:23], v[248:251], v[56:59]
	v_mfma_f32_16x16x32_bf16 v[56:59], v[24:27], v[244:247], v[92:95]
	v_mfma_f32_16x16x32_bf16 v[96:99], v[28:31], v[248:251], v[56:59]
	v_mfma_f32_16x16x32_bf16 v[56:59], v[212:215], v[48:51], v[120:123]
	v_mfma_f32_16x16x32_bf16 v[32:35], v[220:223], v[48:51], v[32:35]
	v_mfma_f32_16x16x32_bf16 v[60:63], v[216:219], v[52:55], v[56:59]
	v_mfma_f32_16x16x32_bf16 v[56:59], v[224:227], v[52:55], v[32:35]
	v_mfma_f32_16x16x32_bf16 v[32:35], v[212:215], v[228:231], v[36:39]
	v_mfma_f32_16x16x32_bf16 v[52:55], v[216:219], v[232:235], v[32:35]
	v_mfma_f32_16x16x32_bf16 v[32:35], v[220:223], v[228:231], v[40:43]
	v_mfma_f32_16x16x32_bf16 v[48:51], v[224:227], v[232:235], v[32:35]
	v_mfma_f32_16x16x32_bf16 v[32:35], v[212:215], v[236:239], v[44:47]
	v_mfma_f32_16x16x32_bf16 v[44:47], v[216:219], v[240:243], v[32:35]
	v_mfma_f32_16x16x32_bf16 v[32:35], v[220:223], v[236:239], v[124:127]
	v_mfma_f32_16x16x32_bf16 v[40:43], v[224:227], v[240:243], v[32:35]
	v_mfma_f32_16x16x32_bf16 v[32:35], v[212:215], v[244:247], v[148:151]
	v_mfma_f32_16x16x32_bf16 v[36:39], v[216:219], v[248:251], v[32:35]
	v_mfma_f32_16x16x32_bf16 v[32:35], v[220:223], v[244:247], v[160:163]
	v_mfma_f32_16x16x32_bf16 v[32:35], v[224:227], v[248:251], v[32:35]
	s_barrier
	s_add_i32 s10, s12, s48
	v_lshl_add_u64 v[64:65], v[252:253], 0, s[16:17]
	s_mov_b32 m0, s10
	ds_read_b128 v[120:123], v157 offset:49152
	ds_read_b128 v[124:127], v157 offset:50176
	ds_read_b128 v[148:151], v157 offset:51200
	ds_read_b128 v[160:163], v157 offset:52224
	ds_read_b128 v[228:231], v157 offset:53248
	ds_read_b128 v[232:235], v157 offset:54272
	ds_read_b128 v[236:239], v157 offset:55296
	ds_read_b128 v[240:243], v157 offset:56320
	global_load_lds_dwordx4 v[64:65], off
	s_add_i32 m0, s10, 0x2000
	s_add_u32 s8, s8, 0x8080
	v_lshl_add_u64 v[64:65], v[254:255], 0, s[16:17]
	s_addc_u32 s9, s9, 0
	s_add_i32 s10, s13, s48
	global_load_lds_dwordx4 v[64:65], off
	v_lshl_add_u64 v[64:65], s[8:9], 0, v[138:139]
	s_mov_b32 m0, s10
	s_nop 0
	global_load_lds_dwordx4 v[64:65], off
	v_lshl_add_u64 v[64:65], s[8:9], 0, v[142:143]
	s_add_i32 m0, s10, 0x2000
	s_nop 0
	global_load_lds_dwordx4 v[64:65], off
	v_lshl_add_u64 v[64:65], v[144:145], 0, s[16:17]
	s_mov_b32 m0, s55
	s_nop 0
	global_load_lds_dwordx4 v[64:65], off
	v_lshl_add_u64 v[64:65], v[146:147], 0, s[16:17]
	s_mov_b32 m0, s56
	s_nop 0
	global_load_lds_dwordx4 v[64:65], off
	s_waitcnt vmcnt(8)
	s_waitcnt lgkmcnt(0)
	s_barrier
	v_mfma_f32_16x16x32_bf16 v[64:67], v[16:19], v[120:123], v[164:167]
	v_mfma_f32_16x16x32_bf16 v[92:95], v[20:23], v[124:127], v[64:67]
	v_mfma_f32_16x16x32_bf16 v[64:67], v[24:27], v[120:123], v[168:171]
	v_mfma_f32_16x16x32_bf16 v[88:91], v[28:31], v[124:127], v[64:67]
	v_mfma_f32_16x16x32_bf16 v[64:67], v[16:19], v[148:151], v[172:175]
	v_mfma_f32_16x16x32_bf16 v[84:87], v[20:23], v[160:163], v[64:67]
	v_mfma_f32_16x16x32_bf16 v[64:67], v[24:27], v[148:151], v[176:179]
	v_mfma_f32_16x16x32_bf16 v[80:83], v[28:31], v[160:163], v[64:67]
	v_mfma_f32_16x16x32_bf16 v[64:67], v[16:19], v[228:231], v[180:183]
	v_mfma_f32_16x16x32_bf16 v[0:3], v[16:19], v[236:239], v[0:3]
	v_mfma_f32_16x16x32_bf16 v[76:79], v[20:23], v[232:235], v[64:67]
	v_mfma_f32_16x16x32_bf16 v[64:67], v[24:27], v[228:231], v[184:187]
	v_mfma_f32_16x16x32_bf16 v[68:71], v[20:23], v[240:243], v[0:3]
	v_mfma_f32_16x16x32_bf16 v[0:3], v[24:27], v[236:239], v[4:7]
	v_mfma_f32_16x16x32_bf16 v[72:75], v[28:31], v[232:235], v[64:67]
	v_mfma_f32_16x16x32_bf16 v[64:67], v[28:31], v[240:243], v[0:3]
	v_mfma_f32_16x16x32_bf16 v[0:3], v[212:215], v[120:123], v[8:11]
	v_mfma_f32_16x16x32_bf16 v[28:31], v[216:219], v[124:127], v[0:3]
	v_mfma_f32_16x16x32_bf16 v[0:3], v[220:223], v[120:123], v[12:15]
	v_mfma_f32_16x16x32_bf16 v[24:27], v[224:227], v[124:127], v[0:3]
	v_mfma_f32_16x16x32_bf16 v[0:3], v[212:215], v[148:151], v[188:191]
	v_mfma_f32_16x16x32_bf16 v[20:23], v[216:219], v[160:163], v[0:3]
	v_mfma_f32_16x16x32_bf16 v[0:3], v[220:223], v[148:151], v[192:195]
	v_mfma_f32_16x16x32_bf16 v[16:19], v[224:227], v[160:163], v[0:3]
	v_mfma_f32_16x16x32_bf16 v[0:3], v[212:215], v[228:231], v[196:199]
	v_mfma_f32_16x16x32_bf16 v[12:15], v[216:219], v[232:235], v[0:3]
	v_mfma_f32_16x16x32_bf16 v[0:3], v[220:223], v[228:231], v[200:203]
	v_mfma_f32_16x16x32_bf16 v[8:11], v[224:227], v[232:235], v[0:3]
	v_mfma_f32_16x16x32_bf16 v[0:3], v[212:215], v[236:239], v[204:207]
	v_mfma_f32_16x16x32_bf16 v[4:7], v[216:219], v[240:243], v[0:3]
	v_mfma_f32_16x16x32_bf16 v[0:3], v[220:223], v[236:239], v[208:211]
	v_mfma_f32_16x16x32_bf16 v[0:3], v[224:227], v[240:243], v[0:3]
	s_barrier
	s_andn2_b64 vcc, exec, s[18:19]
	s_cbranch_vccnz .LBB0_1139
	s_barrier

.LBB0_1169:
	s_ashr_i32 s19, s18, 31
	s_lshl_b64 s[26:27], s[18:19], 17
	s_add_u32 s26, s40, s26
	s_addc_u32 s27, s41, s27
	s_and_b64 s[28:29], s[4:5], exec
	s_cselect_b32 s39, s27, s37
	s_cselect_b32 s38, s26, s36
	s_ashr_i32 s17, s16, 31
	s_lshl_b64 s[28:29], s[16:17], 16
	s_add_u32 s28, s42, s28
	s_addc_u32 s29, s43, s29
	s_add_u32 s60, s36, 0x10080
	ds_read_b128 v[0:3], v141
	ds_read_b128 v[4:7], v141 offset:1024
	ds_read_b128 v[8:11], v141 offset:2048
	ds_read_b128 v[12:15], v141 offset:3072
	ds_read_b128 v[16:19], v142
	ds_read_b128 v[20:23], v142 offset:1024
	ds_read_b128 v[24:27], v142 offset:2048
	ds_read_b128 v[28:31], v142 offset:3072
	s_addc_u32 s61, s37, 0
	s_add_u32 s36, s38, 0x10000
	s_addc_u32 s37, s39, 0
	s_and_b64 s[62:63], s[4:5], exec
	s_cselect_b32 s34, s28, s34
	s_cselect_b32 s35, s29, s35
	s_add_u32 s62, s34, 0x8000
	s_addc_u32 s63, s35, 0
	s_mov_b32 m0, s55
	v_lshl_add_u64 v[64:65], s[60:61], 0, v[128:129]
	ds_read_b128 v[32:35], v143
	ds_read_b128 v[36:39], v143 offset:1024
	ds_read_b128 v[40:43], v143 offset:2048
	ds_read_b128 v[44:47], v143 offset:3072
	ds_read_b128 v[48:51], v143 offset:4096
	ds_read_b128 v[52:55], v143 offset:5120
	ds_read_b128 v[56:59], v143 offset:6144
	ds_read_b128 v[60:63], v143 offset:7168
	global_load_lds_dwordx4 v[64:65], off
	v_lshl_add_u64 v[64:65], s[60:61], 0, v[132:133]
	s_mov_b32 m0, s56
	s_nop 0
	global_load_lds_dwordx4 v[64:65], off
	s_waitcnt vmcnt(8)
	s_waitcnt lgkmcnt(0)
	s_barrier
	v_mfma_f32_16x16x32_bf16 v[88:91], v[0:3], v[56:59], 0
	v_mfma_f32_16x16x32_bf16 v[64:67], v[0:3], v[32:35], 0
	v_mfma_f32_16x16x32_bf16 v[68:71], v[8:11], v[32:35], 0
	v_mfma_f32_16x16x32_bf16 v[72:75], v[0:3], v[40:43], 0
	v_mfma_f32_16x16x32_bf16 v[76:79], v[8:11], v[40:43], 0
	v_mfma_f32_16x16x32_bf16 v[80:83], v[0:3], v[48:51], 0
	v_mfma_f32_16x16x32_bf16 v[84:87], v[8:11], v[48:51], 0
	v_mfma_f32_16x16x32_bf16 v[92:95], v[4:7], v[60:63], v[88:91]
	v_mfma_f32_16x16x32_bf16 v[88:91], v[8:11], v[56:59], 0
	v_mfma_f32_16x16x32_bf16 v[64:67], v[4:7], v[36:39], v[64:67]
	v_mfma_f32_16x16x32_bf16 v[68:71], v[12:15], v[36:39], v[68:71]
	v_mfma_f32_16x16x32_bf16 v[72:75], v[4:7], v[44:47], v[72:75]
	v_mfma_f32_16x16x32_bf16 v[76:79], v[12:15], v[44:47], v[76:79]
	v_mfma_f32_16x16x32_bf16 v[80:83], v[4:7], v[52:55], v[80:83]
	v_mfma_f32_16x16x32_bf16 v[84:87], v[12:15], v[52:55], v[84:87]
	v_mfma_f32_16x16x32_bf16 v[100:103], v[12:15], v[60:63], v[88:91]
	v_mfma_f32_16x16x32_bf16 v[88:91], v[16:19], v[32:35], 0
	v_mfma_f32_16x16x32_bf16 v[32:35], v[24:27], v[32:35], 0
	v_mfma_f32_16x16x32_bf16 v[108:111], v[20:23], v[36:39], v[88:91]
	v_mfma_f32_16x16x32_bf16 v[32:35], v[28:31], v[36:39], v[32:35]
	v_mfma_f32_16x16x32_bf16 v[36:39], v[16:19], v[40:43], 0
	v_mfma_f32_16x16x32_bf16 v[40:43], v[24:27], v[40:43], 0
	v_mfma_f32_16x16x32_bf16 v[36:39], v[20:23], v[44:47], v[36:39]
	v_mfma_f32_16x16x32_bf16 v[40:43], v[28:31], v[44:47], v[40:43]
	v_mfma_f32_16x16x32_bf16 v[44:47], v[16:19], v[48:51], 0
	v_mfma_f32_16x16x32_bf16 v[48:51], v[24:27], v[48:51], 0
	v_mfma_f32_16x16x32_bf16 v[116:119], v[28:31], v[52:55], v[48:51]
	v_mfma_f32_16x16x32_bf16 v[48:51], v[16:19], v[56:59], 0
	v_mfma_f32_16x16x32_bf16 v[124:127], v[20:23], v[60:63], v[48:51]
	v_mfma_f32_16x16x32_bf16 v[48:51], v[24:27], v[56:59], 0
	v_mfma_f32_16x16x32_bf16 v[44:47], v[20:23], v[52:55], v[44:47]
	v_mfma_f32_16x16x32_bf16 v[56:59], v[28:31], v[60:63], v[48:51]
	s_barrier
	s_mov_b32 m0, s57
	v_lshl_add_u64 v[152:153], s[34:35], 0, v[130:131]
	s_nop 1
	ds_read_b128 v[48:51], v143 offset:16384
	ds_read_b128 v[52:55], v143 offset:17408
	ds_read_b128 v[60:63], v143 offset:18432
	ds_read_b128 v[88:91], v143 offset:19456
	ds_read_b128 v[96:99], v143 offset:20480
	ds_read_b128 v[104:107], v143 offset:21504
	ds_read_b128 v[112:115], v143 offset:22528
	ds_read_b128 v[120:123], v143 offset:23552
	global_load_lds_dwordx4 v[152:153], off
	v_lshl_add_u64 v[248:249], s[34:35], 0, v[134:135]
	s_add_i32 m0, s57, 0x2000
	s_add_i32 s17, s53, s44
	global_load_lds_dwordx4 v[248:249], off
	v_lshl_add_u64 v[144:145], s[62:63], 0, v[130:131]
	s_mov_b32 m0, s17
	v_lshl_add_u64 v[250:251], s[38:39], 0, v[128:129]
	global_load_lds_dwordx4 v[144:145], off
	v_lshl_add_u64 v[144:145], s[62:63], 0, v[134:135]
	s_add_i32 m0, s17, 0x2000
	v_lshl_add_u64 v[252:253], s[38:39], 0, v[132:133]
	global_load_lds_dwordx4 v[144:145], off
	s_mov_b32 m0, s31
	s_nop 0
	global_load_lds_dwordx4 v[250:251], off
	s_mov_b32 m0, s45
	s_nop 0
	global_load_lds_dwordx4 v[252:253], off
	s_waitcnt vmcnt(8)
	s_waitcnt lgkmcnt(0)
	s_barrier
	v_mfma_f32_16x16x32_bf16 v[144:147], v[0:3], v[48:51], 0
	v_mfma_f32_16x16x32_bf16 v[156:159], v[0:3], v[60:63], 0
	v_mfma_f32_16x16x32_bf16 v[164:167], v[0:3], v[96:99], 0
	v_mfma_f32_16x16x32_bf16 v[0:3], v[0:3], v[112:115], 0
	v_mfma_f32_16x16x32_bf16 v[172:175], v[4:7], v[120:123], v[0:3]
	v_mfma_f32_16x16x32_bf16 v[0:3], v[8:11], v[112:115], 0
	v_mfma_f32_16x16x32_bf16 v[148:151], v[8:11], v[48:51], 0
	v_mfma_f32_16x16x32_bf16 v[160:163], v[8:11], v[60:63], 0
	v_mfma_f32_16x16x32_bf16 v[168:171], v[8:11], v[96:99], 0
	v_mfma_f32_16x16x32_bf16 v[8:11], v[12:15], v[120:123], v[0:3]
	v_mfma_f32_16x16x32_bf16 v[144:147], v[4:7], v[52:55], v[144:147]
	v_mfma_f32_16x16x32_bf16 v[148:151], v[12:15], v[52:55], v[148:151]
	v_mfma_f32_16x16x32_bf16 v[156:159], v[4:7], v[88:91], v[156:159]
	v_mfma_f32_16x16x32_bf16 v[160:163], v[12:15], v[88:91], v[160:163]
	v_mfma_f32_16x16x32_bf16 v[164:167], v[4:7], v[104:107], v[164:167]
	v_mfma_f32_16x16x32_bf16 v[168:171], v[12:15], v[104:107], v[168:171]
	v_mfma_f32_16x16x32_bf16 v[0:3], v[16:19], v[48:51], 0
	v_mfma_f32_16x16x32_bf16 v[12:15], v[20:23], v[52:55], v[0:3]
	v_mfma_f32_16x16x32_bf16 v[0:3], v[24:27], v[48:51], 0
	v_mfma_f32_16x16x32_bf16 v[176:179], v[28:31], v[52:55], v[0:3]
	v_mfma_f32_16x16x32_bf16 v[0:3], v[16:19], v[60:63], 0
	v_mfma_f32_16x16x32_bf16 v[180:183], v[20:23], v[88:91], v[0:3]
	v_mfma_f32_16x16x32_bf16 v[0:3], v[24:27], v[60:63], 0
	v_mfma_f32_16x16x32_bf16 v[184:187], v[28:31], v[88:91], v[0:3]
	v_mfma_f32_16x16x32_bf16 v[0:3], v[16:19], v[96:99], 0
	v_mfma_f32_16x16x32_bf16 v[188:191], v[20:23], v[104:107], v[0:3]
	v_mfma_f32_16x16x32_bf16 v[0:3], v[24:27], v[96:99], 0
	v_mfma_f32_16x16x32_bf16 v[192:195], v[28:31], v[104:107], v[0:3]
	v_mfma_f32_16x16x32_bf16 v[0:3], v[16:19], v[112:115], 0
	v_mfma_f32_16x16x32_bf16 v[196:199], v[20:23], v[120:123], v[0:3]
	v_mfma_f32_16x16x32_bf16 v[0:3], v[24:27], v[112:115], 0
	v_mfma_f32_16x16x32_bf16 v[200:203], v[28:31], v[120:123], v[0:3]
	s_barrier
	s_add_i32 s17, 0, 0x18000
	s_nop 3
	v_add_u32_e32 v0, s17, v140
	s_add_i32 s19, 0, 0x1c000
	ds_read_b128 v[24:27], v0
	ds_read_b128 v[28:31], v0 offset:1024
	ds_read_b128 v[60:63], v0 offset:2048
	ds_read_b128 v[204:207], v0 offset:3072
	v_add_u32_e32 v0, s19, v140
	ds_read_b128 v[208:211], v0
	ds_read_b128 v[212:215], v0 offset:1024
	ds_read_b128 v[216:219], v0 offset:2048
	ds_read_b128 v[220:223], v0 offset:3072
	s_mov_b32 m0, s46
	v_lshl_add_u64 v[48:49], s[36:37], 0, v[128:129]
	ds_read_b128 v[0:3], v143 offset:32768
	ds_read_b128 v[4:7], v143 offset:33792
	ds_read_b128 v[16:19], v143 offset:34816
	ds_read_b128 v[20:23], v143 offset:35840
	ds_read_b128 v[224:227], v143 offset:36864
	ds_read_b128 v[228:231], v143 offset:37888
	ds_read_b128 v[232:235], v143 offset:38912
	ds_read_b128 v[236:239], v143 offset:39936
	global_load_lds_dwordx4 v[48:49], off
	v_lshl_add_u64 v[48:49], s[36:37], 0, v[132:133]
	s_mov_b32 m0, s47
	s_nop 0
	global_load_lds_dwordx4 v[48:49], off
	s_waitcnt vmcnt(8)
	s_waitcnt lgkmcnt(0)
	s_barrier
	v_mfma_f32_16x16x32_bf16 v[48:51], v[24:27], v[0:3], v[64:67]
	v_mfma_f32_16x16x32_bf16 v[120:123], v[28:31], v[4:7], v[48:51]
	v_mfma_f32_16x16x32_bf16 v[48:51], v[60:63], v[0:3], v[68:71]
	v_mfma_f32_16x16x32_bf16 v[112:115], v[204:207], v[4:7], v[48:51]
	v_mfma_f32_16x16x32_bf16 v[48:51], v[24:27], v[16:19], v[72:75]
	v_mfma_f32_16x16x32_bf16 v[104:107], v[28:31], v[20:23], v[48:51]
	v_mfma_f32_16x16x32_bf16 v[48:51], v[60:63], v[16:19], v[76:79]
	v_mfma_f32_16x16x32_bf16 v[96:99], v[204:207], v[20:23], v[48:51]
	v_mfma_f32_16x16x32_bf16 v[48:51], v[24:27], v[224:227], v[80:83]
	v_mfma_f32_16x16x32_bf16 v[88:91], v[28:31], v[228:231], v[48:51]
	v_mfma_f32_16x16x32_bf16 v[48:51], v[60:63], v[224:227], v[84:87]
	v_mfma_f32_16x16x32_bf16 v[80:83], v[204:207], v[228:231], v[48:51]
	v_mfma_f32_16x16x32_bf16 v[48:51], v[24:27], v[232:235], v[92:95]
	v_mfma_f32_16x16x32_bf16 v[72:75], v[28:31], v[236:239], v[48:51]
	v_mfma_f32_16x16x32_bf16 v[48:51], v[60:63], v[232:235], v[100:103]
	v_mfma_f32_16x16x32_bf16 v[64:67], v[204:207], v[236:239], v[48:51]
	v_mfma_f32_16x16x32_bf16 v[48:51], v[208:211], v[0:3], v[108:111]
	v_mfma_f32_16x16x32_bf16 v[0:3], v[216:219], v[0:3], v[32:35]
	v_mfma_f32_16x16x32_bf16 v[52:55], v[212:215], v[4:7], v[48:51]
	v_mfma_f32_16x16x32_bf16 v[48:51], v[220:223], v[4:7], v[0:3]
	v_mfma_f32_16x16x32_bf16 v[0:3], v[208:211], v[16:19], v[36:39]
	v_mfma_f32_16x16x32_bf16 v[36:39], v[212:215], v[20:23], v[0:3]
	v_mfma_f32_16x16x32_bf16 v[0:3], v[216:219], v[16:19], v[40:43]
	v_mfma_f32_16x16x32_bf16 v[32:35], v[220:223], v[20:23], v[0:3]
	v_mfma_f32_16x16x32_bf16 v[0:3], v[208:211], v[224:227], v[44:47]
	v_mfma_f32_16x16x32_bf16 v[20:23], v[212:215], v[228:231], v[0:3]
	v_mfma_f32_16x16x32_bf16 v[0:3], v[216:219], v[224:227], v[116:119]
	v_mfma_f32_16x16x32_bf16 v[16:19], v[220:223], v[228:231], v[0:3]
	v_mfma_f32_16x16x32_bf16 v[0:3], v[208:211], v[232:235], v[124:127]
	v_mfma_f32_16x16x32_bf16 v[4:7], v[212:215], v[236:239], v[0:3]
	v_mfma_f32_16x16x32_bf16 v[0:3], v[216:219], v[232:235], v[56:59]
	v_mfma_f32_16x16x32_bf16 v[0:3], v[220:223], v[236:239], v[0:3]
	s_barrier
	s_add_i32 s17, s17, s44
	v_lshl_add_u64 v[56:57], v[152:153], 0, s[8:9]
	s_mov_b32 m0, s17
	ds_read_b128 v[40:43], v143 offset:49152
	ds_read_b128 v[44:47], v143 offset:50176
	ds_read_b128 v[224:227], v143 offset:51200
	ds_read_b128 v[228:231], v143 offset:52224
	ds_read_b128 v[232:235], v143 offset:53248
	ds_read_b128 v[236:239], v143 offset:54272
	ds_read_b128 v[240:243], v143 offset:55296
	ds_read_b128 v[244:247], v143 offset:56320
	global_load_lds_dwordx4 v[56:57], off
	s_add_i32 m0, s17, 0x2000
	s_add_u32 s34, s34, 0x8080
	v_lshl_add_u64 v[56:57], v[248:249], 0, s[8:9]
	s_addc_u32 s35, s35, 0
	s_add_i32 s17, s19, s44
	global_load_lds_dwordx4 v[56:57], off
	v_lshl_add_u64 v[56:57], s[34:35], 0, v[130:131]
	s_mov_b32 m0, s17
	s_nop 0
	global_load_lds_dwordx4 v[56:57], off
	v_lshl_add_u64 v[56:57], s[34:35], 0, v[134:135]
	s_add_i32 m0, s17, 0x2000
	s_nop 0
	global_load_lds_dwordx4 v[56:57], off
	v_lshl_add_u64 v[56:57], v[250:251], 0, s[8:9]
	s_mov_b32 m0, s49
	s_nop 0
	global_load_lds_dwordx4 v[56:57], off
	v_lshl_add_u64 v[56:57], v[252:253], 0, s[8:9]
	s_mov_b32 m0, s50
	s_nop 0
	global_load_lds_dwordx4 v[56:57], off
	s_waitcnt vmcnt(8)
	s_waitcnt lgkmcnt(0)
	s_barrier
	v_mfma_f32_16x16x32_bf16 v[56:59], v[24:27], v[40:43], v[144:147]
	v_mfma_f32_16x16x32_bf16 v[124:127], v[28:31], v[44:47], v[56:59]
	v_mfma_f32_16x16x32_bf16 v[56:59], v[60:63], v[40:43], v[148:151]
	v_mfma_f32_16x16x32_bf16 v[116:119], v[204:207], v[44:47], v[56:59]
	v_mfma_f32_16x16x32_bf16 v[56:59], v[24:27], v[224:227], v[156:159]
	v_mfma_f32_16x16x32_bf16 v[108:111], v[28:31], v[228:231], v[56:59]
	v_mfma_f32_16x16x32_bf16 v[56:59], v[60:63], v[224:227], v[160:163]
	v_mfma_f32_16x16x32_bf16 v[100:103], v[204:207], v[228:231], v[56:59]
	v_mfma_f32_16x16x32_bf16 v[56:59], v[24:27], v[232:235], v[164:167]
	v_mfma_f32_16x16x32_bf16 v[92:95], v[28:31], v[236:239], v[56:59]
	v_mfma_f32_16x16x32_bf16 v[56:59], v[60:63], v[232:235], v[168:171]
	v_mfma_f32_16x16x32_bf16 v[24:27], v[24:27], v[240:243], v[172:175]
	v_mfma_f32_16x16x32_bf16 v[8:11], v[60:63], v[240:243], v[8:11]
	v_mfma_f32_16x16x32_bf16 v[84:87], v[204:207], v[236:239], v[56:59]
	v_mfma_f32_16x16x32_bf16 v[76:79], v[28:31], v[244:247], v[24:27]
	v_mfma_f32_16x16x32_bf16 v[68:71], v[204:207], v[244:247], v[8:11]
	v_mfma_f32_16x16x32_bf16 v[8:11], v[208:211], v[40:43], v[12:15]
	v_mfma_f32_16x16x32_bf16 v[60:63], v[212:215], v[44:47], v[8:11]
	v_mfma_f32_16x16x32_bf16 v[8:11], v[216:219], v[40:43], v[176:179]
	v_mfma_f32_16x16x32_bf16 v[56:59], v[220:223], v[44:47], v[8:11]
	v_mfma_f32_16x16x32_bf16 v[8:11], v[208:211], v[224:227], v[180:183]
	v_mfma_f32_16x16x32_bf16 v[44:47], v[212:215], v[228:231], v[8:11]
	v_mfma_f32_16x16x32_bf16 v[8:11], v[216:219], v[224:227], v[184:187]
	v_mfma_f32_16x16x32_bf16 v[40:43], v[220:223], v[228:231], v[8:11]
	v_mfma_f32_16x16x32_bf16 v[8:11], v[208:211], v[232:235], v[188:191]
	v_mfma_f32_16x16x32_bf16 v[28:31], v[212:215], v[236:239], v[8:11]
	v_mfma_f32_16x16x32_bf16 v[8:11], v[216:219], v[232:235], v[192:195]
	v_mfma_f32_16x16x32_bf16 v[24:27], v[220:223], v[236:239], v[8:11]
	v_mfma_f32_16x16x32_bf16 v[8:11], v[208:211], v[240:243], v[196:199]
	v_mfma_f32_16x16x32_bf16 v[12:15], v[212:215], v[244:247], v[8:11]
	v_mfma_f32_16x16x32_bf16 v[8:11], v[216:219], v[240:243], v[200:203]
	v_mfma_f32_16x16x32_bf16 v[8:11], v[220:223], v[244:247], v[8:11]
	s_barrier
	s_andn2_b64 vcc, exec, s[10:11]
	s_cbranch_vccnz .LBB0_1171
	s_barrier

.LBB0_1529:
	ds_read_b128 v[144:147], v149
	ds_read_b128 v[156:159], v149 offset:1024
	ds_read_b128 v[160:163], v149 offset:2048
	ds_read_b128 v[164:167], v149 offset:3072
	ds_read_b128 v[168:171], v150
	ds_read_b128 v[172:175], v150 offset:1024
	ds_read_b128 v[176:179], v150 offset:2048
	ds_read_b128 v[180:183], v150 offset:3072
	s_add_u32 s6, s8, 0x100
	s_addc_u32 s7, s9, 0
	s_cmp_eq_u32 s60, 12
	s_cselect_b32 s35, s27, s7
	s_cselect_b32 s34, s26, s6
	s_cselect_b32 s11, s19, s59
	s_cselect_b32 s10, s57, s58
	v_lshl_add_u64 v[216:217], s[8:9], 0, v[138:139]
	s_add_i32 m0, s31, 0xc000
	ds_read_b128 v[184:187], v151
	ds_read_b128 v[188:191], v151 offset:1024
	ds_read_b128 v[192:195], v151 offset:2048
	ds_read_b128 v[196:199], v151 offset:3072
	ds_read_b128 v[200:203], v151 offset:4096
	ds_read_b128 v[204:207], v151 offset:5120
	ds_read_b128 v[208:211], v151 offset:6144
	ds_read_b128 v[212:215], v151 offset:7168
	global_load_lds_dwordx4 v[216:217], off
	v_lshl_add_u64 v[216:217], s[8:9], 0, v[136:137]
	s_add_i32 m0, s31, 0xe000
	s_nop 0
	global_load_lds_dwordx4 v[216:217], off
	s_waitcnt vmcnt(8)
	s_waitcnt lgkmcnt(0)
	s_barrier
	v_mfma_f32_16x16x32_bf16 v[124:127], v[144:147], v[184:187], v[124:127]
	v_mfma_f32_16x16x32_bf16 v[120:123], v[160:163], v[184:187], v[120:123]
	v_mfma_f32_16x16x32_bf16 v[108:111], v[144:147], v[192:195], v[108:111]
	v_mfma_f32_16x16x32_bf16 v[104:107], v[160:163], v[192:195], v[104:107]
	v_mfma_f32_16x16x32_bf16 v[92:95], v[144:147], v[200:203], v[92:95]
	v_mfma_f32_16x16x32_bf16 v[88:91], v[160:163], v[200:203], v[88:91]
	v_mfma_f32_16x16x32_bf16 v[76:79], v[144:147], v[208:211], v[76:79]
	v_mfma_f32_16x16x32_bf16 v[72:75], v[160:163], v[208:211], v[72:75]
	v_mfma_f32_16x16x32_bf16 v[124:127], v[156:159], v[188:191], v[124:127]
	v_mfma_f32_16x16x32_bf16 v[120:123], v[164:167], v[188:191], v[120:123]
	v_mfma_f32_16x16x32_bf16 v[108:111], v[156:159], v[196:199], v[108:111]
	v_mfma_f32_16x16x32_bf16 v[104:107], v[164:167], v[196:199], v[104:107]
	v_mfma_f32_16x16x32_bf16 v[92:95], v[156:159], v[204:207], v[92:95]
	v_mfma_f32_16x16x32_bf16 v[88:91], v[164:167], v[204:207], v[88:91]
	v_mfma_f32_16x16x32_bf16 v[76:79], v[156:159], v[212:215], v[76:79]
	v_mfma_f32_16x16x32_bf16 v[72:75], v[164:167], v[212:215], v[72:75]
	v_mfma_f32_16x16x32_bf16 v[116:119], v[168:171], v[184:187], v[116:119]
	v_mfma_f32_16x16x32_bf16 v[112:115], v[176:179], v[184:187], v[112:115]
	v_mfma_f32_16x16x32_bf16 v[100:103], v[168:171], v[192:195], v[100:103]
	v_mfma_f32_16x16x32_bf16 v[96:99], v[176:179], v[192:195], v[96:99]
	v_mfma_f32_16x16x32_bf16 v[84:87], v[168:171], v[200:203], v[84:87]
	v_mfma_f32_16x16x32_bf16 v[80:83], v[176:179], v[200:203], v[80:83]
	v_mfma_f32_16x16x32_bf16 v[68:71], v[168:171], v[208:211], v[68:71]
	v_mfma_f32_16x16x32_bf16 v[64:67], v[176:179], v[208:211], v[64:67]
	v_mfma_f32_16x16x32_bf16 v[116:119], v[172:175], v[188:191], v[116:119]
	v_mfma_f32_16x16x32_bf16 v[112:115], v[180:183], v[188:191], v[112:115]
	v_mfma_f32_16x16x32_bf16 v[100:103], v[172:175], v[196:199], v[100:103]
	v_mfma_f32_16x16x32_bf16 v[96:99], v[180:183], v[196:199], v[96:99]
	v_mfma_f32_16x16x32_bf16 v[84:87], v[172:175], v[204:207], v[84:87]
	v_mfma_f32_16x16x32_bf16 v[80:83], v[180:183], v[204:207], v[80:83]
	v_mfma_f32_16x16x32_bf16 v[68:71], v[172:175], v[212:215], v[68:71]
	v_mfma_f32_16x16x32_bf16 v[64:67], v[180:183], v[212:215], v[64:67]
	s_barrier
	s_add_i32 s8, s53, s41
	v_lshl_add_u64 v[216:217], s[10:11], 0, v[130:131]
	s_mov_b32 m0, s8
	ds_read_b128 v[184:187], v151 offset:16384
	ds_read_b128 v[188:191], v151 offset:17408
	ds_read_b128 v[192:195], v151 offset:18432
	ds_read_b128 v[196:199], v151 offset:19456
	ds_read_b128 v[200:203], v151 offset:20480
	ds_read_b128 v[204:207], v151 offset:21504
	ds_read_b128 v[208:211], v151 offset:22528
	ds_read_b128 v[212:215], v151 offset:23552
	global_load_lds_dwordx4 v[216:217], off
	s_add_i32 m0, s8, 0x2000
	s_add_u32 s8, s10, 0x40000
	v_lshl_add_u64 v[218:219], s[10:11], 0, v[134:135]
	s_addc_u32 s9, s11, 0
	s_add_i32 s61, s54, s41
	global_load_lds_dwordx4 v[218:219], off
	v_lshl_add_u64 v[220:221], s[8:9], 0, v[130:131]
	s_mov_b32 m0, s61
	v_lshl_add_u64 v[222:223], s[34:35], 0, v[132:133]
	global_load_lds_dwordx4 v[220:221], off
	v_lshl_add_u64 v[220:221], s[8:9], 0, v[134:135]
	s_add_i32 m0, s61, 0x2000
	s_nop 0
	global_load_lds_dwordx4 v[220:221], off
	v_lshl_add_u64 v[220:221], s[34:35], 0, v[128:129]
	s_mov_b32 m0, s31
	s_nop 0
	global_load_lds_dwordx4 v[220:221], off
	s_mov_b32 m0, s42
	s_nop 0
	global_load_lds_dwordx4 v[222:223], off
	s_waitcnt vmcnt(8)
	s_waitcnt lgkmcnt(0)
	s_barrier
	v_mfma_f32_16x16x32_bf16 v[60:63], v[144:147], v[184:187], v[60:63]
	v_mfma_f32_16x16x32_bf16 v[56:59], v[160:163], v[184:187], v[56:59]
	v_mfma_f32_16x16x32_bf16 v[44:47], v[144:147], v[192:195], v[44:47]
	v_mfma_f32_16x16x32_bf16 v[40:43], v[160:163], v[192:195], v[40:43]
	v_mfma_f32_16x16x32_bf16 v[28:31], v[144:147], v[200:203], v[28:31]
	v_mfma_f32_16x16x32_bf16 v[24:27], v[160:163], v[200:203], v[24:27]
	v_mfma_f32_16x16x32_bf16 v[12:15], v[144:147], v[208:211], v[12:15]
	v_mfma_f32_16x16x32_bf16 v[8:11], v[160:163], v[208:211], v[8:11]
	v_mfma_f32_16x16x32_bf16 v[60:63], v[156:159], v[188:191], v[60:63]
	v_mfma_f32_16x16x32_bf16 v[56:59], v[164:167], v[188:191], v[56:59]
	v_mfma_f32_16x16x32_bf16 v[44:47], v[156:159], v[196:199], v[44:47]
	v_mfma_f32_16x16x32_bf16 v[40:43], v[164:167], v[196:199], v[40:43]
	v_mfma_f32_16x16x32_bf16 v[28:31], v[156:159], v[204:207], v[28:31]
	v_mfma_f32_16x16x32_bf16 v[24:27], v[164:167], v[204:207], v[24:27]
	v_mfma_f32_16x16x32_bf16 v[12:15], v[156:159], v[212:215], v[12:15]
	v_mfma_f32_16x16x32_bf16 v[8:11], v[164:167], v[212:215], v[8:11]
	v_mfma_f32_16x16x32_bf16 v[52:55], v[168:171], v[184:187], v[52:55]
	v_mfma_f32_16x16x32_bf16 v[48:51], v[176:179], v[184:187], v[48:51]
	v_mfma_f32_16x16x32_bf16 v[36:39], v[168:171], v[192:195], v[36:39]
	v_mfma_f32_16x16x32_bf16 v[32:35], v[176:179], v[192:195], v[32:35]
	v_mfma_f32_16x16x32_bf16 v[20:23], v[168:171], v[200:203], v[20:23]
	v_mfma_f32_16x16x32_bf16 v[16:19], v[176:179], v[200:203], v[16:19]
	v_mfma_f32_16x16x32_bf16 v[4:7], v[168:171], v[208:211], v[4:7]
	v_mfma_f32_16x16x32_bf16 v[0:3], v[176:179], v[208:211], v[0:3]
	v_mfma_f32_16x16x32_bf16 v[52:55], v[172:175], v[188:191], v[52:55]
	v_mfma_f32_16x16x32_bf16 v[48:51], v[180:183], v[188:191], v[48:51]
	v_mfma_f32_16x16x32_bf16 v[36:39], v[172:175], v[196:199], v[36:39]
	v_mfma_f32_16x16x32_bf16 v[32:35], v[180:183], v[196:199], v[32:35]
	v_mfma_f32_16x16x32_bf16 v[20:23], v[172:175], v[204:207], v[20:23]
	v_mfma_f32_16x16x32_bf16 v[16:19], v[180:183], v[204:207], v[16:19]
	v_mfma_f32_16x16x32_bf16 v[4:7], v[172:175], v[212:215], v[4:7]
	v_mfma_f32_16x16x32_bf16 v[0:3], v[180:183], v[212:215], v[0:3]
	s_barrier
	s_add_i32 s61, 0, 0x18000
	v_add_u32_e32 v153, s61, v148
	s_add_i32 s62, 0, 0x1c000
	ds_read_b128 v[144:147], v153
	ds_read_b128 v[156:159], v153 offset:1024
	ds_read_b128 v[160:163], v153 offset:2048
	ds_read_b128 v[164:167], v153 offset:3072
	v_add_u32_e32 v153, s62, v148
	ds_read_b128 v[168:171], v153
	ds_read_b128 v[172:175], v153 offset:1024
	ds_read_b128 v[176:179], v153 offset:2048
	ds_read_b128 v[180:183], v153 offset:3072
	s_add_u32 s8, s34, 0xf0000
	s_addc_u32 s9, s35, 0
	s_mov_b32 m0, s43
	v_lshl_add_u64 v[224:225], s[8:9], 0, v[128:129]
	ds_read_b128 v[184:187], v151 offset:32768
	ds_read_b128 v[188:191], v151 offset:33792
	ds_read_b128 v[192:195], v151 offset:34816
	ds_read_b128 v[196:199], v151 offset:35840
	ds_read_b128 v[200:203], v151 offset:36864
	ds_read_b128 v[204:207], v151 offset:37888
	ds_read_b128 v[208:211], v151 offset:38912
	ds_read_b128 v[212:215], v151 offset:39936
	global_load_lds_dwordx4 v[224:225], off
	v_lshl_add_u64 v[224:225], s[8:9], 0, v[132:133]
	s_mov_b32 m0, s44
	s_nop 0
	global_load_lds_dwordx4 v[224:225], off
	s_waitcnt vmcnt(8)
	s_waitcnt lgkmcnt(0)
	s_barrier
	v_mfma_f32_16x16x32_bf16 v[124:127], v[144:147], v[184:187], v[124:127]
	v_mfma_f32_16x16x32_bf16 v[120:123], v[160:163], v[184:187], v[120:123]
	v_mfma_f32_16x16x32_bf16 v[108:111], v[144:147], v[192:195], v[108:111]
	v_mfma_f32_16x16x32_bf16 v[104:107], v[160:163], v[192:195], v[104:107]
	v_mfma_f32_16x16x32_bf16 v[92:95], v[144:147], v[200:203], v[92:95]
	v_mfma_f32_16x16x32_bf16 v[88:91], v[160:163], v[200:203], v[88:91]
	v_mfma_f32_16x16x32_bf16 v[76:79], v[144:147], v[208:211], v[76:79]
	v_mfma_f32_16x16x32_bf16 v[72:75], v[160:163], v[208:211], v[72:75]
	v_mfma_f32_16x16x32_bf16 v[124:127], v[156:159], v[188:191], v[124:127]
	v_mfma_f32_16x16x32_bf16 v[120:123], v[164:167], v[188:191], v[120:123]
	v_mfma_f32_16x16x32_bf16 v[108:111], v[156:159], v[196:199], v[108:111]
	v_mfma_f32_16x16x32_bf16 v[104:107], v[164:167], v[196:199], v[104:107]
	v_mfma_f32_16x16x32_bf16 v[92:95], v[156:159], v[204:207], v[92:95]
	v_mfma_f32_16x16x32_bf16 v[88:91], v[164:167], v[204:207], v[88:91]
	v_mfma_f32_16x16x32_bf16 v[76:79], v[156:159], v[212:215], v[76:79]
	v_mfma_f32_16x16x32_bf16 v[72:75], v[164:167], v[212:215], v[72:75]
	v_mfma_f32_16x16x32_bf16 v[116:119], v[168:171], v[184:187], v[116:119]
	v_mfma_f32_16x16x32_bf16 v[112:115], v[176:179], v[184:187], v[112:115]
	v_mfma_f32_16x16x32_bf16 v[100:103], v[168:171], v[192:195], v[100:103]
	v_mfma_f32_16x16x32_bf16 v[96:99], v[176:179], v[192:195], v[96:99]
	v_mfma_f32_16x16x32_bf16 v[84:87], v[168:171], v[200:203], v[84:87]
	v_mfma_f32_16x16x32_bf16 v[80:83], v[176:179], v[200:203], v[80:83]
	v_mfma_f32_16x16x32_bf16 v[68:71], v[168:171], v[208:211], v[68:71]
	v_mfma_f32_16x16x32_bf16 v[64:67], v[176:179], v[208:211], v[64:67]
	v_mfma_f32_16x16x32_bf16 v[116:119], v[172:175], v[188:191], v[116:119]
	v_mfma_f32_16x16x32_bf16 v[112:115], v[180:183], v[188:191], v[112:115]
	v_mfma_f32_16x16x32_bf16 v[100:103], v[172:175], v[196:199], v[100:103]
	v_mfma_f32_16x16x32_bf16 v[96:99], v[180:183], v[196:199], v[96:99]
	v_mfma_f32_16x16x32_bf16 v[84:87], v[172:175], v[204:207], v[84:87]
	v_mfma_f32_16x16x32_bf16 v[80:83], v[180:183], v[204:207], v[80:83]
	v_mfma_f32_16x16x32_bf16 v[68:71], v[172:175], v[212:215], v[68:71]
	v_mfma_f32_16x16x32_bf16 v[64:67], v[180:183], v[212:215], v[64:67]
	s_barrier
	s_add_i32 s8, s61, s41
	v_lshl_add_u64 v[216:217], v[216:217], 0, s[14:15]
	s_mov_b32 m0, s8
	ds_read_b128 v[184:187], v151 offset:49152
	ds_read_b128 v[188:191], v151 offset:50176
	ds_read_b128 v[192:195], v151 offset:51200
	ds_read_b128 v[196:199], v151 offset:52224
	ds_read_b128 v[200:203], v151 offset:53248
	ds_read_b128 v[204:207], v151 offset:54272
	ds_read_b128 v[208:211], v151 offset:55296
	ds_read_b128 v[212:215], v151 offset:56320
	global_load_lds_dwordx4 v[216:217], off
	s_add_i32 m0, s8, 0x2000
	s_add_u32 s8, s10, 0x40080
	v_lshl_add_u64 v[216:217], v[218:219], 0, s[14:15]
	s_addc_u32 s9, s11, 0
	s_add_i32 s10, s62, s41
	global_load_lds_dwordx4 v[216:217], off
	v_lshl_add_u64 v[216:217], s[8:9], 0, v[130:131]
	s_mov_b32 m0, s10
	s_nop 0
	global_load_lds_dwordx4 v[216:217], off
	v_lshl_add_u64 v[216:217], s[8:9], 0, v[134:135]
	s_add_i32 m0, s10, 0x2000
	s_nop 0
	global_load_lds_dwordx4 v[216:217], off
	v_lshl_add_u64 v[216:217], v[220:221], 0, s[14:15]
	s_mov_b32 m0, s49
	s_nop 0
	global_load_lds_dwordx4 v[216:217], off
	v_lshl_add_u64 v[216:217], v[222:223], 0, s[14:15]
	s_mov_b32 m0, s50
	s_nop 0
	global_load_lds_dwordx4 v[216:217], off
	s_waitcnt vmcnt(8)
	s_waitcnt lgkmcnt(0)
	s_barrier
	v_mfma_f32_16x16x32_bf16 v[60:63], v[144:147], v[184:187], v[60:63]
	v_mfma_f32_16x16x32_bf16 v[56:59], v[160:163], v[184:187], v[56:59]
	v_mfma_f32_16x16x32_bf16 v[44:47], v[144:147], v[192:195], v[44:47]
	v_mfma_f32_16x16x32_bf16 v[40:43], v[160:163], v[192:195], v[40:43]
	v_mfma_f32_16x16x32_bf16 v[28:31], v[144:147], v[200:203], v[28:31]
	v_mfma_f32_16x16x32_bf16 v[24:27], v[160:163], v[200:203], v[24:27]
	v_mfma_f32_16x16x32_bf16 v[12:15], v[144:147], v[208:211], v[12:15]
	v_mfma_f32_16x16x32_bf16 v[8:11], v[160:163], v[208:211], v[8:11]
	v_mfma_f32_16x16x32_bf16 v[60:63], v[156:159], v[188:191], v[60:63]
	v_mfma_f32_16x16x32_bf16 v[56:59], v[164:167], v[188:191], v[56:59]
	v_mfma_f32_16x16x32_bf16 v[44:47], v[156:159], v[196:199], v[44:47]
	v_mfma_f32_16x16x32_bf16 v[40:43], v[164:167], v[196:199], v[40:43]
	v_mfma_f32_16x16x32_bf16 v[28:31], v[156:159], v[204:207], v[28:31]
	v_mfma_f32_16x16x32_bf16 v[24:27], v[164:167], v[204:207], v[24:27]
	v_mfma_f32_16x16x32_bf16 v[12:15], v[156:159], v[212:215], v[12:15]
	v_mfma_f32_16x16x32_bf16 v[8:11], v[164:167], v[212:215], v[8:11]
	v_mfma_f32_16x16x32_bf16 v[52:55], v[168:171], v[184:187], v[52:55]
	v_mfma_f32_16x16x32_bf16 v[48:51], v[176:179], v[184:187], v[48:51]
	v_mfma_f32_16x16x32_bf16 v[36:39], v[168:171], v[192:195], v[36:39]
	v_mfma_f32_16x16x32_bf16 v[32:35], v[176:179], v[192:195], v[32:35]
	v_mfma_f32_16x16x32_bf16 v[20:23], v[168:171], v[200:203], v[20:23]
	v_mfma_f32_16x16x32_bf16 v[16:19], v[176:179], v[200:203], v[16:19]
	v_mfma_f32_16x16x32_bf16 v[4:7], v[168:171], v[208:211], v[4:7]
	v_mfma_f32_16x16x32_bf16 v[0:3], v[176:179], v[208:211], v[0:3]
	v_mfma_f32_16x16x32_bf16 v[52:55], v[172:175], v[188:191], v[52:55]
	v_mfma_f32_16x16x32_bf16 v[48:51], v[180:183], v[188:191], v[48:51]
	v_mfma_f32_16x16x32_bf16 v[36:39], v[172:175], v[196:199], v[36:39]
	v_mfma_f32_16x16x32_bf16 v[32:35], v[180:183], v[196:199], v[32:35]
	v_mfma_f32_16x16x32_bf16 v[20:23], v[172:175], v[204:207], v[20:23]
	v_mfma_f32_16x16x32_bf16 v[16:19], v[180:183], v[204:207], v[16:19]
	v_mfma_f32_16x16x32_bf16 v[4:7], v[172:175], v[212:215], v[4:7]
	v_mfma_f32_16x16x32_bf16 v[0:3], v[180:183], v[212:215], v[0:3]
	s_barrier
	s_add_i32 s60, s60, 2
	s_add_u32 s58, s58, 0x100
	s_addc_u32 s59, s59, 0
	s_cmp_gt_u32 s60, 13
	s_mov_b64 s[8:9], s[6:7]
	s_cbranch_scc0 .LBB0_1529
	s_and_b64 vcc, exec, s[16:17]
	s_cbranch_vccz .LBB0_1532
	s_barrier

.LBB0_1613:
	ds_read_b128 v[144:147], v149
	ds_read_b128 v[156:159], v149 offset:1024
	ds_read_b128 v[160:163], v149 offset:2048
	ds_read_b128 v[164:167], v149 offset:3072
	ds_read_b128 v[168:171], v150
	ds_read_b128 v[172:175], v150 offset:1024
	ds_read_b128 v[176:179], v150 offset:2048
	ds_read_b128 v[180:183], v150 offset:3072
	s_add_u32 s34, s28, 0xfffc0080
	s_addc_u32 s35, s29, -1
	s_cmp_eq_u32 s63, 12
	s_cselect_b32 s37, s17, s35
	s_cselect_b32 s36, s59, s34
	s_cselect_b32 s35, s15, s62
	s_cselect_b32 s34, s60, s61
	v_lshl_add_u64 v[216:217], s[28:29], 0, v[138:139]
	s_add_i32 m0, s31, 0xc000
	ds_read_b128 v[184:187], v151
	ds_read_b128 v[188:191], v151 offset:1024
	ds_read_b128 v[192:195], v151 offset:2048
	ds_read_b128 v[196:199], v151 offset:3072
	ds_read_b128 v[200:203], v151 offset:4096
	ds_read_b128 v[204:207], v151 offset:5120
	ds_read_b128 v[208:211], v151 offset:6144
	ds_read_b128 v[212:215], v151 offset:7168
	global_load_lds_dwordx4 v[216:217], off
	v_lshl_add_u64 v[216:217], s[28:29], 0, v[136:137]
	s_add_i32 m0, s31, 0xe000
	s_nop 0
	global_load_lds_dwordx4 v[216:217], off
	s_waitcnt vmcnt(8)
	s_waitcnt lgkmcnt(0)
	s_barrier
	v_mfma_f32_16x16x32_bf16 v[124:127], v[144:147], v[184:187], v[124:127]
	v_mfma_f32_16x16x32_bf16 v[120:123], v[160:163], v[184:187], v[120:123]
	v_mfma_f32_16x16x32_bf16 v[108:111], v[144:147], v[192:195], v[108:111]
	v_mfma_f32_16x16x32_bf16 v[104:107], v[160:163], v[192:195], v[104:107]
	v_mfma_f32_16x16x32_bf16 v[92:95], v[144:147], v[200:203], v[92:95]
	v_mfma_f32_16x16x32_bf16 v[88:91], v[160:163], v[200:203], v[88:91]
	v_mfma_f32_16x16x32_bf16 v[76:79], v[144:147], v[208:211], v[76:79]
	v_mfma_f32_16x16x32_bf16 v[72:75], v[160:163], v[208:211], v[72:75]
	v_mfma_f32_16x16x32_bf16 v[124:127], v[156:159], v[188:191], v[124:127]
	v_mfma_f32_16x16x32_bf16 v[120:123], v[164:167], v[188:191], v[120:123]
	v_mfma_f32_16x16x32_bf16 v[108:111], v[156:159], v[196:199], v[108:111]
	v_mfma_f32_16x16x32_bf16 v[104:107], v[164:167], v[196:199], v[104:107]
	v_mfma_f32_16x16x32_bf16 v[92:95], v[156:159], v[204:207], v[92:95]
	v_mfma_f32_16x16x32_bf16 v[88:91], v[164:167], v[204:207], v[88:91]
	v_mfma_f32_16x16x32_bf16 v[76:79], v[156:159], v[212:215], v[76:79]
	v_mfma_f32_16x16x32_bf16 v[72:75], v[164:167], v[212:215], v[72:75]
	v_mfma_f32_16x16x32_bf16 v[116:119], v[168:171], v[184:187], v[116:119]
	v_mfma_f32_16x16x32_bf16 v[112:115], v[176:179], v[184:187], v[112:115]
	v_mfma_f32_16x16x32_bf16 v[100:103], v[168:171], v[192:195], v[100:103]
	v_mfma_f32_16x16x32_bf16 v[96:99], v[176:179], v[192:195], v[96:99]
	v_mfma_f32_16x16x32_bf16 v[84:87], v[168:171], v[200:203], v[84:87]
	v_mfma_f32_16x16x32_bf16 v[80:83], v[176:179], v[200:203], v[80:83]
	v_mfma_f32_16x16x32_bf16 v[68:71], v[168:171], v[208:211], v[68:71]
	v_mfma_f32_16x16x32_bf16 v[64:67], v[176:179], v[208:211], v[64:67]
	v_mfma_f32_16x16x32_bf16 v[116:119], v[172:175], v[188:191], v[116:119]
	v_mfma_f32_16x16x32_bf16 v[112:115], v[180:183], v[188:191], v[112:115]
	v_mfma_f32_16x16x32_bf16 v[100:103], v[172:175], v[196:199], v[100:103]
	v_mfma_f32_16x16x32_bf16 v[96:99], v[180:183], v[196:199], v[96:99]
	v_mfma_f32_16x16x32_bf16 v[84:87], v[172:175], v[204:207], v[84:87]
	v_mfma_f32_16x16x32_bf16 v[80:83], v[180:183], v[204:207], v[80:83]
	v_mfma_f32_16x16x32_bf16 v[68:71], v[172:175], v[212:215], v[68:71]
	v_mfma_f32_16x16x32_bf16 v[64:67], v[180:183], v[212:215], v[64:67]
	s_barrier
	s_add_i32 s64, s55, s43
	v_lshl_add_u64 v[216:217], s[34:35], 0, v[132:133]
	s_mov_b32 m0, s64
	ds_read_b128 v[184:187], v151 offset:16384
	ds_read_b128 v[188:191], v151 offset:17408
	ds_read_b128 v[192:195], v151 offset:18432
	ds_read_b128 v[196:199], v151 offset:19456
	ds_read_b128 v[200:203], v151 offset:20480
	ds_read_b128 v[204:207], v151 offset:21504
	ds_read_b128 v[208:211], v151 offset:22528
	ds_read_b128 v[212:215], v151 offset:23552
	global_load_lds_dwordx4 v[216:217], off
	s_add_i32 m0, s64, 0x2000
	s_add_u32 s64, s34, 0x40000
	v_lshl_add_u64 v[218:219], s[34:35], 0, v[128:129]
	s_addc_u32 s65, s35, 0
	s_add_i32 s66, s56, s43
	global_load_lds_dwordx4 v[218:219], off
	v_lshl_add_u64 v[220:221], s[64:65], 0, v[132:133]
	s_mov_b32 m0, s66
	v_lshl_add_u64 v[222:223], s[36:37], 0, v[130:131]
	global_load_lds_dwordx4 v[220:221], off
	v_lshl_add_u64 v[220:221], s[64:65], 0, v[128:129]
	s_add_i32 m0, s66, 0x2000
	s_nop 0
	global_load_lds_dwordx4 v[220:221], off
	v_lshl_add_u64 v[220:221], s[36:37], 0, v[134:135]
	s_mov_b32 m0, s31
	s_nop 0
	global_load_lds_dwordx4 v[220:221], off
	s_mov_b32 m0, s46
	s_nop 0
	global_load_lds_dwordx4 v[222:223], off
	s_waitcnt vmcnt(8)
	s_waitcnt lgkmcnt(0)
	s_barrier
	v_mfma_f32_16x16x32_bf16 v[60:63], v[144:147], v[184:187], v[60:63]
	v_mfma_f32_16x16x32_bf16 v[56:59], v[160:163], v[184:187], v[56:59]
	v_mfma_f32_16x16x32_bf16 v[44:47], v[144:147], v[192:195], v[44:47]
	v_mfma_f32_16x16x32_bf16 v[40:43], v[160:163], v[192:195], v[40:43]
	v_mfma_f32_16x16x32_bf16 v[28:31], v[144:147], v[200:203], v[28:31]
	v_mfma_f32_16x16x32_bf16 v[24:27], v[160:163], v[200:203], v[24:27]
	v_mfma_f32_16x16x32_bf16 v[12:15], v[144:147], v[208:211], v[12:15]
	v_mfma_f32_16x16x32_bf16 v[8:11], v[160:163], v[208:211], v[8:11]
	v_mfma_f32_16x16x32_bf16 v[60:63], v[156:159], v[188:191], v[60:63]
	v_mfma_f32_16x16x32_bf16 v[56:59], v[164:167], v[188:191], v[56:59]
	v_mfma_f32_16x16x32_bf16 v[44:47], v[156:159], v[196:199], v[44:47]
	v_mfma_f32_16x16x32_bf16 v[40:43], v[164:167], v[196:199], v[40:43]
	v_mfma_f32_16x16x32_bf16 v[28:31], v[156:159], v[204:207], v[28:31]
	v_mfma_f32_16x16x32_bf16 v[24:27], v[164:167], v[204:207], v[24:27]
	v_mfma_f32_16x16x32_bf16 v[12:15], v[156:159], v[212:215], v[12:15]
	v_mfma_f32_16x16x32_bf16 v[8:11], v[164:167], v[212:215], v[8:11]
	v_mfma_f32_16x16x32_bf16 v[52:55], v[168:171], v[184:187], v[52:55]
	v_mfma_f32_16x16x32_bf16 v[48:51], v[176:179], v[184:187], v[48:51]
	v_mfma_f32_16x16x32_bf16 v[36:39], v[168:171], v[192:195], v[36:39]
	v_mfma_f32_16x16x32_bf16 v[32:35], v[176:179], v[192:195], v[32:35]
	v_mfma_f32_16x16x32_bf16 v[20:23], v[168:171], v[200:203], v[20:23]
	v_mfma_f32_16x16x32_bf16 v[16:19], v[176:179], v[200:203], v[16:19]
	v_mfma_f32_16x16x32_bf16 v[4:7], v[168:171], v[208:211], v[4:7]
	v_mfma_f32_16x16x32_bf16 v[0:3], v[176:179], v[208:211], v[0:3]
	v_mfma_f32_16x16x32_bf16 v[52:55], v[172:175], v[188:191], v[52:55]
	v_mfma_f32_16x16x32_bf16 v[48:51], v[180:183], v[188:191], v[48:51]
	v_mfma_f32_16x16x32_bf16 v[36:39], v[172:175], v[196:199], v[36:39]
	v_mfma_f32_16x16x32_bf16 v[32:35], v[180:183], v[196:199], v[32:35]
	v_mfma_f32_16x16x32_bf16 v[20:23], v[172:175], v[204:207], v[20:23]
	v_mfma_f32_16x16x32_bf16 v[16:19], v[180:183], v[204:207], v[16:19]
	v_mfma_f32_16x16x32_bf16 v[4:7], v[172:175], v[212:215], v[4:7]
	v_mfma_f32_16x16x32_bf16 v[0:3], v[180:183], v[212:215], v[0:3]
	s_barrier
	s_add_i32 s64, 0, 0x18000
	v_add_u32_e32 v153, s64, v148
	s_add_i32 s65, 0, 0x1c000
	ds_read_b128 v[144:147], v153
	ds_read_b128 v[156:159], v153 offset:1024
	ds_read_b128 v[160:163], v153 offset:2048
	ds_read_b128 v[164:167], v153 offset:3072
	v_add_u32_e32 v153, s65, v148
	ds_read_b128 v[168:171], v153
	ds_read_b128 v[172:175], v153 offset:1024
	ds_read_b128 v[176:179], v153 offset:2048
	ds_read_b128 v[180:183], v153 offset:3072
	s_add_u32 s36, s36, 0x40000
	s_addc_u32 s37, s37, 0
	s_mov_b32 m0, s47
	v_lshl_add_u64 v[224:225], s[36:37], 0, v[134:135]
	ds_read_b128 v[184:187], v151 offset:32768
	ds_read_b128 v[188:191], v151 offset:33792
	ds_read_b128 v[192:195], v151 offset:34816
	ds_read_b128 v[196:199], v151 offset:35840
	ds_read_b128 v[200:203], v151 offset:36864
	ds_read_b128 v[204:207], v151 offset:37888
	ds_read_b128 v[208:211], v151 offset:38912
	ds_read_b128 v[212:215], v151 offset:39936
	global_load_lds_dwordx4 v[224:225], off
	v_lshl_add_u64 v[224:225], s[36:37], 0, v[130:131]
	s_mov_b32 m0, s48
	s_nop 0
	global_load_lds_dwordx4 v[224:225], off
	s_waitcnt vmcnt(8)
	s_waitcnt lgkmcnt(0)
	s_barrier
	v_mfma_f32_16x16x32_bf16 v[124:127], v[144:147], v[184:187], v[124:127]
	v_mfma_f32_16x16x32_bf16 v[120:123], v[160:163], v[184:187], v[120:123]
	v_mfma_f32_16x16x32_bf16 v[108:111], v[144:147], v[192:195], v[108:111]
	v_mfma_f32_16x16x32_bf16 v[104:107], v[160:163], v[192:195], v[104:107]
	v_mfma_f32_16x16x32_bf16 v[92:95], v[144:147], v[200:203], v[92:95]
	v_mfma_f32_16x16x32_bf16 v[88:91], v[160:163], v[200:203], v[88:91]
	v_mfma_f32_16x16x32_bf16 v[76:79], v[144:147], v[208:211], v[76:79]
	v_mfma_f32_16x16x32_bf16 v[72:75], v[160:163], v[208:211], v[72:75]
	v_mfma_f32_16x16x32_bf16 v[124:127], v[156:159], v[188:191], v[124:127]
	v_mfma_f32_16x16x32_bf16 v[120:123], v[164:167], v[188:191], v[120:123]
	v_mfma_f32_16x16x32_bf16 v[108:111], v[156:159], v[196:199], v[108:111]
	v_mfma_f32_16x16x32_bf16 v[104:107], v[164:167], v[196:199], v[104:107]
	v_mfma_f32_16x16x32_bf16 v[92:95], v[156:159], v[204:207], v[92:95]
	v_mfma_f32_16x16x32_bf16 v[88:91], v[164:167], v[204:207], v[88:91]
	v_mfma_f32_16x16x32_bf16 v[76:79], v[156:159], v[212:215], v[76:79]
	v_mfma_f32_16x16x32_bf16 v[72:75], v[164:167], v[212:215], v[72:75]
	v_mfma_f32_16x16x32_bf16 v[116:119], v[168:171], v[184:187], v[116:119]
	v_mfma_f32_16x16x32_bf16 v[112:115], v[176:179], v[184:187], v[112:115]
	v_mfma_f32_16x16x32_bf16 v[100:103], v[168:171], v[192:195], v[100:103]
	v_mfma_f32_16x16x32_bf16 v[96:99], v[176:179], v[192:195], v[96:99]
	v_mfma_f32_16x16x32_bf16 v[84:87], v[168:171], v[200:203], v[84:87]
	v_mfma_f32_16x16x32_bf16 v[80:83], v[176:179], v[200:203], v[80:83]
	v_mfma_f32_16x16x32_bf16 v[68:71], v[168:171], v[208:211], v[68:71]
	v_mfma_f32_16x16x32_bf16 v[64:67], v[176:179], v[208:211], v[64:67]
	v_mfma_f32_16x16x32_bf16 v[116:119], v[172:175], v[188:191], v[116:119]
	v_mfma_f32_16x16x32_bf16 v[112:115], v[180:183], v[188:191], v[112:115]
	v_mfma_f32_16x16x32_bf16 v[100:103], v[172:175], v[196:199], v[100:103]
	v_mfma_f32_16x16x32_bf16 v[96:99], v[180:183], v[196:199], v[96:99]
	v_mfma_f32_16x16x32_bf16 v[84:87], v[172:175], v[204:207], v[84:87]
	v_mfma_f32_16x16x32_bf16 v[80:83], v[180:183], v[204:207], v[80:83]
	v_mfma_f32_16x16x32_bf16 v[68:71], v[172:175], v[212:215], v[68:71]
	v_mfma_f32_16x16x32_bf16 v[64:67], v[180:183], v[212:215], v[64:67]
	s_barrier
	s_add_i32 s36, s64, s43
	v_lshl_add_u64 v[216:217], v[216:217], 0, s[8:9]
	s_mov_b32 m0, s36
	ds_read_b128 v[184:187], v151 offset:49152
	ds_read_b128 v[188:191], v151 offset:50176
	ds_read_b128 v[192:195], v151 offset:51200
	ds_read_b128 v[196:199], v151 offset:52224
	ds_read_b128 v[200:203], v151 offset:53248
	ds_read_b128 v[204:207], v151 offset:54272
	ds_read_b128 v[208:211], v151 offset:55296
	ds_read_b128 v[212:215], v151 offset:56320
	global_load_lds_dwordx4 v[216:217], off
	s_add_i32 m0, s36, 0x2000
	s_add_u32 s34, s34, 0x40080
	v_lshl_add_u64 v[216:217], v[218:219], 0, s[8:9]
	s_addc_u32 s35, s35, 0
	s_add_i32 s36, s65, s43
	global_load_lds_dwordx4 v[216:217], off
	v_lshl_add_u64 v[216:217], s[34:35], 0, v[132:133]
	s_mov_b32 m0, s36
	s_nop 0
	global_load_lds_dwordx4 v[216:217], off
	v_lshl_add_u64 v[216:217], s[34:35], 0, v[128:129]
	s_add_i32 m0, s36, 0x2000
	s_nop 0
	global_load_lds_dwordx4 v[216:217], off
	v_lshl_add_u64 v[216:217], v[220:221], 0, s[8:9]
	s_mov_b32 m0, s51
	s_nop 0
	global_load_lds_dwordx4 v[216:217], off
	v_lshl_add_u64 v[216:217], v[222:223], 0, s[8:9]
	s_mov_b32 m0, s52
	s_nop 0
	global_load_lds_dwordx4 v[216:217], off
	s_waitcnt vmcnt(8)
	s_waitcnt lgkmcnt(0)
	s_barrier
	v_mfma_f32_16x16x32_bf16 v[60:63], v[144:147], v[184:187], v[60:63]
	v_mfma_f32_16x16x32_bf16 v[56:59], v[160:163], v[184:187], v[56:59]
	v_mfma_f32_16x16x32_bf16 v[44:47], v[144:147], v[192:195], v[44:47]
	v_mfma_f32_16x16x32_bf16 v[40:43], v[160:163], v[192:195], v[40:43]
	v_mfma_f32_16x16x32_bf16 v[28:31], v[144:147], v[200:203], v[28:31]
	v_mfma_f32_16x16x32_bf16 v[24:27], v[160:163], v[200:203], v[24:27]
	v_mfma_f32_16x16x32_bf16 v[12:15], v[144:147], v[208:211], v[12:15]
	v_mfma_f32_16x16x32_bf16 v[8:11], v[160:163], v[208:211], v[8:11]
	v_mfma_f32_16x16x32_bf16 v[60:63], v[156:159], v[188:191], v[60:63]
	v_mfma_f32_16x16x32_bf16 v[56:59], v[164:167], v[188:191], v[56:59]
	v_mfma_f32_16x16x32_bf16 v[44:47], v[156:159], v[196:199], v[44:47]
	v_mfma_f32_16x16x32_bf16 v[40:43], v[164:167], v[196:199], v[40:43]
	v_mfma_f32_16x16x32_bf16 v[28:31], v[156:159], v[204:207], v[28:31]
	v_mfma_f32_16x16x32_bf16 v[24:27], v[164:167], v[204:207], v[24:27]
	v_mfma_f32_16x16x32_bf16 v[12:15], v[156:159], v[212:215], v[12:15]
	v_mfma_f32_16x16x32_bf16 v[8:11], v[164:167], v[212:215], v[8:11]
	v_mfma_f32_16x16x32_bf16 v[52:55], v[168:171], v[184:187], v[52:55]
	v_mfma_f32_16x16x32_bf16 v[48:51], v[176:179], v[184:187], v[48:51]
	v_mfma_f32_16x16x32_bf16 v[36:39], v[168:171], v[192:195], v[36:39]
	v_mfma_f32_16x16x32_bf16 v[32:35], v[176:179], v[192:195], v[32:35]
	v_mfma_f32_16x16x32_bf16 v[20:23], v[168:171], v[200:203], v[20:23]
	v_mfma_f32_16x16x32_bf16 v[16:19], v[176:179], v[200:203], v[16:19]
	v_mfma_f32_16x16x32_bf16 v[4:7], v[168:171], v[208:211], v[4:7]
	v_mfma_f32_16x16x32_bf16 v[0:3], v[176:179], v[208:211], v[0:3]
	v_mfma_f32_16x16x32_bf16 v[52:55], v[172:175], v[188:191], v[52:55]
	v_mfma_f32_16x16x32_bf16 v[48:51], v[180:183], v[188:191], v[48:51]
	v_mfma_f32_16x16x32_bf16 v[36:39], v[172:175], v[196:199], v[36:39]
	v_mfma_f32_16x16x32_bf16 v[32:35], v[180:183], v[196:199], v[32:35]
	v_mfma_f32_16x16x32_bf16 v[20:23], v[172:175], v[204:207], v[20:23]
	v_mfma_f32_16x16x32_bf16 v[16:19], v[180:183], v[204:207], v[16:19]
	v_mfma_f32_16x16x32_bf16 v[4:7], v[172:175], v[212:215], v[4:7]
	v_mfma_f32_16x16x32_bf16 v[0:3], v[180:183], v[212:215], v[0:3]
	s_barrier
	s_add_i32 s63, s63, 2
	s_add_u32 s61, s61, 0x100
	s_addc_u32 s62, s62, 0
	s_add_u32 s28, s28, 0x100
	s_addc_u32 s29, s29, 0
	s_cmp_gt_u32 s63, 13
	s_cbranch_scc0 .LBB0_1613
	s_and_b64 vcc, exec, s[10:11]
	s_cbranch_vccz .LBB0_1616
	s_barrier

.LBB0_1813:
	ds_read_b128 v[144:147], v157
	ds_read_b128 v[148:151], v157 offset:1024
	ds_read_b128 v[162:165], v157 offset:2048
	ds_read_b128 v[166:169], v157 offset:3072
	ds_read_b128 v[170:173], v158
	ds_read_b128 v[174:177], v158 offset:1024
	ds_read_b128 v[178:181], v158 offset:2048
	ds_read_b128 v[182:185], v158 offset:3072
	s_add_u32 s10, s8, 0xfffc0080
	s_addc_u32 s11, s9, -1
	s_cmp_eq_u32 s39, 12
	s_cselect_b32 s31, s23, s11
	s_cselect_b32 s30, s34, s10
	s_cselect_b32 s11, s19, s37
	s_cselect_b32 s10, s35, s36
	v_lshl_add_u64 v[152:153], s[8:9], 0, v[138:139]
	s_add_i32 m0, s41, 0xc000
	ds_read_b128 v[186:189], v159
	ds_read_b128 v[190:193], v159 offset:1024
	ds_read_b128 v[194:197], v159 offset:2048
	ds_read_b128 v[198:201], v159 offset:3072
	ds_read_b128 v[202:205], v159 offset:4096
	ds_read_b128 v[206:209], v159 offset:5120
	ds_read_b128 v[210:213], v159 offset:6144
	ds_read_b128 v[214:217], v159 offset:7168
	global_load_lds_dwordx4 v[152:153], off
	v_lshl_add_u64 v[152:153], s[8:9], 0, v[136:137]
	s_add_i32 m0, s41, 0xe000
	s_nop 0
	global_load_lds_dwordx4 v[152:153], off
	s_waitcnt vmcnt(8)
	s_waitcnt lgkmcnt(0)
	s_barrier
	v_mfma_f32_16x16x32_bf16 v[124:127], v[144:147], v[186:189], v[124:127]
	v_mfma_f32_16x16x32_bf16 v[120:123], v[162:165], v[186:189], v[120:123]
	v_mfma_f32_16x16x32_bf16 v[108:111], v[144:147], v[194:197], v[108:111]
	v_mfma_f32_16x16x32_bf16 v[104:107], v[162:165], v[194:197], v[104:107]
	v_mfma_f32_16x16x32_bf16 v[92:95], v[144:147], v[202:205], v[92:95]
	v_mfma_f32_16x16x32_bf16 v[88:91], v[162:165], v[202:205], v[88:91]
	v_mfma_f32_16x16x32_bf16 v[76:79], v[144:147], v[210:213], v[76:79]
	v_mfma_f32_16x16x32_bf16 v[72:75], v[162:165], v[210:213], v[72:75]
	v_mfma_f32_16x16x32_bf16 v[124:127], v[148:151], v[190:193], v[124:127]
	v_mfma_f32_16x16x32_bf16 v[120:123], v[166:169], v[190:193], v[120:123]
	v_mfma_f32_16x16x32_bf16 v[108:111], v[148:151], v[198:201], v[108:111]
	v_mfma_f32_16x16x32_bf16 v[104:107], v[166:169], v[198:201], v[104:107]
	v_mfma_f32_16x16x32_bf16 v[92:95], v[148:151], v[206:209], v[92:95]
	v_mfma_f32_16x16x32_bf16 v[88:91], v[166:169], v[206:209], v[88:91]
	v_mfma_f32_16x16x32_bf16 v[76:79], v[148:151], v[214:217], v[76:79]
	v_mfma_f32_16x16x32_bf16 v[72:75], v[166:169], v[214:217], v[72:75]
	v_mfma_f32_16x16x32_bf16 v[116:119], v[170:173], v[186:189], v[116:119]
	v_mfma_f32_16x16x32_bf16 v[112:115], v[178:181], v[186:189], v[112:115]
	v_mfma_f32_16x16x32_bf16 v[100:103], v[170:173], v[194:197], v[100:103]
	v_mfma_f32_16x16x32_bf16 v[96:99], v[178:181], v[194:197], v[96:99]
	v_mfma_f32_16x16x32_bf16 v[84:87], v[170:173], v[202:205], v[84:87]
	v_mfma_f32_16x16x32_bf16 v[80:83], v[178:181], v[202:205], v[80:83]
	v_mfma_f32_16x16x32_bf16 v[68:71], v[170:173], v[210:213], v[68:71]
	v_mfma_f32_16x16x32_bf16 v[64:67], v[178:181], v[210:213], v[64:67]
	v_mfma_f32_16x16x32_bf16 v[116:119], v[174:177], v[190:193], v[116:119]
	v_mfma_f32_16x16x32_bf16 v[112:115], v[182:185], v[190:193], v[112:115]
	v_mfma_f32_16x16x32_bf16 v[100:103], v[174:177], v[198:201], v[100:103]
	v_mfma_f32_16x16x32_bf16 v[96:99], v[182:185], v[198:201], v[96:99]
	v_mfma_f32_16x16x32_bf16 v[84:87], v[174:177], v[206:209], v[84:87]
	v_mfma_f32_16x16x32_bf16 v[80:83], v[182:185], v[206:209], v[80:83]
	v_mfma_f32_16x16x32_bf16 v[68:71], v[174:177], v[214:217], v[68:71]
	v_mfma_f32_16x16x32_bf16 v[64:67], v[182:185], v[214:217], v[64:67]
	s_barrier
	s_add_i32 s42, s61, s49
	v_lshl_add_u64 v[152:153], s[10:11], 0, v[130:131]
	s_mov_b32 m0, s42
	ds_read_b128 v[186:189], v159 offset:16384
	ds_read_b128 v[190:193], v159 offset:17408
	ds_read_b128 v[194:197], v159 offset:18432
	ds_read_b128 v[198:201], v159 offset:19456
	ds_read_b128 v[202:205], v159 offset:20480
	ds_read_b128 v[206:209], v159 offset:21504
	ds_read_b128 v[210:213], v159 offset:22528
	ds_read_b128 v[214:217], v159 offset:23552
	global_load_lds_dwordx4 v[152:153], off
	s_add_i32 m0, s42, 0x2000
	s_add_u32 s42, s10, 0x40000
	v_lshl_add_u64 v[218:219], s[10:11], 0, v[134:135]
	s_addc_u32 s43, s11, 0
	s_add_i32 s64, s62, s49
	global_load_lds_dwordx4 v[218:219], off
	v_lshl_add_u64 v[220:221], s[42:43], 0, v[130:131]
	s_mov_b32 m0, s64
	v_lshl_add_u64 v[222:223], s[30:31], 0, v[132:133]
	global_load_lds_dwordx4 v[220:221], off
	v_lshl_add_u64 v[220:221], s[42:43], 0, v[134:135]
	s_add_i32 m0, s64, 0x2000
	s_nop 0
	global_load_lds_dwordx4 v[220:221], off
	v_lshl_add_u64 v[220:221], s[30:31], 0, v[128:129]
	s_mov_b32 m0, s41
	s_nop 0
	global_load_lds_dwordx4 v[220:221], off
	s_mov_b32 m0, s50
	s_nop 0
	global_load_lds_dwordx4 v[222:223], off
	s_waitcnt vmcnt(8)
	s_waitcnt lgkmcnt(0)
	s_barrier
	v_mfma_f32_16x16x32_bf16 v[60:63], v[144:147], v[186:189], v[60:63]
	v_mfma_f32_16x16x32_bf16 v[56:59], v[162:165], v[186:189], v[56:59]
	v_mfma_f32_16x16x32_bf16 v[44:47], v[144:147], v[194:197], v[44:47]
	v_mfma_f32_16x16x32_bf16 v[40:43], v[162:165], v[194:197], v[40:43]
	v_mfma_f32_16x16x32_bf16 v[28:31], v[144:147], v[202:205], v[28:31]
	v_mfma_f32_16x16x32_bf16 v[24:27], v[162:165], v[202:205], v[24:27]
	v_mfma_f32_16x16x32_bf16 v[12:15], v[144:147], v[210:213], v[12:15]
	v_mfma_f32_16x16x32_bf16 v[8:11], v[162:165], v[210:213], v[8:11]
	v_mfma_f32_16x16x32_bf16 v[60:63], v[148:151], v[190:193], v[60:63]
	v_mfma_f32_16x16x32_bf16 v[56:59], v[166:169], v[190:193], v[56:59]
	v_mfma_f32_16x16x32_bf16 v[44:47], v[148:151], v[198:201], v[44:47]
	v_mfma_f32_16x16x32_bf16 v[40:43], v[166:169], v[198:201], v[40:43]
	v_mfma_f32_16x16x32_bf16 v[28:31], v[148:151], v[206:209], v[28:31]
	v_mfma_f32_16x16x32_bf16 v[24:27], v[166:169], v[206:209], v[24:27]
	v_mfma_f32_16x16x32_bf16 v[12:15], v[148:151], v[214:217], v[12:15]
	v_mfma_f32_16x16x32_bf16 v[8:11], v[166:169], v[214:217], v[8:11]
	v_mfma_f32_16x16x32_bf16 v[52:55], v[170:173], v[186:189], v[52:55]
	v_mfma_f32_16x16x32_bf16 v[48:51], v[178:181], v[186:189], v[48:51]
	v_mfma_f32_16x16x32_bf16 v[36:39], v[170:173], v[194:197], v[36:39]
	v_mfma_f32_16x16x32_bf16 v[32:35], v[178:181], v[194:197], v[32:35]
	v_mfma_f32_16x16x32_bf16 v[20:23], v[170:173], v[202:205], v[20:23]
	v_mfma_f32_16x16x32_bf16 v[16:19], v[178:181], v[202:205], v[16:19]
	v_mfma_f32_16x16x32_bf16 v[4:7], v[170:173], v[210:213], v[4:7]
	v_mfma_f32_16x16x32_bf16 v[0:3], v[178:181], v[210:213], v[0:3]
	v_mfma_f32_16x16x32_bf16 v[52:55], v[174:177], v[190:193], v[52:55]
	v_mfma_f32_16x16x32_bf16 v[48:51], v[182:185], v[190:193], v[48:51]
	v_mfma_f32_16x16x32_bf16 v[36:39], v[174:177], v[198:201], v[36:39]
	v_mfma_f32_16x16x32_bf16 v[32:35], v[182:185], v[198:201], v[32:35]
	v_mfma_f32_16x16x32_bf16 v[20:23], v[174:177], v[206:209], v[20:23]
	v_mfma_f32_16x16x32_bf16 v[16:19], v[182:185], v[206:209], v[16:19]
	v_mfma_f32_16x16x32_bf16 v[4:7], v[174:177], v[214:217], v[4:7]
	v_mfma_f32_16x16x32_bf16 v[0:3], v[182:185], v[214:217], v[0:3]
	s_barrier
	s_add_i32 s42, 0, 0x18000
	v_add_u32_e32 v161, s42, v156
	s_add_i32 s43, 0, 0x1c000
	ds_read_b128 v[144:147], v161
	ds_read_b128 v[148:151], v161 offset:1024
	ds_read_b128 v[162:165], v161 offset:2048
	ds_read_b128 v[166:169], v161 offset:3072
	v_add_u32_e32 v161, s43, v156
	ds_read_b128 v[170:173], v161
	ds_read_b128 v[174:177], v161 offset:1024
	ds_read_b128 v[178:181], v161 offset:2048
	ds_read_b128 v[182:185], v161 offset:3072
	s_add_u32 s30, s30, 0x40000
	s_addc_u32 s31, s31, 0
	s_mov_b32 m0, s51
	v_lshl_add_u64 v[224:225], s[30:31], 0, v[128:129]
	ds_read_b128 v[186:189], v159 offset:32768
	ds_read_b128 v[190:193], v159 offset:33792
	ds_read_b128 v[194:197], v159 offset:34816
	ds_read_b128 v[198:201], v159 offset:35840
	ds_read_b128 v[202:205], v159 offset:36864
	ds_read_b128 v[206:209], v159 offset:37888
	ds_read_b128 v[210:213], v159 offset:38912
	ds_read_b128 v[214:217], v159 offset:39936
	global_load_lds_dwordx4 v[224:225], off
	v_lshl_add_u64 v[224:225], s[30:31], 0, v[132:133]
	s_mov_b32 m0, s52
	s_nop 0
	global_load_lds_dwordx4 v[224:225], off
	s_waitcnt vmcnt(8)
	s_waitcnt lgkmcnt(0)
	s_barrier
	v_mfma_f32_16x16x32_bf16 v[124:127], v[144:147], v[186:189], v[124:127]
	v_mfma_f32_16x16x32_bf16 v[120:123], v[162:165], v[186:189], v[120:123]
	v_mfma_f32_16x16x32_bf16 v[108:111], v[144:147], v[194:197], v[108:111]
	v_mfma_f32_16x16x32_bf16 v[104:107], v[162:165], v[194:197], v[104:107]
	v_mfma_f32_16x16x32_bf16 v[92:95], v[144:147], v[202:205], v[92:95]
	v_mfma_f32_16x16x32_bf16 v[88:91], v[162:165], v[202:205], v[88:91]
	v_mfma_f32_16x16x32_bf16 v[76:79], v[144:147], v[210:213], v[76:79]
	v_mfma_f32_16x16x32_bf16 v[72:75], v[162:165], v[210:213], v[72:75]
	v_mfma_f32_16x16x32_bf16 v[124:127], v[148:151], v[190:193], v[124:127]
	v_mfma_f32_16x16x32_bf16 v[120:123], v[166:169], v[190:193], v[120:123]
	v_mfma_f32_16x16x32_bf16 v[108:111], v[148:151], v[198:201], v[108:111]
	v_mfma_f32_16x16x32_bf16 v[104:107], v[166:169], v[198:201], v[104:107]
	v_mfma_f32_16x16x32_bf16 v[92:95], v[148:151], v[206:209], v[92:95]
	v_mfma_f32_16x16x32_bf16 v[88:91], v[166:169], v[206:209], v[88:91]
	v_mfma_f32_16x16x32_bf16 v[76:79], v[148:151], v[214:217], v[76:79]
	v_mfma_f32_16x16x32_bf16 v[72:75], v[166:169], v[214:217], v[72:75]
	v_mfma_f32_16x16x32_bf16 v[116:119], v[170:173], v[186:189], v[116:119]
	v_mfma_f32_16x16x32_bf16 v[112:115], v[178:181], v[186:189], v[112:115]
	v_mfma_f32_16x16x32_bf16 v[100:103], v[170:173], v[194:197], v[100:103]
	v_mfma_f32_16x16x32_bf16 v[96:99], v[178:181], v[194:197], v[96:99]
	v_mfma_f32_16x16x32_bf16 v[84:87], v[170:173], v[202:205], v[84:87]
	v_mfma_f32_16x16x32_bf16 v[80:83], v[178:181], v[202:205], v[80:83]
	v_mfma_f32_16x16x32_bf16 v[68:71], v[170:173], v[210:213], v[68:71]
	v_mfma_f32_16x16x32_bf16 v[64:67], v[178:181], v[210:213], v[64:67]
	v_mfma_f32_16x16x32_bf16 v[116:119], v[174:177], v[190:193], v[116:119]
	v_mfma_f32_16x16x32_bf16 v[112:115], v[182:185], v[190:193], v[112:115]
	v_mfma_f32_16x16x32_bf16 v[100:103], v[174:177], v[198:201], v[100:103]
	v_mfma_f32_16x16x32_bf16 v[96:99], v[182:185], v[198:201], v[96:99]
	v_mfma_f32_16x16x32_bf16 v[84:87], v[174:177], v[206:209], v[84:87]
	v_mfma_f32_16x16x32_bf16 v[80:83], v[182:185], v[206:209], v[80:83]
	v_mfma_f32_16x16x32_bf16 v[68:71], v[174:177], v[214:217], v[68:71]
	v_mfma_f32_16x16x32_bf16 v[64:67], v[182:185], v[214:217], v[64:67]
	s_barrier
	s_add_i32 s30, s42, s49
	v_lshl_add_u64 v[152:153], v[152:153], 0, s[12:13]
	s_mov_b32 m0, s30
	ds_read_b128 v[186:189], v159 offset:49152
	ds_read_b128 v[190:193], v159 offset:50176
	ds_read_b128 v[194:197], v159 offset:51200
	ds_read_b128 v[198:201], v159 offset:52224
	ds_read_b128 v[202:205], v159 offset:53248
	ds_read_b128 v[206:209], v159 offset:54272
	ds_read_b128 v[210:213], v159 offset:55296
	ds_read_b128 v[214:217], v159 offset:56320
	global_load_lds_dwordx4 v[152:153], off
	s_add_i32 m0, s30, 0x2000
	s_add_u32 s10, s10, 0x40080
	v_lshl_add_u64 v[152:153], v[218:219], 0, s[12:13]
	s_addc_u32 s11, s11, 0
	s_add_i32 s30, s43, s49
	global_load_lds_dwordx4 v[152:153], off
	v_lshl_add_u64 v[152:153], s[10:11], 0, v[130:131]
	s_mov_b32 m0, s30
	s_nop 0
	global_load_lds_dwordx4 v[152:153], off
	v_lshl_add_u64 v[152:153], s[10:11], 0, v[134:135]
	s_add_i32 m0, s30, 0x2000
	s_nop 0
	global_load_lds_dwordx4 v[152:153], off
	v_lshl_add_u64 v[152:153], v[220:221], 0, s[12:13]
	s_mov_b32 m0, s57
	s_nop 0
	global_load_lds_dwordx4 v[152:153], off
	v_lshl_add_u64 v[152:153], v[222:223], 0, s[12:13]
	s_mov_b32 m0, s58
	s_nop 0
	global_load_lds_dwordx4 v[152:153], off
	s_waitcnt vmcnt(8)
	s_waitcnt lgkmcnt(0)
	s_barrier
	v_mfma_f32_16x16x32_bf16 v[60:63], v[144:147], v[186:189], v[60:63]
	v_mfma_f32_16x16x32_bf16 v[56:59], v[162:165], v[186:189], v[56:59]
	v_mfma_f32_16x16x32_bf16 v[44:47], v[144:147], v[194:197], v[44:47]
	v_mfma_f32_16x16x32_bf16 v[40:43], v[162:165], v[194:197], v[40:43]
	v_mfma_f32_16x16x32_bf16 v[28:31], v[144:147], v[202:205], v[28:31]
	v_mfma_f32_16x16x32_bf16 v[24:27], v[162:165], v[202:205], v[24:27]
	v_mfma_f32_16x16x32_bf16 v[12:15], v[144:147], v[210:213], v[12:15]
	v_mfma_f32_16x16x32_bf16 v[8:11], v[162:165], v[210:213], v[8:11]
	v_mfma_f32_16x16x32_bf16 v[60:63], v[148:151], v[190:193], v[60:63]
	v_mfma_f32_16x16x32_bf16 v[56:59], v[166:169], v[190:193], v[56:59]
	v_mfma_f32_16x16x32_bf16 v[44:47], v[148:151], v[198:201], v[44:47]
	v_mfma_f32_16x16x32_bf16 v[40:43], v[166:169], v[198:201], v[40:43]
	v_mfma_f32_16x16x32_bf16 v[28:31], v[148:151], v[206:209], v[28:31]
	v_mfma_f32_16x16x32_bf16 v[24:27], v[166:169], v[206:209], v[24:27]
	v_mfma_f32_16x16x32_bf16 v[12:15], v[148:151], v[214:217], v[12:15]
	v_mfma_f32_16x16x32_bf16 v[8:11], v[166:169], v[214:217], v[8:11]
	v_mfma_f32_16x16x32_bf16 v[52:55], v[170:173], v[186:189], v[52:55]
	v_mfma_f32_16x16x32_bf16 v[48:51], v[178:181], v[186:189], v[48:51]
	v_mfma_f32_16x16x32_bf16 v[36:39], v[170:173], v[194:197], v[36:39]
	v_mfma_f32_16x16x32_bf16 v[32:35], v[178:181], v[194:197], v[32:35]
	v_mfma_f32_16x16x32_bf16 v[20:23], v[170:173], v[202:205], v[20:23]
	v_mfma_f32_16x16x32_bf16 v[16:19], v[178:181], v[202:205], v[16:19]
	v_mfma_f32_16x16x32_bf16 v[4:7], v[170:173], v[210:213], v[4:7]
	v_mfma_f32_16x16x32_bf16 v[0:3], v[178:181], v[210:213], v[0:3]
	v_mfma_f32_16x16x32_bf16 v[52:55], v[174:177], v[190:193], v[52:55]
	v_mfma_f32_16x16x32_bf16 v[48:51], v[182:185], v[190:193], v[48:51]
	v_mfma_f32_16x16x32_bf16 v[36:39], v[174:177], v[198:201], v[36:39]
	v_mfma_f32_16x16x32_bf16 v[32:35], v[182:185], v[198:201], v[32:35]
	v_mfma_f32_16x16x32_bf16 v[20:23], v[174:177], v[206:209], v[20:23]
	v_mfma_f32_16x16x32_bf16 v[16:19], v[182:185], v[206:209], v[16:19]
	v_mfma_f32_16x16x32_bf16 v[4:7], v[174:177], v[214:217], v[4:7]
	v_mfma_f32_16x16x32_bf16 v[0:3], v[182:185], v[214:217], v[0:3]
	s_barrier
	s_add_i32 s39, s39, 2
	s_add_u32 s36, s36, 0x100
	s_addc_u32 s37, s37, 0
	s_add_u32 s8, s8, 0x100
	s_addc_u32 s9, s9, 0
	s_cmp_gt_u32 s39, 13
	s_cbranch_scc0 .LBB0_1813
	s_and_b64 vcc, exec, s[14:15]
	s_cbranch_vccz .LBB0_1816
	s_barrier
